# v12 without the per-phase s_setprio pairs in the GEMM main loops
# baseline (speedup 1.0000x reference)
; #define PG8_STAGE(bufoff, gbase, voff) do { _Pragma("unroll") for (int _i = 0; _i < 2; ++_i) \
;         __builtin_amdgcn_global_load_lds((const unsigned*)((const char*)(gbase) + (voff)[_i]), (LAS unsigned*)(lds + (bufoff) + ldsw + _i * 8192), 16, 0, 0); } while (0)
; #define PG8_LDA(dst, b, h) do { _Pragma("unroll") for (int m = 0; m < 4; ++m) _Pragma("unroll") for (int k = 0; k < 2; ++k) dst[m][k] = *(const LAS bf16x8*)(lds + PG8_SA(b, h) + aoff + m * 2048 + k * 1024); } while (0)
; #define PG8_LDB(dst, b, h) do { _Pragma("unroll") for (int n = 0; n < 2; ++n) _Pragma("unroll") for (int k = 0; k < 2; ++k) dst[n][k] = *(const LAS bf16x8*)(lds + PG8_SB(b, h) + boff + n * 2048 + k * 1024); } while (0)
; #define PG8_MMA(ai, bj, At, Bt) do { __builtin_amdgcn_s_setprio(1); _Pragma("unroll") for (int m = 0; m < 4; ++m) _Pragma("unroll") for (int n = 0; n < 2; ++n) _Pragma("unroll") for (int k = 0; k < 2; ++k) \
;         acc[ai][bj][m][n] = __builtin_amdgcn_mfma_f32_16x16x32_bf16(Bt[n][k], At[m][k], acc[ai][bj][m][n], 0, 0, 0); __builtin_amdgcn_s_setprio(0); } while (0)
; #define PG8_WAIT_V(n) asm volatile("s_waitcnt vmcnt(" #n ")" ::: "memory")
; #define PG8_WAIT_L(n) asm volatile("s_waitcnt lgkmcnt(" #n ")" ::: "memory")
; #define PG8_BAR __builtin_amdgcn_s_barrier()
; #define PG8_SCHED __builtin_amdgcn_sched_barrier(0)
; template <class Epi, bool ALIGN_EPI = true>
; __device__ __forceinline__ void gemm_phase(LAS unsigned char* lds, const Gemm g, const StaticOrder& S, const Epi& E, int wave_k) {
;     ...
;             const bool last = (t == nt - 2);
;             const char* a1 = cA + (size_t)(t + 1) * kstep;
;             const char* a2 = last ? nA : cA + (size_t)(t + 2) * kstep; const char* b2 = last ? nB : cB + (size_t)(t + 2) * kstep;
;             const char* a3 = a2 + kstep; const char* b3 = b2 + kstep;
;             PG8_LDB(B0, 0, 0); PG8_LDB(B1, 0, 1); PG8_SCHED; PG8_LDA(At, 0, 0); PG8_STAGE(PG8_SA(1, 1), a1 + hstepA, voffA);
;             PG8_WAIT_V(8); PG8_WAIT_L(0); PG8_BAR; PG8_MMA(0, 0, At, B0); PG8_MMA(0, 1, At, B1); PG8_BAR; PG8_SCHED;
;             PG8_LDA(At, 0, 1); PG8_STAGE(PG8_SB(0, 0), b2, voffB); PG8_STAGE(PG8_SB(0, 1), b2 + hstepB, voffB); PG8_STAGE(PG8_SA(0, 0), a2, voffA);
;             PG8_WAIT_V(8); PG8_WAIT_L(0); PG8_BAR; PG8_MMA(1, 0, At, B0); PG8_MMA(1, 1, At, B1); PG8_BAR; PG8_SCHED;
.LBB0_81:
	s_add_u32 s16, s2, 0xfffc0080
	s_addc_u32 s17, s3, -1
	s_add_i32 s65, 0, 0x10000
	s_cmp_eq_u32 s64, 12
	s_cselect_b32 s19, s42, s17
	s_cselect_b32 s18, s43, s16
	s_cselect_b32 s17, s49, s63
	s_cselect_b32 s16, s51, s62
	s_add_i32 s68, 0, 0x14000
	v_add_u32_e32 v150, s65, v157
	v_add_u32_e32 v154, s68, v157
	ds_read_b128 v[138:141], v150
	ds_read_b128 v[142:145], v150 offset:1024
	ds_read_b128 v[146:149], v150 offset:2048
	ds_read_b128 v[150:153], v150 offset:3072
	ds_read_b128 v[162:165], v154
	ds_read_b128 v[166:169], v154 offset:1024
	ds_read_b128 v[170:173], v154 offset:2048
	ds_read_b128 v[174:177], v154 offset:3072
	s_add_i32 m0, s35, 0xc000
	ds_read_b128 v[178:181], v159
	ds_read_b128 v[182:185], v159 offset:1024
	ds_read_b128 v[186:189], v159 offset:2048
	ds_read_b128 v[190:193], v159 offset:3072
	ds_read_b128 v[194:197], v159 offset:4096
	ds_read_b128 v[198:201], v159 offset:5120
	ds_read_b128 v[202:205], v159 offset:6144
	ds_read_b128 v[206:209], v159 offset:7168
	global_load_lds_dwordx4 v134, s[2:3]
	s_add_i32 m0, s35, 0xe000
	s_nop 0
	global_load_lds_dwordx4 v136, s[2:3]
	s_waitcnt vmcnt(8) lgkmcnt(0)
	s_barrier
	v_mfma_f32_16x16x32_bf16 v[124:127], v[138:141], v[178:181], v[124:127]
	v_mfma_f32_16x16x32_bf16 v[120:123], v[146:149], v[178:181], v[120:123]
	v_mfma_f32_16x16x32_bf16 v[108:111], v[138:141], v[186:189], v[108:111]
	v_mfma_f32_16x16x32_bf16 v[100:103], v[146:149], v[186:189], v[100:103]
	v_mfma_f32_16x16x32_bf16 v[92:95], v[138:141], v[194:197], v[92:95]
	v_mfma_f32_16x16x32_bf16 v[84:87], v[146:149], v[194:197], v[84:87]
	v_mfma_f32_16x16x32_bf16 v[76:79], v[138:141], v[202:205], v[76:79]
	v_mfma_f32_16x16x32_bf16 v[68:71], v[146:149], v[202:205], v[68:71]
	v_mfma_f32_16x16x32_bf16 v[124:127], v[142:145], v[182:185], v[124:127]
	v_mfma_f32_16x16x32_bf16 v[120:123], v[150:153], v[182:185], v[120:123]
	v_mfma_f32_16x16x32_bf16 v[108:111], v[142:145], v[190:193], v[108:111]
	v_mfma_f32_16x16x32_bf16 v[100:103], v[150:153], v[190:193], v[100:103]
	v_mfma_f32_16x16x32_bf16 v[92:95], v[142:145], v[198:201], v[92:95]
	v_mfma_f32_16x16x32_bf16 v[84:87], v[150:153], v[198:201], v[84:87]
	v_mfma_f32_16x16x32_bf16 v[76:79], v[142:145], v[206:209], v[76:79]
	v_mfma_f32_16x16x32_bf16 v[68:71], v[150:153], v[206:209], v[68:71]
	v_mfma_f32_16x16x32_bf16 v[116:119], v[162:165], v[178:181], v[116:119]
	v_mfma_f32_16x16x32_bf16 v[112:115], v[170:173], v[178:181], v[112:115]
	v_mfma_f32_16x16x32_bf16 v[104:107], v[162:165], v[186:189], v[104:107]
	v_mfma_f32_16x16x32_bf16 v[96:99], v[170:173], v[186:189], v[96:99]
	v_mfma_f32_16x16x32_bf16 v[88:91], v[162:165], v[194:197], v[88:91]
	v_mfma_f32_16x16x32_bf16 v[80:83], v[170:173], v[194:197], v[80:83]
	v_mfma_f32_16x16x32_bf16 v[72:75], v[162:165], v[202:205], v[72:75]
	v_mfma_f32_16x16x32_bf16 v[64:67], v[170:173], v[202:205], v[64:67]
	v_mfma_f32_16x16x32_bf16 v[116:119], v[166:169], v[182:185], v[116:119]
	v_mfma_f32_16x16x32_bf16 v[112:115], v[174:177], v[182:185], v[112:115]
	v_mfma_f32_16x16x32_bf16 v[104:107], v[166:169], v[190:193], v[104:107]
	v_mfma_f32_16x16x32_bf16 v[96:99], v[174:177], v[190:193], v[96:99]
	v_mfma_f32_16x16x32_bf16 v[88:91], v[166:169], v[198:201], v[88:91]
	v_mfma_f32_16x16x32_bf16 v[80:83], v[174:177], v[198:201], v[80:83]
	v_mfma_f32_16x16x32_bf16 v[72:75], v[166:169], v[206:209], v[72:75]
	v_mfma_f32_16x16x32_bf16 v[64:67], v[174:177], v[206:209], v[64:67]
	s_barrier
	s_add_i32 s65, s65, s29
	v_lshl_add_u64 v[154:155], s[16:17], 0, v[160:161]
	s_mov_b32 m0, s65
	ds_read_b128 v[178:181], v159 offset:16384
	ds_read_b128 v[182:185], v159 offset:17408
	ds_read_b128 v[186:189], v159 offset:18432
	ds_read_b128 v[190:193], v159 offset:19456
	ds_read_b128 v[194:197], v159 offset:20480
	ds_read_b128 v[198:201], v159 offset:21504
	ds_read_b128 v[202:205], v159 offset:22528
	ds_read_b128 v[206:209], v159 offset:23552
	global_load_lds_dwordx4 v[154:155], off
	s_add_i32 m0, s65, 0x2000
	s_add_u32 s66, s16, 0x40000
	v_lshl_add_u64 v[210:211], s[16:17], 0, v[128:129]
	s_addc_u32 s67, s17, 0
	s_add_i32 s65, s68, s29
	global_load_lds_dwordx4 v[210:211], off
	s_mov_b32 m0, s65
	v_lshl_add_u64 v[218:219], s[18:19], 0, v[130:131]
	global_load_lds_dwordx4 v160, s[66:67]
	s_add_i32 m0, s65, 0x2000
	s_nop 0
	global_load_lds_dwordx4 v128, s[66:67]
	v_lshl_add_u64 v[212:213], s[18:19], 0, v[132:133]
	s_mov_b32 m0, s35
	s_nop 0
	global_load_lds_dwordx4 v[212:213], off
	s_mov_b32 m0, s56
	s_nop 0
	global_load_lds_dwordx4 v[218:219], off
	s_waitcnt vmcnt(8) lgkmcnt(0)
	s_barrier
	v_mfma_f32_16x16x32_bf16 v[60:63], v[138:141], v[178:181], v[60:63]
	v_mfma_f32_16x16x32_bf16 v[52:55], v[146:149], v[178:181], v[52:55]
	v_mfma_f32_16x16x32_bf16 v[44:47], v[138:141], v[186:189], v[44:47]
	v_mfma_f32_16x16x32_bf16 v[36:39], v[146:149], v[186:189], v[36:39]
	v_mfma_f32_16x16x32_bf16 v[28:31], v[138:141], v[194:197], v[28:31]
	v_mfma_f32_16x16x32_bf16 v[20:23], v[146:149], v[194:197], v[20:23]
	v_mfma_f32_16x16x32_bf16 v[12:15], v[138:141], v[202:205], v[12:15]
	v_mfma_f32_16x16x32_bf16 v[4:7], v[146:149], v[202:205], v[4:7]
	v_mfma_f32_16x16x32_bf16 v[60:63], v[142:145], v[182:185], v[60:63]
	v_mfma_f32_16x16x32_bf16 v[52:55], v[150:153], v[182:185], v[52:55]
	v_mfma_f32_16x16x32_bf16 v[44:47], v[142:145], v[190:193], v[44:47]
	v_mfma_f32_16x16x32_bf16 v[36:39], v[150:153], v[190:193], v[36:39]
	v_mfma_f32_16x16x32_bf16 v[28:31], v[142:145], v[198:201], v[28:31]
	v_mfma_f32_16x16x32_bf16 v[20:23], v[150:153], v[198:201], v[20:23]
	v_mfma_f32_16x16x32_bf16 v[12:15], v[142:145], v[206:209], v[12:15]
	v_mfma_f32_16x16x32_bf16 v[4:7], v[150:153], v[206:209], v[4:7]
	v_mfma_f32_16x16x32_bf16 v[56:59], v[162:165], v[178:181], v[56:59]
	v_mfma_f32_16x16x32_bf16 v[48:51], v[170:173], v[178:181], v[48:51]
	v_mfma_f32_16x16x32_bf16 v[40:43], v[162:165], v[186:189], v[40:43]
	v_mfma_f32_16x16x32_bf16 v[32:35], v[170:173], v[186:189], v[32:35]
	v_mfma_f32_16x16x32_bf16 v[24:27], v[162:165], v[194:197], v[24:27]
	v_mfma_f32_16x16x32_bf16 v[16:19], v[170:173], v[194:197], v[16:19]
	v_mfma_f32_16x16x32_bf16 v[8:11], v[162:165], v[202:205], v[8:11]
	v_mfma_f32_16x16x32_bf16 v[0:3], v[170:173], v[202:205], v[0:3]
	v_mfma_f32_16x16x32_bf16 v[56:59], v[166:169], v[182:185], v[56:59]
	v_mfma_f32_16x16x32_bf16 v[48:51], v[174:177], v[182:185], v[48:51]
	v_mfma_f32_16x16x32_bf16 v[40:43], v[166:169], v[190:193], v[40:43]
	v_mfma_f32_16x16x32_bf16 v[32:35], v[174:177], v[190:193], v[32:35]
	v_mfma_f32_16x16x32_bf16 v[24:27], v[166:169], v[198:201], v[24:27]
	v_mfma_f32_16x16x32_bf16 v[16:19], v[174:177], v[198:201], v[16:19]
	v_mfma_f32_16x16x32_bf16 v[8:11], v[166:169], v[206:209], v[8:11]
	v_mfma_f32_16x16x32_bf16 v[0:3], v[174:177], v[206:209], v[0:3]
	s_barrier
; #define PG8_STAGE(bufoff, gbase, voff) do { _Pragma("unroll") for (int _i = 0; _i < 2; ++_i) \
;         __builtin_amdgcn_global_load_lds((const unsigned*)((const char*)(gbase) + (voff)[_i]), (LAS unsigned*)(lds + (bufoff) + ldsw + _i * 8192), 16, 0, 0); } while (0)
; #define PG8_LDA(dst, b, h) do { _Pragma("unroll") for (int m = 0; m < 4; ++m) _Pragma("unroll") for (int k = 0; k < 2; ++k) dst[m][k] = *(const LAS bf16x8*)(lds + PG8_SA(b, h) + aoff + m * 2048 + k * 1024); } while (0)
; #define PG8_LDB(dst, b, h) do { _Pragma("unroll") for (int n = 0; n < 2; ++n) _Pragma("unroll") for (int k = 0; k < 2; ++k) dst[n][k] = *(const LAS bf16x8*)(lds + PG8_SB(b, h) + boff + n * 2048 + k * 1024); } while (0)
; #define PG8_MMA(ai, bj, At, Bt) do { __builtin_amdgcn_s_setprio(1); _Pragma("unroll") for (int m = 0; m < 4; ++m) _Pragma("unroll") for (int n = 0; n < 2; ++n) _Pragma("unroll") for (int k = 0; k < 2; ++k) \
;         acc[ai][bj][m][n] = __builtin_amdgcn_mfma_f32_16x16x32_bf16(Bt[n][k], At[m][k], acc[ai][bj][m][n], 0, 0, 0); __builtin_amdgcn_s_setprio(0); } while (0)
; #define PG8_WAIT_V(n) asm volatile("s_waitcnt vmcnt(" #n ")" ::: "memory")
; #define PG8_WAIT_L(n) asm volatile("s_waitcnt lgkmcnt(" #n ")" ::: "memory")
; #define PG8_BAR __builtin_amdgcn_s_barrier()
; #define PG8_SCHED __builtin_amdgcn_sched_barrier(0)
; template <class Epi, bool ALIGN_EPI = true>
; __device__ __forceinline__ void gemm_phase(LAS unsigned char* lds, const Gemm g, const StaticOrder& S, const Epi& E, int wave_k) {
;     ...
;             PG8_LDB(B0, 1, 0); PG8_LDB(B1, 1, 1); PG8_SCHED; PG8_LDA(At, 1, 0); PG8_STAGE(PG8_SA(0, 1), a2 + hstepA, voffA);
;             PG8_WAIT_V(8); PG8_WAIT_L(0); PG8_BAR; PG8_MMA(0, 0, At, B0); PG8_MMA(0, 1, At, B1); PG8_BAR; PG8_SCHED;
;             PG8_LDA(At, 1, 1); PG8_STAGE(PG8_SB(1, 0), b3, voffB); PG8_STAGE(PG8_SB(1, 1), b3 + hstepB, voffB); PG8_STAGE(PG8_SA(1, 0), a3, voffA);
;             PG8_WAIT_V(8); PG8_WAIT_L(0); PG8_BAR; PG8_MMA(1, 0, At, B0); PG8_MMA(1, 1, At, B1); PG8_BAR; PG8_SCHED;
;         }
	s_add_i32 s65, 0, 0x18000
	s_add_i32 s66, 0, 0x1c000
	v_add_u32_e32 v150, s65, v157
	v_add_u32_e32 v174, s66, v157
	ds_read_b128 v[138:141], v150
	ds_read_b128 v[142:145], v150 offset:1024
	ds_read_b128 v[146:149], v150 offset:2048
	ds_read_b128 v[150:153], v150 offset:3072
	ds_read_b128 v[162:165], v174
	ds_read_b128 v[166:169], v174 offset:1024
	ds_read_b128 v[170:173], v174 offset:2048
	ds_read_b128 v[174:177], v174 offset:3072
	s_add_u32 s18, s18, 0x40000
	s_addc_u32 s19, s19, 0
	s_mov_b32 m0, s57
	ds_read_b128 v[178:181], v159 offset:32768
	ds_read_b128 v[182:185], v159 offset:33792
	ds_read_b128 v[186:189], v159 offset:34816
	ds_read_b128 v[190:193], v159 offset:35840
	ds_read_b128 v[194:197], v159 offset:36864
	ds_read_b128 v[198:201], v159 offset:37888
	ds_read_b128 v[202:205], v159 offset:38912
	ds_read_b128 v[206:209], v159 offset:39936
	global_load_lds_dwordx4 v132, s[18:19]
	s_mov_b32 m0, s58
	s_nop 0
	global_load_lds_dwordx4 v130, s[18:19]
	s_waitcnt vmcnt(8) lgkmcnt(0)
	s_barrier
	v_mfma_f32_16x16x32_bf16 v[124:127], v[138:141], v[178:181], v[124:127]
	v_mfma_f32_16x16x32_bf16 v[120:123], v[146:149], v[178:181], v[120:123]
	v_mfma_f32_16x16x32_bf16 v[108:111], v[138:141], v[186:189], v[108:111]
	v_mfma_f32_16x16x32_bf16 v[100:103], v[146:149], v[186:189], v[100:103]
	v_mfma_f32_16x16x32_bf16 v[92:95], v[138:141], v[194:197], v[92:95]
	v_mfma_f32_16x16x32_bf16 v[84:87], v[146:149], v[194:197], v[84:87]
	v_mfma_f32_16x16x32_bf16 v[76:79], v[138:141], v[202:205], v[76:79]
	v_mfma_f32_16x16x32_bf16 v[68:71], v[146:149], v[202:205], v[68:71]
	v_mfma_f32_16x16x32_bf16 v[124:127], v[142:145], v[182:185], v[124:127]
	v_mfma_f32_16x16x32_bf16 v[120:123], v[150:153], v[182:185], v[120:123]
	v_mfma_f32_16x16x32_bf16 v[108:111], v[142:145], v[190:193], v[108:111]
	v_mfma_f32_16x16x32_bf16 v[100:103], v[150:153], v[190:193], v[100:103]
	v_mfma_f32_16x16x32_bf16 v[92:95], v[142:145], v[198:201], v[92:95]
	v_mfma_f32_16x16x32_bf16 v[84:87], v[150:153], v[198:201], v[84:87]
	v_mfma_f32_16x16x32_bf16 v[76:79], v[142:145], v[206:209], v[76:79]
	v_mfma_f32_16x16x32_bf16 v[68:71], v[150:153], v[206:209], v[68:71]
	v_mfma_f32_16x16x32_bf16 v[116:119], v[162:165], v[178:181], v[116:119]
	v_mfma_f32_16x16x32_bf16 v[112:115], v[170:173], v[178:181], v[112:115]
	v_mfma_f32_16x16x32_bf16 v[104:107], v[162:165], v[186:189], v[104:107]
	v_mfma_f32_16x16x32_bf16 v[96:99], v[170:173], v[186:189], v[96:99]
	v_mfma_f32_16x16x32_bf16 v[88:91], v[162:165], v[194:197], v[88:91]
	v_mfma_f32_16x16x32_bf16 v[80:83], v[170:173], v[194:197], v[80:83]
	v_mfma_f32_16x16x32_bf16 v[72:75], v[162:165], v[202:205], v[72:75]
	v_mfma_f32_16x16x32_bf16 v[64:67], v[170:173], v[202:205], v[64:67]
	v_mfma_f32_16x16x32_bf16 v[116:119], v[166:169], v[182:185], v[116:119]
	v_mfma_f32_16x16x32_bf16 v[112:115], v[174:177], v[182:185], v[112:115]
	v_mfma_f32_16x16x32_bf16 v[104:107], v[166:169], v[190:193], v[104:107]
	v_mfma_f32_16x16x32_bf16 v[96:99], v[174:177], v[190:193], v[96:99]
	v_mfma_f32_16x16x32_bf16 v[88:91], v[166:169], v[198:201], v[88:91]
	v_mfma_f32_16x16x32_bf16 v[80:83], v[174:177], v[198:201], v[80:83]
	v_mfma_f32_16x16x32_bf16 v[72:75], v[166:169], v[206:209], v[72:75]
	v_mfma_f32_16x16x32_bf16 v[64:67], v[174:177], v[206:209], v[64:67]
	s_barrier
	s_add_i32 s18, s65, s29
	v_lshl_add_u64 v[154:155], v[154:155], 0, s[22:23]
	s_mov_b32 m0, s18
	ds_read_b128 v[178:181], v159 offset:49152
	ds_read_b128 v[182:185], v159 offset:50176
	ds_read_b128 v[186:189], v159 offset:51200
	ds_read_b128 v[190:193], v159 offset:52224
	ds_read_b128 v[194:197], v159 offset:53248
	ds_read_b128 v[198:201], v159 offset:54272
	ds_read_b128 v[202:205], v159 offset:55296
	ds_read_b128 v[206:209], v159 offset:56320
	global_load_lds_dwordx4 v[154:155], off
	s_add_i32 m0, s18, 0x2000
	s_add_u32 s16, s16, 0x40080
	v_lshl_add_u64 v[154:155], v[210:211], 0, s[22:23]
	s_addc_u32 s17, s17, 0
	s_add_i32 s18, s66, s29
	global_load_lds_dwordx4 v[154:155], off
	s_mov_b32 m0, s18
	s_nop 0
	global_load_lds_dwordx4 v160, s[16:17]
	s_add_i32 m0, s18, 0x2000
	s_nop 0
	global_load_lds_dwordx4 v128, s[16:17]
	v_lshl_add_u64 v[154:155], v[212:213], 0, s[22:23]
	s_mov_b32 m0, s59
	s_nop 0
	global_load_lds_dwordx4 v[154:155], off
	v_lshl_add_u64 v[154:155], v[218:219], 0, s[22:23]
	s_mov_b32 m0, s60
	s_nop 0
	global_load_lds_dwordx4 v[154:155], off
	s_waitcnt vmcnt(8) lgkmcnt(0)
	s_barrier
	v_mfma_f32_16x16x32_bf16 v[60:63], v[138:141], v[178:181], v[60:63]
	v_mfma_f32_16x16x32_bf16 v[52:55], v[146:149], v[178:181], v[52:55]
	v_mfma_f32_16x16x32_bf16 v[44:47], v[138:141], v[186:189], v[44:47]
	v_mfma_f32_16x16x32_bf16 v[36:39], v[146:149], v[186:189], v[36:39]
	v_mfma_f32_16x16x32_bf16 v[28:31], v[138:141], v[194:197], v[28:31]
	v_mfma_f32_16x16x32_bf16 v[20:23], v[146:149], v[194:197], v[20:23]
	v_mfma_f32_16x16x32_bf16 v[12:15], v[138:141], v[202:205], v[12:15]
	v_mfma_f32_16x16x32_bf16 v[4:7], v[146:149], v[202:205], v[4:7]
	v_mfma_f32_16x16x32_bf16 v[60:63], v[142:145], v[182:185], v[60:63]
	v_mfma_f32_16x16x32_bf16 v[52:55], v[150:153], v[182:185], v[52:55]
	v_mfma_f32_16x16x32_bf16 v[44:47], v[142:145], v[190:193], v[44:47]
	v_mfma_f32_16x16x32_bf16 v[36:39], v[150:153], v[190:193], v[36:39]
	v_mfma_f32_16x16x32_bf16 v[28:31], v[142:145], v[198:201], v[28:31]
	v_mfma_f32_16x16x32_bf16 v[20:23], v[150:153], v[198:201], v[20:23]
	v_mfma_f32_16x16x32_bf16 v[12:15], v[142:145], v[206:209], v[12:15]
	v_mfma_f32_16x16x32_bf16 v[4:7], v[150:153], v[206:209], v[4:7]
	v_mfma_f32_16x16x32_bf16 v[56:59], v[162:165], v[178:181], v[56:59]
	v_mfma_f32_16x16x32_bf16 v[48:51], v[170:173], v[178:181], v[48:51]
	v_mfma_f32_16x16x32_bf16 v[40:43], v[162:165], v[186:189], v[40:43]
	v_mfma_f32_16x16x32_bf16 v[32:35], v[170:173], v[186:189], v[32:35]
	v_mfma_f32_16x16x32_bf16 v[24:27], v[162:165], v[194:197], v[24:27]
	v_mfma_f32_16x16x32_bf16 v[16:19], v[170:173], v[194:197], v[16:19]
	v_mfma_f32_16x16x32_bf16 v[8:11], v[162:165], v[202:205], v[8:11]
	v_mfma_f32_16x16x32_bf16 v[0:3], v[170:173], v[202:205], v[0:3]
	v_mfma_f32_16x16x32_bf16 v[56:59], v[166:169], v[182:185], v[56:59]
	v_mfma_f32_16x16x32_bf16 v[48:51], v[174:177], v[182:185], v[48:51]
	v_mfma_f32_16x16x32_bf16 v[40:43], v[166:169], v[190:193], v[40:43]
	v_mfma_f32_16x16x32_bf16 v[32:35], v[174:177], v[190:193], v[32:35]
	v_mfma_f32_16x16x32_bf16 v[24:27], v[166:169], v[198:201], v[24:27]
	v_mfma_f32_16x16x32_bf16 v[16:19], v[174:177], v[198:201], v[16:19]
	v_mfma_f32_16x16x32_bf16 v[8:11], v[166:169], v[206:209], v[8:11]
	v_mfma_f32_16x16x32_bf16 v[0:3], v[174:177], v[206:209], v[0:3]
	s_barrier
	s_add_i32 s64, s64, 2
	s_add_u32 s2, s2, 0x100
	s_addc_u32 s3, s3, 0
	s_add_u32 s62, s62, 0x100
	s_addc_u32 s63, s63, 0
	s_cmp_gt_u32 s64, 13
	s_cbranch_scc0 .LBB0_81
	s_and_b64 vcc, exec, s[46:47]
	s_cbranch_vccz .LBB0_84
	s_barrier

; #define PG8_STAGE(bufoff, gbase, voff) do { _Pragma("unroll") for (int _i = 0; _i < 2; ++_i) \
;         __builtin_amdgcn_global_load_lds((const unsigned*)((const char*)(gbase) + (voff)[_i]), (LAS unsigned*)(lds + (bufoff) + ldsw + _i * 8192), 16, 0, 0); } while (0)
; #define PG8_LDA(dst, b, h) do { _Pragma("unroll") for (int m = 0; m < 4; ++m) _Pragma("unroll") for (int k = 0; k < 2; ++k) dst[m][k] = *(const LAS bf16x8*)(lds + PG8_SA(b, h) + aoff + m * 2048 + k * 1024); } while (0)
; #define PG8_LDB(dst, b, h) do { _Pragma("unroll") for (int n = 0; n < 2; ++n) _Pragma("unroll") for (int k = 0; k < 2; ++k) dst[n][k] = *(const LAS bf16x8*)(lds + PG8_SB(b, h) + boff + n * 2048 + k * 1024); } while (0)
; #define PG8_MMA(ai, bj, At, Bt) do { __builtin_amdgcn_s_setprio(1); _Pragma("unroll") for (int m = 0; m < 4; ++m) _Pragma("unroll") for (int n = 0; n < 2; ++n) _Pragma("unroll") for (int k = 0; k < 2; ++k) \
;         acc[ai][bj][m][n] = __builtin_amdgcn_mfma_f32_16x16x32_bf16(Bt[n][k], At[m][k], acc[ai][bj][m][n], 0, 0, 0); __builtin_amdgcn_s_setprio(0); } while (0)
; #define PG8_WAIT_V(n) asm volatile("s_waitcnt vmcnt(" #n ")" ::: "memory")
; #define PG8_WAIT_L(n) asm volatile("s_waitcnt lgkmcnt(" #n ")" ::: "memory")
; #define PG8_BAR __builtin_amdgcn_s_barrier()
; #define PG8_SCHED __builtin_amdgcn_sched_barrier(0)
; template <class Epi, bool ALIGN_EPI = true>
; __device__ __forceinline__ void gemm_phase(LAS unsigned char* lds, const Gemm g, const StaticOrder& S, const Epi& E, int wave_k) {
;     ...
;             const bool last = (t == nt - 2);
;             const char* a1 = cA + (size_t)(t + 1) * kstep;
;             const char* a2 = last ? nA : cA + (size_t)(t + 2) * kstep; const char* b2 = last ? nB : cB + (size_t)(t + 2) * kstep;
;             const char* a3 = a2 + kstep; const char* b3 = b2 + kstep;
;             PG8_LDB(B0, 0, 0); PG8_LDB(B1, 0, 1); PG8_SCHED; PG8_LDA(At, 0, 0); PG8_STAGE(PG8_SA(1, 1), a1 + hstepA, voffA);
;             PG8_WAIT_V(8); PG8_WAIT_L(0); PG8_BAR; PG8_MMA(0, 0, At, B0); PG8_MMA(0, 1, At, B1); PG8_BAR; PG8_SCHED;
;             PG8_LDA(At, 0, 1); PG8_STAGE(PG8_SB(0, 0), b2, voffB); PG8_STAGE(PG8_SB(0, 1), b2 + hstepB, voffB); PG8_STAGE(PG8_SA(0, 0), a2, voffA);
;             PG8_WAIT_V(8); PG8_WAIT_L(0); PG8_BAR; PG8_MMA(1, 0, At, B0); PG8_MMA(1, 1, At, B1); PG8_BAR; PG8_SCHED;
.LBB0_170:
	s_add_u32 s16, s24, 0x100
	s_addc_u32 s17, s25, 0
	s_add_i32 s71, 0, 0x10000
	s_cmp_eq_u32 s70, 40
	s_cselect_b32 s29, s1, s17
	s_cselect_b32 s28, s0, s16
	v_add_u32_e32 v142, s71, v145
	s_cselect_b32 s27, s37, s47
	s_cselect_b32 s26, s36, s46
	s_add_i32 s72, 0, 0x14000
	ds_read_b128 v[138:141], v142
	ds_read_b128 v[148:151], v142 offset:1024
	ds_read_b128 v[152:155], v142 offset:2048
	ds_read_b128 v[156:159], v142 offset:3072
	v_add_u32_e32 v142, s72, v145
	ds_read_b128 v[162:165], v142
	ds_read_b128 v[166:169], v142 offset:1024
	ds_read_b128 v[170:173], v142 offset:2048
	ds_read_b128 v[174:177], v142 offset:3072
	v_lshl_add_u64 v[142:143], s[24:25], 0, v[134:135]
	s_add_i32 m0, s57, 0xc000
	ds_read_b128 v[178:181], v147
	ds_read_b128 v[182:185], v147 offset:1024
	ds_read_b128 v[186:189], v147 offset:2048
	ds_read_b128 v[190:193], v147 offset:3072
	ds_read_b128 v[194:197], v147 offset:4096
	ds_read_b128 v[198:201], v147 offset:5120
	ds_read_b128 v[202:205], v147 offset:6144
	ds_read_b128 v[206:209], v147 offset:7168
	global_load_lds_dwordx4 v[142:143], off
	v_lshl_add_u64 v[142:143], s[24:25], 0, v[136:137]
	s_add_i32 m0, s57, 0xe000
	s_nop 0
	global_load_lds_dwordx4 v[142:143], off
	s_waitcnt vmcnt(8) lgkmcnt(0)
	s_barrier
	v_mfma_f32_16x16x32_bf16 v[124:127], v[138:141], v[178:181], v[124:127]
	v_mfma_f32_16x16x32_bf16 v[120:123], v[152:155], v[178:181], v[120:123]
	v_mfma_f32_16x16x32_bf16 v[108:111], v[138:141], v[186:189], v[108:111]
	v_mfma_f32_16x16x32_bf16 v[104:107], v[152:155], v[186:189], v[104:107]
	v_mfma_f32_16x16x32_bf16 v[92:95], v[138:141], v[194:197], v[92:95]
	v_mfma_f32_16x16x32_bf16 v[88:91], v[152:155], v[194:197], v[88:91]
	v_mfma_f32_16x16x32_bf16 v[76:79], v[138:141], v[202:205], v[76:79]
	v_mfma_f32_16x16x32_bf16 v[72:75], v[152:155], v[202:205], v[72:75]
	v_mfma_f32_16x16x32_bf16 v[124:127], v[148:151], v[182:185], v[124:127]
	v_mfma_f32_16x16x32_bf16 v[120:123], v[156:159], v[182:185], v[120:123]
	v_mfma_f32_16x16x32_bf16 v[108:111], v[148:151], v[190:193], v[108:111]
	v_mfma_f32_16x16x32_bf16 v[104:107], v[156:159], v[190:193], v[104:107]
	v_mfma_f32_16x16x32_bf16 v[92:95], v[148:151], v[198:201], v[92:95]
	v_mfma_f32_16x16x32_bf16 v[88:91], v[156:159], v[198:201], v[88:91]
	v_mfma_f32_16x16x32_bf16 v[76:79], v[148:151], v[206:209], v[76:79]
	v_mfma_f32_16x16x32_bf16 v[72:75], v[156:159], v[206:209], v[72:75]
	v_mfma_f32_16x16x32_bf16 v[116:119], v[162:165], v[178:181], v[116:119]
	v_mfma_f32_16x16x32_bf16 v[112:115], v[170:173], v[178:181], v[112:115]
	v_mfma_f32_16x16x32_bf16 v[100:103], v[162:165], v[186:189], v[100:103]
	v_mfma_f32_16x16x32_bf16 v[96:99], v[170:173], v[186:189], v[96:99]
	v_mfma_f32_16x16x32_bf16 v[84:87], v[162:165], v[194:197], v[84:87]
	v_mfma_f32_16x16x32_bf16 v[80:83], v[170:173], v[194:197], v[80:83]
	v_mfma_f32_16x16x32_bf16 v[68:71], v[162:165], v[202:205], v[68:71]
	v_mfma_f32_16x16x32_bf16 v[64:67], v[170:173], v[202:205], v[64:67]
	v_mfma_f32_16x16x32_bf16 v[116:119], v[166:169], v[182:185], v[116:119]
	v_mfma_f32_16x16x32_bf16 v[112:115], v[174:177], v[182:185], v[112:115]
	v_mfma_f32_16x16x32_bf16 v[100:103], v[166:169], v[190:193], v[100:103]
	v_mfma_f32_16x16x32_bf16 v[96:99], v[174:177], v[190:193], v[96:99]
	v_mfma_f32_16x16x32_bf16 v[84:87], v[166:169], v[198:201], v[84:87]
	v_mfma_f32_16x16x32_bf16 v[80:83], v[174:177], v[198:201], v[80:83]
	v_mfma_f32_16x16x32_bf16 v[68:71], v[166:169], v[206:209], v[68:71]
	v_mfma_f32_16x16x32_bf16 v[64:67], v[174:177], v[206:209], v[64:67]
	s_barrier
	s_add_i32 s24, s71, s52
	v_lshl_add_u64 v[142:143], s[26:27], 0, v[160:161]
	s_mov_b32 m0, s24
	ds_read_b128 v[178:181], v147 offset:16384
	ds_read_b128 v[182:185], v147 offset:17408
	ds_read_b128 v[186:189], v147 offset:18432
	ds_read_b128 v[190:193], v147 offset:19456
	ds_read_b128 v[194:197], v147 offset:20480
	ds_read_b128 v[198:201], v147 offset:21504
	ds_read_b128 v[202:205], v147 offset:22528
	ds_read_b128 v[206:209], v147 offset:23552
	global_load_lds_dwordx4 v[142:143], off
	s_add_i32 m0, s24, 0x2000
	s_add_u32 s24, s26, 0xb0000
	v_lshl_add_u64 v[210:211], s[26:27], 0, v[132:133]
	s_addc_u32 s25, s27, 0
	s_add_i32 s71, s72, s52
	global_load_lds_dwordx4 v[210:211], off
	s_mov_b32 m0, s71
	v_lshl_add_u64 v[218:219], s[28:29], 0, v[130:131]
	global_load_lds_dwordx4 v160, s[24:25]
	s_add_i32 m0, s71, 0x2000
	s_nop 0
	global_load_lds_dwordx4 v132, s[24:25]
	v_lshl_add_u64 v[212:213], s[28:29], 0, v[128:129]
	s_mov_b32 m0, s57
	s_nop 0
	global_load_lds_dwordx4 v[212:213], off
	s_mov_b32 m0, s58
	s_nop 0
	global_load_lds_dwordx4 v[218:219], off
	s_waitcnt vmcnt(8) lgkmcnt(0)
	s_barrier
; #define PG8_STAGE(bufoff, gbase, voff) do { _Pragma("unroll") for (int _i = 0; _i < 2; ++_i) \
;         __builtin_amdgcn_global_load_lds((const unsigned*)((const char*)(gbase) + (voff)[_i]), (LAS unsigned*)(lds + (bufoff) + ldsw + _i * 8192), 16, 0, 0); } while (0)
; #define PG8_LDA(dst, b, h) do { _Pragma("unroll") for (int m = 0; m < 4; ++m) _Pragma("unroll") for (int k = 0; k < 2; ++k) dst[m][k] = *(const LAS bf16x8*)(lds + PG8_SA(b, h) + aoff + m * 2048 + k * 1024); } while (0)
; #define PG8_LDB(dst, b, h) do { _Pragma("unroll") for (int n = 0; n < 2; ++n) _Pragma("unroll") for (int k = 0; k < 2; ++k) dst[n][k] = *(const LAS bf16x8*)(lds + PG8_SB(b, h) + boff + n * 2048 + k * 1024); } while (0)
; #define PG8_MMA(ai, bj, At, Bt) do { __builtin_amdgcn_s_setprio(1); _Pragma("unroll") for (int m = 0; m < 4; ++m) _Pragma("unroll") for (int n = 0; n < 2; ++n) _Pragma("unroll") for (int k = 0; k < 2; ++k) \
;         acc[ai][bj][m][n] = __builtin_amdgcn_mfma_f32_16x16x32_bf16(Bt[n][k], At[m][k], acc[ai][bj][m][n], 0, 0, 0); __builtin_amdgcn_s_setprio(0); } while (0)
; #define PG8_WAIT_V(n) asm volatile("s_waitcnt vmcnt(" #n ")" ::: "memory")
; #define PG8_WAIT_L(n) asm volatile("s_waitcnt lgkmcnt(" #n ")" ::: "memory")
; #define PG8_BAR __builtin_amdgcn_s_barrier()
; #define PG8_SCHED __builtin_amdgcn_sched_barrier(0)
; template <class Epi, bool ALIGN_EPI = true>
; __device__ __forceinline__ void gemm_phase(LAS unsigned char* lds, const Gemm g, const StaticOrder& S, const Epi& E, int wave_k) {
;     ...
;             PG8_WAIT_V(8); PG8_WAIT_L(0); PG8_BAR; PG8_MMA(1, 0, At, B0); PG8_MMA(1, 1, At, B1); PG8_BAR; PG8_SCHED;
;             PG8_LDB(B0, 1, 0); PG8_LDB(B1, 1, 1); PG8_SCHED; PG8_LDA(At, 1, 0); PG8_STAGE(PG8_SA(0, 1), a2 + hstepA, voffA);
;             PG8_WAIT_V(8); PG8_WAIT_L(0); PG8_BAR; PG8_MMA(0, 0, At, B0); PG8_MMA(0, 1, At, B1); PG8_BAR; PG8_SCHED;
	v_mfma_f32_16x16x32_bf16 v[60:63], v[138:141], v[178:181], v[60:63]
	v_mfma_f32_16x16x32_bf16 v[56:59], v[152:155], v[178:181], v[56:59]
	v_mfma_f32_16x16x32_bf16 v[44:47], v[138:141], v[186:189], v[44:47]
	v_mfma_f32_16x16x32_bf16 v[40:43], v[152:155], v[186:189], v[40:43]
	v_mfma_f32_16x16x32_bf16 v[28:31], v[138:141], v[194:197], v[28:31]
	v_mfma_f32_16x16x32_bf16 v[24:27], v[152:155], v[194:197], v[24:27]
	v_mfma_f32_16x16x32_bf16 v[12:15], v[138:141], v[202:205], v[12:15]
	v_mfma_f32_16x16x32_bf16 v[8:11], v[152:155], v[202:205], v[8:11]
	v_mfma_f32_16x16x32_bf16 v[60:63], v[148:151], v[182:185], v[60:63]
	v_mfma_f32_16x16x32_bf16 v[56:59], v[156:159], v[182:185], v[56:59]
	v_mfma_f32_16x16x32_bf16 v[44:47], v[148:151], v[190:193], v[44:47]
	v_mfma_f32_16x16x32_bf16 v[40:43], v[156:159], v[190:193], v[40:43]
	v_mfma_f32_16x16x32_bf16 v[28:31], v[148:151], v[198:201], v[28:31]
	v_mfma_f32_16x16x32_bf16 v[24:27], v[156:159], v[198:201], v[24:27]
	v_mfma_f32_16x16x32_bf16 v[12:15], v[148:151], v[206:209], v[12:15]
	v_mfma_f32_16x16x32_bf16 v[8:11], v[156:159], v[206:209], v[8:11]
	v_mfma_f32_16x16x32_bf16 v[52:55], v[162:165], v[178:181], v[52:55]
	v_mfma_f32_16x16x32_bf16 v[48:51], v[170:173], v[178:181], v[48:51]
	v_mfma_f32_16x16x32_bf16 v[36:39], v[162:165], v[186:189], v[36:39]
	v_mfma_f32_16x16x32_bf16 v[32:35], v[170:173], v[186:189], v[32:35]
	v_mfma_f32_16x16x32_bf16 v[20:23], v[162:165], v[194:197], v[20:23]
	v_mfma_f32_16x16x32_bf16 v[16:19], v[170:173], v[194:197], v[16:19]
	v_mfma_f32_16x16x32_bf16 v[4:7], v[162:165], v[202:205], v[4:7]
	v_mfma_f32_16x16x32_bf16 v[0:3], v[170:173], v[202:205], v[0:3]
	v_mfma_f32_16x16x32_bf16 v[52:55], v[166:169], v[182:185], v[52:55]
	v_mfma_f32_16x16x32_bf16 v[48:51], v[174:177], v[182:185], v[48:51]
	v_mfma_f32_16x16x32_bf16 v[36:39], v[166:169], v[190:193], v[36:39]
	v_mfma_f32_16x16x32_bf16 v[32:35], v[174:177], v[190:193], v[32:35]
	v_mfma_f32_16x16x32_bf16 v[20:23], v[166:169], v[198:201], v[20:23]
	v_mfma_f32_16x16x32_bf16 v[16:19], v[174:177], v[198:201], v[16:19]
	v_mfma_f32_16x16x32_bf16 v[4:7], v[166:169], v[206:209], v[4:7]
	v_mfma_f32_16x16x32_bf16 v[0:3], v[174:177], v[206:209], v[0:3]
	s_barrier
	s_add_i32 s71, 0, 0x18000
	s_add_i32 s72, 0, 0x1c000
	v_add_u32_e32 v156, s71, v145
	v_add_u32_e32 v174, s72, v145
	ds_read_b128 v[138:141], v156
	ds_read_b128 v[148:151], v156 offset:1024
	ds_read_b128 v[152:155], v156 offset:2048
	ds_read_b128 v[156:159], v156 offset:3072
	ds_read_b128 v[162:165], v174
	ds_read_b128 v[166:169], v174 offset:1024
	ds_read_b128 v[170:173], v174 offset:2048
	ds_read_b128 v[174:177], v174 offset:3072
	s_add_u32 s24, s28, 0xb0000
	s_addc_u32 s25, s29, 0
	s_mov_b32 m0, s59
	ds_read_b128 v[178:181], v147 offset:32768
	ds_read_b128 v[182:185], v147 offset:33792
	ds_read_b128 v[186:189], v147 offset:34816
	ds_read_b128 v[190:193], v147 offset:35840
	ds_read_b128 v[194:197], v147 offset:36864
	ds_read_b128 v[198:201], v147 offset:37888
	ds_read_b128 v[202:205], v147 offset:38912
	ds_read_b128 v[206:209], v147 offset:39936
	global_load_lds_dwordx4 v128, s[24:25]
	s_mov_b32 m0, s60
	s_nop 0
	global_load_lds_dwordx4 v130, s[24:25]
	s_waitcnt vmcnt(8) lgkmcnt(0)
	s_barrier
	v_mfma_f32_16x16x32_bf16 v[124:127], v[138:141], v[178:181], v[124:127]
	v_mfma_f32_16x16x32_bf16 v[120:123], v[152:155], v[178:181], v[120:123]
	v_mfma_f32_16x16x32_bf16 v[108:111], v[138:141], v[186:189], v[108:111]
	v_mfma_f32_16x16x32_bf16 v[104:107], v[152:155], v[186:189], v[104:107]
	v_mfma_f32_16x16x32_bf16 v[92:95], v[138:141], v[194:197], v[92:95]
	v_mfma_f32_16x16x32_bf16 v[88:91], v[152:155], v[194:197], v[88:91]
	v_mfma_f32_16x16x32_bf16 v[76:79], v[138:141], v[202:205], v[76:79]
	v_mfma_f32_16x16x32_bf16 v[72:75], v[152:155], v[202:205], v[72:75]
	v_mfma_f32_16x16x32_bf16 v[124:127], v[148:151], v[182:185], v[124:127]
	v_mfma_f32_16x16x32_bf16 v[120:123], v[156:159], v[182:185], v[120:123]
	v_mfma_f32_16x16x32_bf16 v[108:111], v[148:151], v[190:193], v[108:111]
	v_mfma_f32_16x16x32_bf16 v[104:107], v[156:159], v[190:193], v[104:107]
	v_mfma_f32_16x16x32_bf16 v[92:95], v[148:151], v[198:201], v[92:95]
	v_mfma_f32_16x16x32_bf16 v[88:91], v[156:159], v[198:201], v[88:91]
	v_mfma_f32_16x16x32_bf16 v[76:79], v[148:151], v[206:209], v[76:79]
	v_mfma_f32_16x16x32_bf16 v[72:75], v[156:159], v[206:209], v[72:75]
	v_mfma_f32_16x16x32_bf16 v[116:119], v[162:165], v[178:181], v[116:119]
	v_mfma_f32_16x16x32_bf16 v[112:115], v[170:173], v[178:181], v[112:115]
	v_mfma_f32_16x16x32_bf16 v[100:103], v[162:165], v[186:189], v[100:103]
	v_mfma_f32_16x16x32_bf16 v[96:99], v[170:173], v[186:189], v[96:99]
	v_mfma_f32_16x16x32_bf16 v[84:87], v[162:165], v[194:197], v[84:87]
	v_mfma_f32_16x16x32_bf16 v[80:83], v[170:173], v[194:197], v[80:83]
	v_mfma_f32_16x16x32_bf16 v[68:71], v[162:165], v[202:205], v[68:71]
	v_mfma_f32_16x16x32_bf16 v[64:67], v[170:173], v[202:205], v[64:67]
	v_mfma_f32_16x16x32_bf16 v[116:119], v[166:169], v[182:185], v[116:119]
	v_mfma_f32_16x16x32_bf16 v[112:115], v[174:177], v[182:185], v[112:115]
	v_mfma_f32_16x16x32_bf16 v[100:103], v[166:169], v[190:193], v[100:103]
	v_mfma_f32_16x16x32_bf16 v[96:99], v[174:177], v[190:193], v[96:99]
	v_mfma_f32_16x16x32_bf16 v[84:87], v[166:169], v[198:201], v[84:87]
	v_mfma_f32_16x16x32_bf16 v[80:83], v[174:177], v[198:201], v[80:83]
	v_mfma_f32_16x16x32_bf16 v[68:71], v[166:169], v[206:209], v[68:71]
	v_mfma_f32_16x16x32_bf16 v[64:67], v[174:177], v[206:209], v[64:67]
	s_barrier
; #define PG8_STAGE(bufoff, gbase, voff) do { _Pragma("unroll") for (int _i = 0; _i < 2; ++_i) \
;         __builtin_amdgcn_global_load_lds((const unsigned*)((const char*)(gbase) + (voff)[_i]), (LAS unsigned*)(lds + (bufoff) + ldsw + _i * 8192), 16, 0, 0); } while (0)
; #define PG8_LDA(dst, b, h) do { _Pragma("unroll") for (int m = 0; m < 4; ++m) _Pragma("unroll") for (int k = 0; k < 2; ++k) dst[m][k] = *(const LAS bf16x8*)(lds + PG8_SA(b, h) + aoff + m * 2048 + k * 1024); } while (0)
; #define PG8_MMA(ai, bj, At, Bt) do { __builtin_amdgcn_s_setprio(1); _Pragma("unroll") for (int m = 0; m < 4; ++m) _Pragma("unroll") for (int n = 0; n < 2; ++n) _Pragma("unroll") for (int k = 0; k < 2; ++k) \
;         acc[ai][bj][m][n] = __builtin_amdgcn_mfma_f32_16x16x32_bf16(Bt[n][k], At[m][k], acc[ai][bj][m][n], 0, 0, 0); __builtin_amdgcn_s_setprio(0); } while (0)
; #define PG8_WAIT_V(n) asm volatile("s_waitcnt vmcnt(" #n ")" ::: "memory")
; #define PG8_WAIT_L(n) asm volatile("s_waitcnt lgkmcnt(" #n ")" ::: "memory")
; #define PG8_BAR __builtin_amdgcn_s_barrier()
; #define PG8_SCHED __builtin_amdgcn_sched_barrier(0)
; template <class Epi, bool ALIGN_EPI = true>
; __device__ __forceinline__ void gemm_phase(LAS unsigned char* lds, const Gemm g, const StaticOrder& S, const Epi& E, int wave_k) {
;     ...
;             PG8_LDA(At, 1, 1); PG8_STAGE(PG8_SB(1, 0), b3, voffB); PG8_STAGE(PG8_SB(1, 1), b3 + hstepB, voffB); PG8_STAGE(PG8_SA(1, 0), a3, voffA);
;             PG8_WAIT_V(8); PG8_WAIT_L(0); PG8_BAR; PG8_MMA(1, 0, At, B0); PG8_MMA(1, 1, At, B1); PG8_BAR; PG8_SCHED;
;         }
	s_add_i32 s24, s71, s52
	v_lshl_add_u64 v[142:143], v[142:143], 0, s[22:23]
	s_mov_b32 m0, s24
	ds_read_b128 v[178:181], v147 offset:49152
	ds_read_b128 v[182:185], v147 offset:50176
	ds_read_b128 v[186:189], v147 offset:51200
	ds_read_b128 v[190:193], v147 offset:52224
	ds_read_b128 v[194:197], v147 offset:53248
	ds_read_b128 v[198:201], v147 offset:54272
	ds_read_b128 v[202:205], v147 offset:55296
	ds_read_b128 v[206:209], v147 offset:56320
	global_load_lds_dwordx4 v[142:143], off
	s_add_i32 m0, s24, 0x2000
	s_add_u32 s24, s26, 0xb0080
	v_lshl_add_u64 v[142:143], v[210:211], 0, s[22:23]
	s_addc_u32 s25, s27, 0
	s_add_i32 s26, s72, s52
	global_load_lds_dwordx4 v[142:143], off
	s_mov_b32 m0, s26
	s_nop 0
	global_load_lds_dwordx4 v160, s[24:25]
	s_add_i32 m0, s26, 0x2000
	s_nop 0
	global_load_lds_dwordx4 v132, s[24:25]
	v_lshl_add_u64 v[142:143], v[212:213], 0, s[22:23]
	s_mov_b32 m0, s50
	s_nop 0
	global_load_lds_dwordx4 v[142:143], off
	v_lshl_add_u64 v[142:143], v[218:219], 0, s[22:23]
	s_mov_b32 m0, s51
	s_nop 0
	global_load_lds_dwordx4 v[142:143], off
	s_waitcnt vmcnt(8) lgkmcnt(0)
	s_barrier
	v_mfma_f32_16x16x32_bf16 v[60:63], v[138:141], v[178:181], v[60:63]
	v_mfma_f32_16x16x32_bf16 v[56:59], v[152:155], v[178:181], v[56:59]
	v_mfma_f32_16x16x32_bf16 v[44:47], v[138:141], v[186:189], v[44:47]
	v_mfma_f32_16x16x32_bf16 v[40:43], v[152:155], v[186:189], v[40:43]
	v_mfma_f32_16x16x32_bf16 v[28:31], v[138:141], v[194:197], v[28:31]
	v_mfma_f32_16x16x32_bf16 v[24:27], v[152:155], v[194:197], v[24:27]
	v_mfma_f32_16x16x32_bf16 v[12:15], v[138:141], v[202:205], v[12:15]
	v_mfma_f32_16x16x32_bf16 v[8:11], v[152:155], v[202:205], v[8:11]
	v_mfma_f32_16x16x32_bf16 v[60:63], v[148:151], v[182:185], v[60:63]
	v_mfma_f32_16x16x32_bf16 v[56:59], v[156:159], v[182:185], v[56:59]
	v_mfma_f32_16x16x32_bf16 v[44:47], v[148:151], v[190:193], v[44:47]
	v_mfma_f32_16x16x32_bf16 v[40:43], v[156:159], v[190:193], v[40:43]
	v_mfma_f32_16x16x32_bf16 v[28:31], v[148:151], v[198:201], v[28:31]
	v_mfma_f32_16x16x32_bf16 v[24:27], v[156:159], v[198:201], v[24:27]
	v_mfma_f32_16x16x32_bf16 v[12:15], v[148:151], v[206:209], v[12:15]
	v_mfma_f32_16x16x32_bf16 v[8:11], v[156:159], v[206:209], v[8:11]
	v_mfma_f32_16x16x32_bf16 v[52:55], v[162:165], v[178:181], v[52:55]
	v_mfma_f32_16x16x32_bf16 v[48:51], v[170:173], v[178:181], v[48:51]
	v_mfma_f32_16x16x32_bf16 v[36:39], v[162:165], v[186:189], v[36:39]
	v_mfma_f32_16x16x32_bf16 v[32:35], v[170:173], v[186:189], v[32:35]
	v_mfma_f32_16x16x32_bf16 v[20:23], v[162:165], v[194:197], v[20:23]
	v_mfma_f32_16x16x32_bf16 v[16:19], v[170:173], v[194:197], v[16:19]
	v_mfma_f32_16x16x32_bf16 v[4:7], v[162:165], v[202:205], v[4:7]
	v_mfma_f32_16x16x32_bf16 v[0:3], v[170:173], v[202:205], v[0:3]
	v_mfma_f32_16x16x32_bf16 v[52:55], v[166:169], v[182:185], v[52:55]
	v_mfma_f32_16x16x32_bf16 v[48:51], v[174:177], v[182:185], v[48:51]
	v_mfma_f32_16x16x32_bf16 v[36:39], v[166:169], v[190:193], v[36:39]
	v_mfma_f32_16x16x32_bf16 v[32:35], v[174:177], v[190:193], v[32:35]
	v_mfma_f32_16x16x32_bf16 v[20:23], v[166:169], v[198:201], v[20:23]
	v_mfma_f32_16x16x32_bf16 v[16:19], v[174:177], v[198:201], v[16:19]
	v_mfma_f32_16x16x32_bf16 v[4:7], v[166:169], v[206:209], v[4:7]
	v_mfma_f32_16x16x32_bf16 v[0:3], v[174:177], v[206:209], v[0:3]
	s_barrier
	s_add_i32 s70, s70, 2
	s_add_u32 s46, s46, 0x100
	s_addc_u32 s47, s47, 0
	s_cmp_gt_u32 s70, 41
	s_mov_b64 s[24:25], s[16:17]
	s_cbranch_scc0 .LBB0_170
	s_and_b64 vcc, exec, s[34:35]
	s_cbranch_vccz .LBB0_173
	s_barrier

; #define PG8_STAGE(bufoff, gbase, voff) do { _Pragma("unroll") for (int _i = 0; _i < 2; ++_i) \
;         __builtin_amdgcn_global_load_lds((const unsigned*)((const char*)(gbase) + (voff)[_i]), (LAS unsigned*)(lds + (bufoff) + ldsw + _i * 8192), 16, 0, 0); } while (0)
; #define PG8_LDA(dst, b, h) do { _Pragma("unroll") for (int m = 0; m < 4; ++m) _Pragma("unroll") for (int k = 0; k < 2; ++k) dst[m][k] = *(const LAS bf16x8*)(lds + PG8_SA(b, h) + aoff + m * 2048 + k * 1024); } while (0)
; #define PG8_LDB(dst, b, h) do { _Pragma("unroll") for (int n = 0; n < 2; ++n) _Pragma("unroll") for (int k = 0; k < 2; ++k) dst[n][k] = *(const LAS bf16x8*)(lds + PG8_SB(b, h) + boff + n * 2048 + k * 1024); } while (0)
; #define PG8_MMA(ai, bj, At, Bt) do { __builtin_amdgcn_s_setprio(1); _Pragma("unroll") for (int m = 0; m < 4; ++m) _Pragma("unroll") for (int n = 0; n < 2; ++n) _Pragma("unroll") for (int k = 0; k < 2; ++k) \
;         acc[ai][bj][m][n] = __builtin_amdgcn_mfma_f32_16x16x32_bf16(Bt[n][k], At[m][k], acc[ai][bj][m][n], 0, 0, 0); __builtin_amdgcn_s_setprio(0); } while (0)
; #define PG8_WAIT_V(n) asm volatile("s_waitcnt vmcnt(" #n ")" ::: "memory")
; #define PG8_WAIT_L(n) asm volatile("s_waitcnt lgkmcnt(" #n ")" ::: "memory")
; #define PG8_BAR __builtin_amdgcn_s_barrier()
; #define PG8_SCHED __builtin_amdgcn_sched_barrier(0)
; template <class Epi, bool ALIGN_EPI = true>
; __device__ __forceinline__ void gemm_phase(LAS unsigned char* lds, const Gemm g, const StaticOrder& S, const Epi& E, int wave_k) {
;     ...
;             const bool last = (t == nt - 2);
;             const char* a1 = cA + (size_t)(t + 1) * kstep;
;             const char* a2 = last ? nA : cA + (size_t)(t + 2) * kstep; const char* b2 = last ? nB : cB + (size_t)(t + 2) * kstep;
;             const char* a3 = a2 + kstep; const char* b3 = b2 + kstep;
;             PG8_LDB(B0, 0, 0); PG8_LDB(B1, 0, 1); PG8_SCHED; PG8_LDA(At, 0, 0); PG8_STAGE(PG8_SA(1, 1), a1 + hstepA, voffA);
;             PG8_WAIT_V(8); PG8_WAIT_L(0); PG8_BAR; PG8_MMA(0, 0, At, B0); PG8_MMA(0, 1, At, B1); PG8_BAR; PG8_SCHED;
;             PG8_LDA(At, 0, 1); PG8_STAGE(PG8_SB(0, 0), b2, voffB); PG8_STAGE(PG8_SB(0, 1), b2 + hstepB, voffB); PG8_STAGE(PG8_SA(0, 0), a2, voffA);
;             PG8_WAIT_V(8); PG8_WAIT_L(0); PG8_BAR; PG8_MMA(1, 0, At, B0); PG8_MMA(1, 1, At, B1); PG8_BAR; PG8_SCHED;
.LBB0_256:
	s_add_u32 s16, s46, 0xfffc0080
	s_addc_u32 s17, s47, -1
	s_add_i32 s49, 0, 0x10000
	s_cmp_eq_u32 s48, 12
	s_cselect_b32 s25, s1, s17
	s_cselect_b32 s24, s26, s16
	s_cselect_b32 s17, s27, s45
	s_cselect_b32 s16, s37, s41
	s_add_i32 s72, 0, 0x14000
	v_add_u32_e32 v152, s49, v168
	v_add_u32_e32 v160, s72, v168
	ds_read_b128 v[140:143], v152
	ds_read_b128 v[144:147], v152 offset:1024
	ds_read_b128 v[148:151], v152 offset:2048
	ds_read_b128 v[152:155], v152 offset:3072
	ds_read_b128 v[156:159], v160
	ds_read_b128 v[162:165], v160 offset:1024
	ds_read_b128 v[170:173], v160 offset:2048
	ds_read_b128 v[174:177], v160 offset:3072
	s_add_i32 m0, s59, 0xc000
	ds_read_b128 v[178:181], v169
	ds_read_b128 v[182:185], v169 offset:1024
	ds_read_b128 v[186:189], v169 offset:2048
	ds_read_b128 v[190:193], v169 offset:3072
	ds_read_b128 v[194:197], v169 offset:4096
	ds_read_b128 v[198:201], v169 offset:5120
	ds_read_b128 v[202:205], v169 offset:6144
	ds_read_b128 v[206:209], v169 offset:7168
	global_load_lds_dwordx4 v136, s[46:47]
	s_add_i32 m0, s59, 0xe000
	s_nop 0
	global_load_lds_dwordx4 v138, s[46:47]
	s_waitcnt vmcnt(8) lgkmcnt(0)
	s_barrier
	v_mfma_f32_16x16x32_bf16 v[124:127], v[140:143], v[178:181], v[124:127]
	v_mfma_f32_16x16x32_bf16 v[120:123], v[148:151], v[178:181], v[120:123]
	v_mfma_f32_16x16x32_bf16 v[108:111], v[140:143], v[186:189], v[108:111]
	v_mfma_f32_16x16x32_bf16 v[104:107], v[148:151], v[186:189], v[104:107]
	v_mfma_f32_16x16x32_bf16 v[92:95], v[140:143], v[194:197], v[92:95]
	v_mfma_f32_16x16x32_bf16 v[88:91], v[148:151], v[194:197], v[88:91]
	v_mfma_f32_16x16x32_bf16 v[76:79], v[140:143], v[202:205], v[76:79]
	v_mfma_f32_16x16x32_bf16 v[72:75], v[148:151], v[202:205], v[72:75]
	v_mfma_f32_16x16x32_bf16 v[124:127], v[144:147], v[182:185], v[124:127]
	v_mfma_f32_16x16x32_bf16 v[120:123], v[152:155], v[182:185], v[120:123]
	v_mfma_f32_16x16x32_bf16 v[108:111], v[144:147], v[190:193], v[108:111]
	v_mfma_f32_16x16x32_bf16 v[104:107], v[152:155], v[190:193], v[104:107]
	v_mfma_f32_16x16x32_bf16 v[92:95], v[144:147], v[198:201], v[92:95]
	v_mfma_f32_16x16x32_bf16 v[88:91], v[152:155], v[198:201], v[88:91]
	v_mfma_f32_16x16x32_bf16 v[76:79], v[144:147], v[206:209], v[76:79]
	v_mfma_f32_16x16x32_bf16 v[72:75], v[152:155], v[206:209], v[72:75]
	v_mfma_f32_16x16x32_bf16 v[116:119], v[156:159], v[178:181], v[116:119]
	v_mfma_f32_16x16x32_bf16 v[112:115], v[170:173], v[178:181], v[112:115]
	v_mfma_f32_16x16x32_bf16 v[100:103], v[156:159], v[186:189], v[100:103]
	v_mfma_f32_16x16x32_bf16 v[96:99], v[170:173], v[186:189], v[96:99]
	v_mfma_f32_16x16x32_bf16 v[84:87], v[156:159], v[194:197], v[84:87]
	v_mfma_f32_16x16x32_bf16 v[80:83], v[170:173], v[194:197], v[80:83]
	v_mfma_f32_16x16x32_bf16 v[68:71], v[156:159], v[202:205], v[68:71]
	v_mfma_f32_16x16x32_bf16 v[64:67], v[170:173], v[202:205], v[64:67]
	v_mfma_f32_16x16x32_bf16 v[116:119], v[162:165], v[182:185], v[116:119]
	v_mfma_f32_16x16x32_bf16 v[112:115], v[174:177], v[182:185], v[112:115]
	v_mfma_f32_16x16x32_bf16 v[100:103], v[162:165], v[190:193], v[100:103]
	v_mfma_f32_16x16x32_bf16 v[96:99], v[174:177], v[190:193], v[96:99]
	v_mfma_f32_16x16x32_bf16 v[84:87], v[162:165], v[198:201], v[84:87]
	v_mfma_f32_16x16x32_bf16 v[80:83], v[174:177], v[198:201], v[80:83]
	v_mfma_f32_16x16x32_bf16 v[68:71], v[162:165], v[206:209], v[68:71]
	v_mfma_f32_16x16x32_bf16 v[64:67], v[174:177], v[206:209], v[64:67]
	s_barrier
	s_add_i32 s49, s49, s58
	v_lshl_add_u64 v[210:211], s[16:17], 0, v[130:131]
	s_mov_b32 m0, s49
	ds_read_b128 v[178:181], v169 offset:16384
	ds_read_b128 v[182:185], v169 offset:17408
	ds_read_b128 v[186:189], v169 offset:18432
	ds_read_b128 v[190:193], v169 offset:19456
	ds_read_b128 v[194:197], v169 offset:20480
	ds_read_b128 v[198:201], v169 offset:21504
	ds_read_b128 v[202:205], v169 offset:22528
	ds_read_b128 v[206:209], v169 offset:23552
	global_load_lds_dwordx4 v[210:211], off
	s_add_i32 m0, s49, 0x2000
	s_add_u32 s66, s16, 0x40000
	v_lshl_add_u64 v[212:213], s[16:17], 0, v[134:135]
	s_addc_u32 s67, s17, 0
	s_add_i32 s49, s72, s58
	global_load_lds_dwordx4 v[212:213], off
	s_mov_b32 m0, s49
	v_lshl_add_u64 v[220:221], s[24:25], 0, v[132:133]
	global_load_lds_dwordx4 v130, s[66:67]
	s_add_i32 m0, s49, 0x2000
	s_nop 0
	global_load_lds_dwordx4 v134, s[66:67]
	v_lshl_add_u64 v[218:219], s[24:25], 0, v[128:129]
	s_mov_b32 m0, s59
	s_nop 0
	global_load_lds_dwordx4 v[218:219], off
	s_mov_b32 m0, s60
	s_nop 0
	global_load_lds_dwordx4 v[220:221], off
	s_waitcnt vmcnt(8) lgkmcnt(0)
	s_barrier
	v_mfma_f32_16x16x32_bf16 v[60:63], v[140:143], v[178:181], v[60:63]
	v_mfma_f32_16x16x32_bf16 v[56:59], v[148:151], v[178:181], v[56:59]
	v_mfma_f32_16x16x32_bf16 v[44:47], v[140:143], v[186:189], v[44:47]
	v_mfma_f32_16x16x32_bf16 v[40:43], v[148:151], v[186:189], v[40:43]
	v_mfma_f32_16x16x32_bf16 v[28:31], v[140:143], v[194:197], v[28:31]
	v_mfma_f32_16x16x32_bf16 v[24:27], v[148:151], v[194:197], v[24:27]
	v_mfma_f32_16x16x32_bf16 v[12:15], v[140:143], v[202:205], v[12:15]
	v_mfma_f32_16x16x32_bf16 v[8:11], v[148:151], v[202:205], v[8:11]
	v_mfma_f32_16x16x32_bf16 v[60:63], v[144:147], v[182:185], v[60:63]
	v_mfma_f32_16x16x32_bf16 v[56:59], v[152:155], v[182:185], v[56:59]
	v_mfma_f32_16x16x32_bf16 v[44:47], v[144:147], v[190:193], v[44:47]
	v_mfma_f32_16x16x32_bf16 v[40:43], v[152:155], v[190:193], v[40:43]
	v_mfma_f32_16x16x32_bf16 v[28:31], v[144:147], v[198:201], v[28:31]
	v_mfma_f32_16x16x32_bf16 v[24:27], v[152:155], v[198:201], v[24:27]
	v_mfma_f32_16x16x32_bf16 v[12:15], v[144:147], v[206:209], v[12:15]
	v_mfma_f32_16x16x32_bf16 v[8:11], v[152:155], v[206:209], v[8:11]
	v_mfma_f32_16x16x32_bf16 v[52:55], v[156:159], v[178:181], v[52:55]
	v_mfma_f32_16x16x32_bf16 v[48:51], v[170:173], v[178:181], v[48:51]
	v_mfma_f32_16x16x32_bf16 v[36:39], v[156:159], v[186:189], v[36:39]
	v_mfma_f32_16x16x32_bf16 v[32:35], v[170:173], v[186:189], v[32:35]
	v_mfma_f32_16x16x32_bf16 v[20:23], v[156:159], v[194:197], v[20:23]
	v_mfma_f32_16x16x32_bf16 v[16:19], v[170:173], v[194:197], v[16:19]
	v_mfma_f32_16x16x32_bf16 v[4:7], v[156:159], v[202:205], v[4:7]
	v_mfma_f32_16x16x32_bf16 v[0:3], v[170:173], v[202:205], v[0:3]
	v_mfma_f32_16x16x32_bf16 v[52:55], v[162:165], v[182:185], v[52:55]
	v_mfma_f32_16x16x32_bf16 v[48:51], v[174:177], v[182:185], v[48:51]
	v_mfma_f32_16x16x32_bf16 v[36:39], v[162:165], v[190:193], v[36:39]
	v_mfma_f32_16x16x32_bf16 v[32:35], v[174:177], v[190:193], v[32:35]
	v_mfma_f32_16x16x32_bf16 v[20:23], v[162:165], v[198:201], v[20:23]
	v_mfma_f32_16x16x32_bf16 v[16:19], v[174:177], v[198:201], v[16:19]
	v_mfma_f32_16x16x32_bf16 v[4:7], v[162:165], v[206:209], v[4:7]
	v_mfma_f32_16x16x32_bf16 v[0:3], v[174:177], v[206:209], v[0:3]
	s_barrier
; #define PG8_STAGE(bufoff, gbase, voff) do { _Pragma("unroll") for (int _i = 0; _i < 2; ++_i) \
;         __builtin_amdgcn_global_load_lds((const unsigned*)((const char*)(gbase) + (voff)[_i]), (LAS unsigned*)(lds + (bufoff) + ldsw + _i * 8192), 16, 0, 0); } while (0)
; #define PG8_LDA(dst, b, h) do { _Pragma("unroll") for (int m = 0; m < 4; ++m) _Pragma("unroll") for (int k = 0; k < 2; ++k) dst[m][k] = *(const LAS bf16x8*)(lds + PG8_SA(b, h) + aoff + m * 2048 + k * 1024); } while (0)
; #define PG8_LDB(dst, b, h) do { _Pragma("unroll") for (int n = 0; n < 2; ++n) _Pragma("unroll") for (int k = 0; k < 2; ++k) dst[n][k] = *(const LAS bf16x8*)(lds + PG8_SB(b, h) + boff + n * 2048 + k * 1024); } while (0)
; #define PG8_MMA(ai, bj, At, Bt) do { __builtin_amdgcn_s_setprio(1); _Pragma("unroll") for (int m = 0; m < 4; ++m) _Pragma("unroll") for (int n = 0; n < 2; ++n) _Pragma("unroll") for (int k = 0; k < 2; ++k) \
;         acc[ai][bj][m][n] = __builtin_amdgcn_mfma_f32_16x16x32_bf16(Bt[n][k], At[m][k], acc[ai][bj][m][n], 0, 0, 0); __builtin_amdgcn_s_setprio(0); } while (0)
; #define PG8_WAIT_V(n) asm volatile("s_waitcnt vmcnt(" #n ")" ::: "memory")
; #define PG8_WAIT_L(n) asm volatile("s_waitcnt lgkmcnt(" #n ")" ::: "memory")
; #define PG8_BAR __builtin_amdgcn_s_barrier()
; #define PG8_SCHED __builtin_amdgcn_sched_barrier(0)
; template <class Epi, bool ALIGN_EPI = true>
; __device__ __forceinline__ void gemm_phase(LAS unsigned char* lds, const Gemm g, const StaticOrder& S, const Epi& E, int wave_k) {
;     ...
;             PG8_LDB(B0, 1, 0); PG8_LDB(B1, 1, 1); PG8_SCHED; PG8_LDA(At, 1, 0); PG8_STAGE(PG8_SA(0, 1), a2 + hstepA, voffA);
;             PG8_WAIT_V(8); PG8_WAIT_L(0); PG8_BAR; PG8_MMA(0, 0, At, B0); PG8_MMA(0, 1, At, B1); PG8_BAR; PG8_SCHED;
;             PG8_LDA(At, 1, 1); PG8_STAGE(PG8_SB(1, 0), b3, voffB); PG8_STAGE(PG8_SB(1, 1), b3 + hstepB, voffB); PG8_STAGE(PG8_SA(1, 0), a3, voffA);
;             PG8_WAIT_V(8); PG8_WAIT_L(0); PG8_BAR; PG8_MMA(1, 0, At, B0); PG8_MMA(1, 1, At, B1); PG8_BAR; PG8_SCHED;
;         }
	s_add_i32 s49, 0, 0x18000
	s_add_i32 s66, 0, 0x1c000
	v_add_u32_e32 v152, s49, v168
	v_add_u32_e32 v160, s66, v168
	ds_read_b128 v[140:143], v152
	ds_read_b128 v[144:147], v152 offset:1024
	ds_read_b128 v[148:151], v152 offset:2048
	ds_read_b128 v[152:155], v152 offset:3072
	ds_read_b128 v[156:159], v160
	ds_read_b128 v[162:165], v160 offset:1024
	ds_read_b128 v[170:173], v160 offset:2048
	ds_read_b128 v[174:177], v160 offset:3072
	s_add_u32 s24, s24, 0x40000
	s_addc_u32 s25, s25, 0
	s_mov_b32 m0, s61
	ds_read_b128 v[178:181], v169 offset:32768
	ds_read_b128 v[182:185], v169 offset:33792
	ds_read_b128 v[186:189], v169 offset:34816
	ds_read_b128 v[190:193], v169 offset:35840
	ds_read_b128 v[194:197], v169 offset:36864
	ds_read_b128 v[198:201], v169 offset:37888
	ds_read_b128 v[202:205], v169 offset:38912
	ds_read_b128 v[206:209], v169 offset:39936
	global_load_lds_dwordx4 v128, s[24:25]
	s_mov_b32 m0, s62
	s_nop 0
	global_load_lds_dwordx4 v132, s[24:25]
	s_waitcnt vmcnt(8) lgkmcnt(0)
	s_barrier
	v_mfma_f32_16x16x32_bf16 v[124:127], v[140:143], v[178:181], v[124:127]
	v_mfma_f32_16x16x32_bf16 v[120:123], v[148:151], v[178:181], v[120:123]
	v_mfma_f32_16x16x32_bf16 v[108:111], v[140:143], v[186:189], v[108:111]
	v_mfma_f32_16x16x32_bf16 v[104:107], v[148:151], v[186:189], v[104:107]
	v_mfma_f32_16x16x32_bf16 v[92:95], v[140:143], v[194:197], v[92:95]
	v_mfma_f32_16x16x32_bf16 v[88:91], v[148:151], v[194:197], v[88:91]
	v_mfma_f32_16x16x32_bf16 v[76:79], v[140:143], v[202:205], v[76:79]
	v_mfma_f32_16x16x32_bf16 v[72:75], v[148:151], v[202:205], v[72:75]
	v_mfma_f32_16x16x32_bf16 v[124:127], v[144:147], v[182:185], v[124:127]
	v_mfma_f32_16x16x32_bf16 v[120:123], v[152:155], v[182:185], v[120:123]
	v_mfma_f32_16x16x32_bf16 v[108:111], v[144:147], v[190:193], v[108:111]
	v_mfma_f32_16x16x32_bf16 v[104:107], v[152:155], v[190:193], v[104:107]
	v_mfma_f32_16x16x32_bf16 v[92:95], v[144:147], v[198:201], v[92:95]
	v_mfma_f32_16x16x32_bf16 v[88:91], v[152:155], v[198:201], v[88:91]
	v_mfma_f32_16x16x32_bf16 v[76:79], v[144:147], v[206:209], v[76:79]
	v_mfma_f32_16x16x32_bf16 v[72:75], v[152:155], v[206:209], v[72:75]
	v_mfma_f32_16x16x32_bf16 v[116:119], v[156:159], v[178:181], v[116:119]
	v_mfma_f32_16x16x32_bf16 v[112:115], v[170:173], v[178:181], v[112:115]
	v_mfma_f32_16x16x32_bf16 v[100:103], v[156:159], v[186:189], v[100:103]
	v_mfma_f32_16x16x32_bf16 v[96:99], v[170:173], v[186:189], v[96:99]
	v_mfma_f32_16x16x32_bf16 v[84:87], v[156:159], v[194:197], v[84:87]
	v_mfma_f32_16x16x32_bf16 v[80:83], v[170:173], v[194:197], v[80:83]
	v_mfma_f32_16x16x32_bf16 v[68:71], v[156:159], v[202:205], v[68:71]
	v_mfma_f32_16x16x32_bf16 v[64:67], v[170:173], v[202:205], v[64:67]
	v_mfma_f32_16x16x32_bf16 v[116:119], v[162:165], v[182:185], v[116:119]
	v_mfma_f32_16x16x32_bf16 v[112:115], v[174:177], v[182:185], v[112:115]
	v_mfma_f32_16x16x32_bf16 v[100:103], v[162:165], v[190:193], v[100:103]
	v_mfma_f32_16x16x32_bf16 v[96:99], v[174:177], v[190:193], v[96:99]
	v_mfma_f32_16x16x32_bf16 v[84:87], v[162:165], v[198:201], v[84:87]
	v_mfma_f32_16x16x32_bf16 v[80:83], v[174:177], v[198:201], v[80:83]
	v_mfma_f32_16x16x32_bf16 v[68:71], v[162:165], v[206:209], v[68:71]
	v_mfma_f32_16x16x32_bf16 v[64:67], v[174:177], v[206:209], v[64:67]
	s_barrier
	s_add_i32 s24, s49, s58
	v_lshl_add_u64 v[210:211], v[210:211], 0, s[22:23]
	s_mov_b32 m0, s24
	ds_read_b128 v[178:181], v169 offset:49152
	ds_read_b128 v[182:185], v169 offset:50176
	ds_read_b128 v[186:189], v169 offset:51200
	ds_read_b128 v[190:193], v169 offset:52224
	ds_read_b128 v[194:197], v169 offset:53248
	ds_read_b128 v[198:201], v169 offset:54272
	ds_read_b128 v[202:205], v169 offset:55296
	ds_read_b128 v[206:209], v169 offset:56320
	global_load_lds_dwordx4 v[210:211], off
	s_add_i32 m0, s24, 0x2000
	s_add_u32 s16, s16, 0x40080
	v_lshl_add_u64 v[210:211], v[212:213], 0, s[22:23]
	s_addc_u32 s17, s17, 0
	s_add_i32 s24, s66, s58
	global_load_lds_dwordx4 v[210:211], off
	s_mov_b32 m0, s24
	s_nop 0
	global_load_lds_dwordx4 v130, s[16:17]
	s_add_i32 m0, s24, 0x2000
	s_nop 0
	global_load_lds_dwordx4 v134, s[16:17]
	v_lshl_add_u64 v[210:211], v[218:219], 0, s[22:23]
	s_mov_b32 m0, s64
	s_nop 0
	global_load_lds_dwordx4 v[210:211], off
	v_lshl_add_u64 v[210:211], v[220:221], 0, s[22:23]
	s_mov_b32 m0, s65
	s_nop 0
	global_load_lds_dwordx4 v[210:211], off
	s_waitcnt vmcnt(8) lgkmcnt(0)
	s_barrier
	v_mfma_f32_16x16x32_bf16 v[60:63], v[140:143], v[178:181], v[60:63]
	v_mfma_f32_16x16x32_bf16 v[56:59], v[148:151], v[178:181], v[56:59]
	v_mfma_f32_16x16x32_bf16 v[44:47], v[140:143], v[186:189], v[44:47]
	v_mfma_f32_16x16x32_bf16 v[40:43], v[148:151], v[186:189], v[40:43]
	v_mfma_f32_16x16x32_bf16 v[28:31], v[140:143], v[194:197], v[28:31]
	v_mfma_f32_16x16x32_bf16 v[24:27], v[148:151], v[194:197], v[24:27]
	v_mfma_f32_16x16x32_bf16 v[12:15], v[140:143], v[202:205], v[12:15]
	v_mfma_f32_16x16x32_bf16 v[8:11], v[148:151], v[202:205], v[8:11]
	v_mfma_f32_16x16x32_bf16 v[60:63], v[144:147], v[182:185], v[60:63]
	v_mfma_f32_16x16x32_bf16 v[56:59], v[152:155], v[182:185], v[56:59]
	v_mfma_f32_16x16x32_bf16 v[44:47], v[144:147], v[190:193], v[44:47]
	v_mfma_f32_16x16x32_bf16 v[40:43], v[152:155], v[190:193], v[40:43]
	v_mfma_f32_16x16x32_bf16 v[28:31], v[144:147], v[198:201], v[28:31]
	v_mfma_f32_16x16x32_bf16 v[24:27], v[152:155], v[198:201], v[24:27]
	v_mfma_f32_16x16x32_bf16 v[12:15], v[144:147], v[206:209], v[12:15]
	v_mfma_f32_16x16x32_bf16 v[8:11], v[152:155], v[206:209], v[8:11]
	v_mfma_f32_16x16x32_bf16 v[52:55], v[156:159], v[178:181], v[52:55]
	v_mfma_f32_16x16x32_bf16 v[48:51], v[170:173], v[178:181], v[48:51]
	v_mfma_f32_16x16x32_bf16 v[36:39], v[156:159], v[186:189], v[36:39]
	v_mfma_f32_16x16x32_bf16 v[32:35], v[170:173], v[186:189], v[32:35]
	v_mfma_f32_16x16x32_bf16 v[20:23], v[156:159], v[194:197], v[20:23]
	v_mfma_f32_16x16x32_bf16 v[16:19], v[170:173], v[194:197], v[16:19]
	v_mfma_f32_16x16x32_bf16 v[4:7], v[156:159], v[202:205], v[4:7]
	v_mfma_f32_16x16x32_bf16 v[0:3], v[170:173], v[202:205], v[0:3]
	v_mfma_f32_16x16x32_bf16 v[52:55], v[162:165], v[182:185], v[52:55]
	v_mfma_f32_16x16x32_bf16 v[48:51], v[174:177], v[182:185], v[48:51]
	v_mfma_f32_16x16x32_bf16 v[36:39], v[162:165], v[190:193], v[36:39]
	v_mfma_f32_16x16x32_bf16 v[32:35], v[174:177], v[190:193], v[32:35]
	v_mfma_f32_16x16x32_bf16 v[20:23], v[162:165], v[198:201], v[20:23]
	v_mfma_f32_16x16x32_bf16 v[16:19], v[174:177], v[198:201], v[16:19]
	v_mfma_f32_16x16x32_bf16 v[4:7], v[162:165], v[206:209], v[4:7]
	v_mfma_f32_16x16x32_bf16 v[0:3], v[174:177], v[206:209], v[0:3]
	s_barrier
	s_add_i32 s48, s48, 2
	s_add_u32 s46, s46, 0x100
	s_addc_u32 s47, s47, 0
	s_add_u32 s41, s41, 0x100
	s_addc_u32 s45, s45, 0
	s_cmp_gt_u32 s48, 13
	s_cbranch_scc0 .LBB0_256
	s_and_b64 vcc, exec, s[34:35]
	s_cbranch_vccz .LBB0_259
	s_barrier

; #define PG8_STAGE(bufoff, gbase, voff) do { _Pragma("unroll") for (int _i = 0; _i < 2; ++_i) \
;         __builtin_amdgcn_global_load_lds((const unsigned*)((const char*)(gbase) + (voff)[_i]), (LAS unsigned*)(lds + (bufoff) + ldsw + _i * 8192), 16, 0, 0); } while (0)
; #define PG8_LDA(dst, b, h) do { _Pragma("unroll") for (int m = 0; m < 4; ++m) _Pragma("unroll") for (int k = 0; k < 2; ++k) dst[m][k] = *(const LAS bf16x8*)(lds + PG8_SA(b, h) + aoff + m * 2048 + k * 1024); } while (0)
; #define PG8_LDB(dst, b, h) do { _Pragma("unroll") for (int n = 0; n < 2; ++n) _Pragma("unroll") for (int k = 0; k < 2; ++k) dst[n][k] = *(const LAS bf16x8*)(lds + PG8_SB(b, h) + boff + n * 2048 + k * 1024); } while (0)
; #define PG8_MMA(ai, bj, At, Bt) do { __builtin_amdgcn_s_setprio(1); _Pragma("unroll") for (int m = 0; m < 4; ++m) _Pragma("unroll") for (int n = 0; n < 2; ++n) _Pragma("unroll") for (int k = 0; k < 2; ++k) \
;         acc[ai][bj][m][n] = __builtin_amdgcn_mfma_f32_16x16x32_bf16(Bt[n][k], At[m][k], acc[ai][bj][m][n], 0, 0, 0); __builtin_amdgcn_s_setprio(0); } while (0)
; #define PG8_WAIT_V(n) asm volatile("s_waitcnt vmcnt(" #n ")" ::: "memory")
; #define PG8_WAIT_L(n) asm volatile("s_waitcnt lgkmcnt(" #n ")" ::: "memory")
; #define PG8_BAR __builtin_amdgcn_s_barrier()
; #define PG8_SCHED __builtin_amdgcn_sched_barrier(0)
; template <class Epi, bool ALIGN_EPI = true>
; __device__ __forceinline__ void gemm_phase(LAS unsigned char* lds, const Gemm g, const StaticOrder& S, const Epi& E, int wave_k) {
;     ...
;             const bool last = (t == nt - 2);
;             const char* a1 = cA + (size_t)(t + 1) * kstep;
;             const char* a2 = last ? nA : cA + (size_t)(t + 2) * kstep; const char* b2 = last ? nB : cB + (size_t)(t + 2) * kstep;
;             const char* a3 = a2 + kstep; const char* b3 = b2 + kstep;
;             PG8_LDB(B0, 0, 0); PG8_LDB(B1, 0, 1); PG8_SCHED; PG8_LDA(At, 0, 0); PG8_STAGE(PG8_SA(1, 1), a1 + hstepA, voffA);
;             PG8_WAIT_V(8); PG8_WAIT_L(0); PG8_BAR; PG8_MMA(0, 0, At, B0); PG8_MMA(0, 1, At, B1); PG8_BAR; PG8_SCHED;
;             PG8_LDA(At, 0, 1); PG8_STAGE(PG8_SB(0, 0), b2, voffB); PG8_STAGE(PG8_SB(0, 1), b2 + hstepB, voffB); PG8_STAGE(PG8_SA(0, 0), a2, voffA);
;             PG8_WAIT_V(8); PG8_WAIT_L(0); PG8_BAR; PG8_MMA(1, 0, At, B0); PG8_MMA(1, 1, At, B1); PG8_BAR; PG8_SCHED;
.LBB0_774:
	s_add_u32 s16, s24, 0x100
	s_addc_u32 s17, s25, 0
	s_add_i32 s61, 0, 0x10000
	s_cmp_eq_u32 s60, 2
	s_cselect_b32 s29, s19, s17
	s_cselect_b32 s28, s18, s16
	s_cselect_b32 s27, s21, s45
	s_cselect_b32 s26, s20, s44
	s_add_i32 s62, 0, 0x14000
	v_add_u32_e32 v154, s61, v139
	v_add_u32_e32 v158, s62, v139
	ds_read_b128 v[142:145], v154
	ds_read_b128 v[146:149], v154 offset:1024
	ds_read_b128 v[150:153], v154 offset:2048
	ds_read_b128 v[154:157], v154 offset:3072
	ds_read_b128 v[162:165], v158
	ds_read_b128 v[166:169], v158 offset:1024
	ds_read_b128 v[170:173], v158 offset:2048
	ds_read_b128 v[174:177], v158 offset:3072
	v_lshl_add_u64 v[158:159], s[24:25], 0, v[134:135]
	s_add_i32 m0, s48, 0xc000
	ds_read_b128 v[178:181], v141
	ds_read_b128 v[182:185], v141 offset:1024
	ds_read_b128 v[186:189], v141 offset:2048
	ds_read_b128 v[190:193], v141 offset:3072
	ds_read_b128 v[194:197], v141 offset:4096
	ds_read_b128 v[198:201], v141 offset:5120
	ds_read_b128 v[202:205], v141 offset:6144
	ds_read_b128 v[206:209], v141 offset:7168
	global_load_lds_dwordx4 v[158:159], off
	v_lshl_add_u64 v[158:159], s[24:25], 0, v[136:137]
	s_add_i32 m0, s48, 0xe000
	s_nop 0
	global_load_lds_dwordx4 v[158:159], off
	s_waitcnt vmcnt(8) lgkmcnt(0)
	s_barrier
	v_mfma_f32_16x16x32_bf16 v[124:127], v[142:145], v[178:181], v[124:127]
	v_mfma_f32_16x16x32_bf16 v[120:123], v[150:153], v[178:181], v[120:123]
	v_mfma_f32_16x16x32_bf16 v[116:119], v[142:145], v[186:189], v[116:119]
	v_mfma_f32_16x16x32_bf16 v[112:115], v[150:153], v[186:189], v[112:115]
	v_mfma_f32_16x16x32_bf16 v[100:103], v[142:145], v[194:197], v[100:103]
	v_mfma_f32_16x16x32_bf16 v[96:99], v[150:153], v[194:197], v[96:99]
	v_mfma_f32_16x16x32_bf16 v[84:87], v[142:145], v[202:205], v[84:87]
	v_mfma_f32_16x16x32_bf16 v[80:83], v[150:153], v[202:205], v[80:83]
	v_mfma_f32_16x16x32_bf16 v[124:127], v[146:149], v[182:185], v[124:127]
	v_mfma_f32_16x16x32_bf16 v[120:123], v[154:157], v[182:185], v[120:123]
	v_mfma_f32_16x16x32_bf16 v[116:119], v[146:149], v[190:193], v[116:119]
	v_mfma_f32_16x16x32_bf16 v[112:115], v[154:157], v[190:193], v[112:115]
	v_mfma_f32_16x16x32_bf16 v[100:103], v[146:149], v[198:201], v[100:103]
	v_mfma_f32_16x16x32_bf16 v[96:99], v[154:157], v[198:201], v[96:99]
	v_mfma_f32_16x16x32_bf16 v[84:87], v[146:149], v[206:209], v[84:87]
	v_mfma_f32_16x16x32_bf16 v[80:83], v[154:157], v[206:209], v[80:83]
	v_mfma_f32_16x16x32_bf16 v[108:111], v[162:165], v[178:181], v[108:111]
	v_mfma_f32_16x16x32_bf16 v[104:107], v[170:173], v[178:181], v[104:107]
	v_mfma_f32_16x16x32_bf16 v[92:95], v[162:165], v[186:189], v[92:95]
	v_mfma_f32_16x16x32_bf16 v[88:91], v[170:173], v[186:189], v[88:91]
	v_mfma_f32_16x16x32_bf16 v[76:79], v[162:165], v[194:197], v[76:79]
	v_mfma_f32_16x16x32_bf16 v[72:75], v[170:173], v[194:197], v[72:75]
	v_mfma_f32_16x16x32_bf16 v[68:71], v[162:165], v[202:205], v[68:71]
	v_mfma_f32_16x16x32_bf16 v[64:67], v[170:173], v[202:205], v[64:67]
	v_mfma_f32_16x16x32_bf16 v[108:111], v[166:169], v[182:185], v[108:111]
	v_mfma_f32_16x16x32_bf16 v[104:107], v[174:177], v[182:185], v[104:107]
	v_mfma_f32_16x16x32_bf16 v[92:95], v[166:169], v[190:193], v[92:95]
	v_mfma_f32_16x16x32_bf16 v[88:91], v[174:177], v[190:193], v[88:91]
	v_mfma_f32_16x16x32_bf16 v[76:79], v[166:169], v[198:201], v[76:79]
	v_mfma_f32_16x16x32_bf16 v[72:75], v[174:177], v[198:201], v[72:75]
	v_mfma_f32_16x16x32_bf16 v[68:71], v[166:169], v[206:209], v[68:71]
	v_mfma_f32_16x16x32_bf16 v[64:67], v[174:177], v[206:209], v[64:67]
	s_barrier
	s_add_i32 s24, s61, s46
	v_lshl_add_u64 v[158:159], s[26:27], 0, v[160:161]
	s_mov_b32 m0, s24
	ds_read_b128 v[178:181], v141 offset:16384
	ds_read_b128 v[182:185], v141 offset:17408
	ds_read_b128 v[186:189], v141 offset:18432
	ds_read_b128 v[190:193], v141 offset:19456
	ds_read_b128 v[194:197], v141 offset:20480
	ds_read_b128 v[198:201], v141 offset:21504
	ds_read_b128 v[202:205], v141 offset:22528
	ds_read_b128 v[206:209], v141 offset:23552
	global_load_lds_dwordx4 v[158:159], off
	s_add_i32 m0, s24, 0x2000
	s_add_u32 s24, s26, 0x18000
	v_lshl_add_u64 v[210:211], s[26:27], 0, v[128:129]
	s_addc_u32 s25, s27, 0
	s_add_i32 s61, s62, s46
	global_load_lds_dwordx4 v[210:211], off
	s_mov_b32 m0, s61
	v_lshl_add_u64 v[218:219], s[28:29], 0, v[130:131]
	global_load_lds_dwordx4 v160, s[24:25]
	s_add_i32 m0, s61, 0x2000
	s_nop 0
	global_load_lds_dwordx4 v128, s[24:25]
	v_lshl_add_u64 v[212:213], s[28:29], 0, v[132:133]
	s_mov_b32 m0, s48
	s_nop 0
	global_load_lds_dwordx4 v[212:213], off
	s_mov_b32 m0, s49
	s_nop 0
	global_load_lds_dwordx4 v[218:219], off
	s_waitcnt vmcnt(8) lgkmcnt(0)
	s_barrier
; #define PG8_STAGE(bufoff, gbase, voff) do { _Pragma("unroll") for (int _i = 0; _i < 2; ++_i) \
;         __builtin_amdgcn_global_load_lds((const unsigned*)((const char*)(gbase) + (voff)[_i]), (LAS unsigned*)(lds + (bufoff) + ldsw + _i * 8192), 16, 0, 0); } while (0)
; #define PG8_LDA(dst, b, h) do { _Pragma("unroll") for (int m = 0; m < 4; ++m) _Pragma("unroll") for (int k = 0; k < 2; ++k) dst[m][k] = *(const LAS bf16x8*)(lds + PG8_SA(b, h) + aoff + m * 2048 + k * 1024); } while (0)
; #define PG8_LDB(dst, b, h) do { _Pragma("unroll") for (int n = 0; n < 2; ++n) _Pragma("unroll") for (int k = 0; k < 2; ++k) dst[n][k] = *(const LAS bf16x8*)(lds + PG8_SB(b, h) + boff + n * 2048 + k * 1024); } while (0)
; #define PG8_MMA(ai, bj, At, Bt) do { __builtin_amdgcn_s_setprio(1); _Pragma("unroll") for (int m = 0; m < 4; ++m) _Pragma("unroll") for (int n = 0; n < 2; ++n) _Pragma("unroll") for (int k = 0; k < 2; ++k) \
;         acc[ai][bj][m][n] = __builtin_amdgcn_mfma_f32_16x16x32_bf16(Bt[n][k], At[m][k], acc[ai][bj][m][n], 0, 0, 0); __builtin_amdgcn_s_setprio(0); } while (0)
; #define PG8_WAIT_V(n) asm volatile("s_waitcnt vmcnt(" #n ")" ::: "memory")
; #define PG8_WAIT_L(n) asm volatile("s_waitcnt lgkmcnt(" #n ")" ::: "memory")
; #define PG8_BAR __builtin_amdgcn_s_barrier()
; #define PG8_SCHED __builtin_amdgcn_sched_barrier(0)
; template <class Epi, bool ALIGN_EPI = true>
; __device__ __forceinline__ void gemm_phase(LAS unsigned char* lds, const Gemm g, const StaticOrder& S, const Epi& E, int wave_k) {
;     ...
;             PG8_WAIT_V(8); PG8_WAIT_L(0); PG8_BAR; PG8_MMA(1, 0, At, B0); PG8_MMA(1, 1, At, B1); PG8_BAR; PG8_SCHED;
;             PG8_LDB(B0, 1, 0); PG8_LDB(B1, 1, 1); PG8_SCHED; PG8_LDA(At, 1, 0); PG8_STAGE(PG8_SA(0, 1), a2 + hstepA, voffA);
;             PG8_WAIT_V(8); PG8_WAIT_L(0); PG8_BAR; PG8_MMA(0, 0, At, B0); PG8_MMA(0, 1, At, B1); PG8_BAR; PG8_SCHED;
	v_mfma_f32_16x16x32_bf16 v[60:63], v[142:145], v[178:181], v[60:63]
	v_mfma_f32_16x16x32_bf16 v[56:59], v[150:153], v[178:181], v[56:59]
	v_mfma_f32_16x16x32_bf16 v[52:55], v[142:145], v[186:189], v[52:55]
	v_mfma_f32_16x16x32_bf16 v[48:51], v[150:153], v[186:189], v[48:51]
	v_mfma_f32_16x16x32_bf16 v[36:39], v[142:145], v[194:197], v[36:39]
	v_mfma_f32_16x16x32_bf16 v[32:35], v[150:153], v[194:197], v[32:35]
	v_mfma_f32_16x16x32_bf16 v[20:23], v[142:145], v[202:205], v[20:23]
	v_mfma_f32_16x16x32_bf16 v[16:19], v[150:153], v[202:205], v[16:19]
	v_mfma_f32_16x16x32_bf16 v[60:63], v[146:149], v[182:185], v[60:63]
	v_mfma_f32_16x16x32_bf16 v[56:59], v[154:157], v[182:185], v[56:59]
	v_mfma_f32_16x16x32_bf16 v[52:55], v[146:149], v[190:193], v[52:55]
	v_mfma_f32_16x16x32_bf16 v[48:51], v[154:157], v[190:193], v[48:51]
	v_mfma_f32_16x16x32_bf16 v[36:39], v[146:149], v[198:201], v[36:39]
	v_mfma_f32_16x16x32_bf16 v[32:35], v[154:157], v[198:201], v[32:35]
	v_mfma_f32_16x16x32_bf16 v[20:23], v[146:149], v[206:209], v[20:23]
	v_mfma_f32_16x16x32_bf16 v[16:19], v[154:157], v[206:209], v[16:19]
	v_mfma_f32_16x16x32_bf16 v[44:47], v[162:165], v[178:181], v[44:47]
	v_mfma_f32_16x16x32_bf16 v[40:43], v[170:173], v[178:181], v[40:43]
	v_mfma_f32_16x16x32_bf16 v[28:31], v[162:165], v[186:189], v[28:31]
	v_mfma_f32_16x16x32_bf16 v[24:27], v[170:173], v[186:189], v[24:27]
	v_mfma_f32_16x16x32_bf16 v[12:15], v[162:165], v[194:197], v[12:15]
	v_mfma_f32_16x16x32_bf16 v[8:11], v[170:173], v[194:197], v[8:11]
	v_mfma_f32_16x16x32_bf16 v[4:7], v[162:165], v[202:205], v[4:7]
	v_mfma_f32_16x16x32_bf16 v[0:3], v[170:173], v[202:205], v[0:3]
	v_mfma_f32_16x16x32_bf16 v[44:47], v[166:169], v[182:185], v[44:47]
	v_mfma_f32_16x16x32_bf16 v[40:43], v[174:177], v[182:185], v[40:43]
	v_mfma_f32_16x16x32_bf16 v[28:31], v[166:169], v[190:193], v[28:31]
	v_mfma_f32_16x16x32_bf16 v[24:27], v[174:177], v[190:193], v[24:27]
	v_mfma_f32_16x16x32_bf16 v[12:15], v[166:169], v[198:201], v[12:15]
	v_mfma_f32_16x16x32_bf16 v[8:11], v[174:177], v[198:201], v[8:11]
	v_mfma_f32_16x16x32_bf16 v[4:7], v[166:169], v[206:209], v[4:7]
	v_mfma_f32_16x16x32_bf16 v[0:3], v[174:177], v[206:209], v[0:3]
	s_barrier
	s_add_i32 s61, 0, 0x18000
	s_add_i32 s62, 0, 0x1c000
	v_add_u32_e32 v154, s61, v139
	v_add_u32_e32 v174, s62, v139
	ds_read_b128 v[142:145], v154
	ds_read_b128 v[146:149], v154 offset:1024
	ds_read_b128 v[150:153], v154 offset:2048
	ds_read_b128 v[154:157], v154 offset:3072
	ds_read_b128 v[162:165], v174
	ds_read_b128 v[166:169], v174 offset:1024
	ds_read_b128 v[170:173], v174 offset:2048
	ds_read_b128 v[174:177], v174 offset:3072
	s_add_u32 s24, s28, 0x28000
	s_addc_u32 s25, s29, 0
	s_mov_b32 m0, s50
	ds_read_b128 v[178:181], v141 offset:32768
	ds_read_b128 v[182:185], v141 offset:33792
	ds_read_b128 v[186:189], v141 offset:34816
	ds_read_b128 v[190:193], v141 offset:35840
	ds_read_b128 v[194:197], v141 offset:36864
	ds_read_b128 v[198:201], v141 offset:37888
	ds_read_b128 v[202:205], v141 offset:38912
	ds_read_b128 v[206:209], v141 offset:39936
	global_load_lds_dwordx4 v132, s[24:25]
	s_mov_b32 m0, s51
	s_nop 0
	global_load_lds_dwordx4 v130, s[24:25]
	s_waitcnt vmcnt(8) lgkmcnt(0)
	s_barrier
	v_mfma_f32_16x16x32_bf16 v[124:127], v[142:145], v[178:181], v[124:127]
	v_mfma_f32_16x16x32_bf16 v[120:123], v[150:153], v[178:181], v[120:123]
	v_mfma_f32_16x16x32_bf16 v[116:119], v[142:145], v[186:189], v[116:119]
	v_mfma_f32_16x16x32_bf16 v[112:115], v[150:153], v[186:189], v[112:115]
	v_mfma_f32_16x16x32_bf16 v[100:103], v[142:145], v[194:197], v[100:103]
	v_mfma_f32_16x16x32_bf16 v[96:99], v[150:153], v[194:197], v[96:99]
	v_mfma_f32_16x16x32_bf16 v[84:87], v[142:145], v[202:205], v[84:87]
	v_mfma_f32_16x16x32_bf16 v[80:83], v[150:153], v[202:205], v[80:83]
	v_mfma_f32_16x16x32_bf16 v[124:127], v[146:149], v[182:185], v[124:127]
	v_mfma_f32_16x16x32_bf16 v[120:123], v[154:157], v[182:185], v[120:123]
	v_mfma_f32_16x16x32_bf16 v[116:119], v[146:149], v[190:193], v[116:119]
	v_mfma_f32_16x16x32_bf16 v[112:115], v[154:157], v[190:193], v[112:115]
	v_mfma_f32_16x16x32_bf16 v[100:103], v[146:149], v[198:201], v[100:103]
	v_mfma_f32_16x16x32_bf16 v[96:99], v[154:157], v[198:201], v[96:99]
	v_mfma_f32_16x16x32_bf16 v[84:87], v[146:149], v[206:209], v[84:87]
	v_mfma_f32_16x16x32_bf16 v[80:83], v[154:157], v[206:209], v[80:83]
	v_mfma_f32_16x16x32_bf16 v[108:111], v[162:165], v[178:181], v[108:111]
	v_mfma_f32_16x16x32_bf16 v[104:107], v[170:173], v[178:181], v[104:107]
	v_mfma_f32_16x16x32_bf16 v[92:95], v[162:165], v[186:189], v[92:95]
	v_mfma_f32_16x16x32_bf16 v[88:91], v[170:173], v[186:189], v[88:91]
	v_mfma_f32_16x16x32_bf16 v[76:79], v[162:165], v[194:197], v[76:79]
	v_mfma_f32_16x16x32_bf16 v[72:75], v[170:173], v[194:197], v[72:75]
	v_mfma_f32_16x16x32_bf16 v[68:71], v[162:165], v[202:205], v[68:71]
	v_mfma_f32_16x16x32_bf16 v[64:67], v[170:173], v[202:205], v[64:67]
	v_mfma_f32_16x16x32_bf16 v[108:111], v[166:169], v[182:185], v[108:111]
	v_mfma_f32_16x16x32_bf16 v[104:107], v[174:177], v[182:185], v[104:107]
	v_mfma_f32_16x16x32_bf16 v[92:95], v[166:169], v[190:193], v[92:95]
	v_mfma_f32_16x16x32_bf16 v[88:91], v[174:177], v[190:193], v[88:91]
	v_mfma_f32_16x16x32_bf16 v[76:79], v[166:169], v[198:201], v[76:79]
	v_mfma_f32_16x16x32_bf16 v[72:75], v[174:177], v[198:201], v[72:75]
	v_mfma_f32_16x16x32_bf16 v[68:71], v[166:169], v[206:209], v[68:71]
	v_mfma_f32_16x16x32_bf16 v[64:67], v[174:177], v[206:209], v[64:67]
	s_barrier
; #define PG8_STAGE(bufoff, gbase, voff) do { _Pragma("unroll") for (int _i = 0; _i < 2; ++_i) \
;         __builtin_amdgcn_global_load_lds((const unsigned*)((const char*)(gbase) + (voff)[_i]), (LAS unsigned*)(lds + (bufoff) + ldsw + _i * 8192), 16, 0, 0); } while (0)
; #define PG8_LDA(dst, b, h) do { _Pragma("unroll") for (int m = 0; m < 4; ++m) _Pragma("unroll") for (int k = 0; k < 2; ++k) dst[m][k] = *(const LAS bf16x8*)(lds + PG8_SA(b, h) + aoff + m * 2048 + k * 1024); } while (0)
; #define PG8_MMA(ai, bj, At, Bt) do { __builtin_amdgcn_s_setprio(1); _Pragma("unroll") for (int m = 0; m < 4; ++m) _Pragma("unroll") for (int n = 0; n < 2; ++n) _Pragma("unroll") for (int k = 0; k < 2; ++k) \
;         acc[ai][bj][m][n] = __builtin_amdgcn_mfma_f32_16x16x32_bf16(Bt[n][k], At[m][k], acc[ai][bj][m][n], 0, 0, 0); __builtin_amdgcn_s_setprio(0); } while (0)
; #define PG8_WAIT_V(n) asm volatile("s_waitcnt vmcnt(" #n ")" ::: "memory")
; #define PG8_WAIT_L(n) asm volatile("s_waitcnt lgkmcnt(" #n ")" ::: "memory")
; #define PG8_BAR __builtin_amdgcn_s_barrier()
; #define PG8_SCHED __builtin_amdgcn_sched_barrier(0)
; template <class Epi, bool ALIGN_EPI = true>
; __device__ __forceinline__ void gemm_phase(LAS unsigned char* lds, const Gemm g, const StaticOrder& S, const Epi& E, int wave_k) {
;     ...
;             PG8_LDA(At, 1, 1); PG8_STAGE(PG8_SB(1, 0), b3, voffB); PG8_STAGE(PG8_SB(1, 1), b3 + hstepB, voffB); PG8_STAGE(PG8_SA(1, 0), a3, voffA);
;             PG8_WAIT_V(8); PG8_WAIT_L(0); PG8_BAR; PG8_MMA(1, 0, At, B0); PG8_MMA(1, 1, At, B1); PG8_BAR; PG8_SCHED;
;         }
	s_add_i32 s24, s61, s46
	v_lshl_add_u64 v[158:159], v[158:159], 0, s[22:23]
	s_mov_b32 m0, s24
	ds_read_b128 v[178:181], v141 offset:49152
	ds_read_b128 v[182:185], v141 offset:50176
	ds_read_b128 v[186:189], v141 offset:51200
	ds_read_b128 v[190:193], v141 offset:52224
	ds_read_b128 v[194:197], v141 offset:53248
	ds_read_b128 v[198:201], v141 offset:54272
	ds_read_b128 v[202:205], v141 offset:55296
	ds_read_b128 v[206:209], v141 offset:56320
	global_load_lds_dwordx4 v[158:159], off
	s_add_i32 m0, s24, 0x2000
	s_add_u32 s24, s26, 0x18080
	v_lshl_add_u64 v[158:159], v[210:211], 0, s[22:23]
	s_addc_u32 s25, s27, 0
	s_add_i32 s26, s62, s46
	global_load_lds_dwordx4 v[158:159], off
	s_mov_b32 m0, s26
	s_nop 0
	global_load_lds_dwordx4 v160, s[24:25]
	s_add_i32 m0, s26, 0x2000
	s_nop 0
	global_load_lds_dwordx4 v128, s[24:25]
	v_lshl_add_u64 v[158:159], v[212:213], 0, s[22:23]
	s_mov_b32 m0, s52
	s_nop 0
	global_load_lds_dwordx4 v[158:159], off
	v_lshl_add_u64 v[158:159], v[218:219], 0, s[22:23]
	s_mov_b32 m0, s53
	s_nop 0
	global_load_lds_dwordx4 v[158:159], off
	s_waitcnt vmcnt(8) lgkmcnt(0)
	s_barrier
	v_mfma_f32_16x16x32_bf16 v[60:63], v[142:145], v[178:181], v[60:63]
	v_mfma_f32_16x16x32_bf16 v[56:59], v[150:153], v[178:181], v[56:59]
	v_mfma_f32_16x16x32_bf16 v[52:55], v[142:145], v[186:189], v[52:55]
	v_mfma_f32_16x16x32_bf16 v[48:51], v[150:153], v[186:189], v[48:51]
	v_mfma_f32_16x16x32_bf16 v[36:39], v[142:145], v[194:197], v[36:39]
	v_mfma_f32_16x16x32_bf16 v[32:35], v[150:153], v[194:197], v[32:35]
	v_mfma_f32_16x16x32_bf16 v[20:23], v[142:145], v[202:205], v[20:23]
	v_mfma_f32_16x16x32_bf16 v[16:19], v[150:153], v[202:205], v[16:19]
	v_mfma_f32_16x16x32_bf16 v[60:63], v[146:149], v[182:185], v[60:63]
	v_mfma_f32_16x16x32_bf16 v[56:59], v[154:157], v[182:185], v[56:59]
	v_mfma_f32_16x16x32_bf16 v[52:55], v[146:149], v[190:193], v[52:55]
	v_mfma_f32_16x16x32_bf16 v[48:51], v[154:157], v[190:193], v[48:51]
	v_mfma_f32_16x16x32_bf16 v[36:39], v[146:149], v[198:201], v[36:39]
	v_mfma_f32_16x16x32_bf16 v[32:35], v[154:157], v[198:201], v[32:35]
	v_mfma_f32_16x16x32_bf16 v[20:23], v[146:149], v[206:209], v[20:23]
	v_mfma_f32_16x16x32_bf16 v[16:19], v[154:157], v[206:209], v[16:19]
	v_mfma_f32_16x16x32_bf16 v[44:47], v[162:165], v[178:181], v[44:47]
	v_mfma_f32_16x16x32_bf16 v[40:43], v[170:173], v[178:181], v[40:43]
	v_mfma_f32_16x16x32_bf16 v[28:31], v[162:165], v[186:189], v[28:31]
	v_mfma_f32_16x16x32_bf16 v[24:27], v[170:173], v[186:189], v[24:27]
	v_mfma_f32_16x16x32_bf16 v[12:15], v[162:165], v[194:197], v[12:15]
	v_mfma_f32_16x16x32_bf16 v[8:11], v[170:173], v[194:197], v[8:11]
	v_mfma_f32_16x16x32_bf16 v[4:7], v[162:165], v[202:205], v[4:7]
	v_mfma_f32_16x16x32_bf16 v[0:3], v[170:173], v[202:205], v[0:3]
	v_mfma_f32_16x16x32_bf16 v[44:47], v[166:169], v[182:185], v[44:47]
	v_mfma_f32_16x16x32_bf16 v[40:43], v[174:177], v[182:185], v[40:43]
	v_mfma_f32_16x16x32_bf16 v[28:31], v[166:169], v[190:193], v[28:31]
	v_mfma_f32_16x16x32_bf16 v[24:27], v[174:177], v[190:193], v[24:27]
	v_mfma_f32_16x16x32_bf16 v[12:15], v[166:169], v[198:201], v[12:15]
	v_mfma_f32_16x16x32_bf16 v[8:11], v[174:177], v[198:201], v[8:11]
	v_mfma_f32_16x16x32_bf16 v[4:7], v[166:169], v[206:209], v[4:7]
	v_mfma_f32_16x16x32_bf16 v[0:3], v[174:177], v[206:209], v[0:3]
	s_barrier
	s_add_i32 s60, s60, 2
	s_add_u32 s44, s44, 0x100
	s_addc_u32 s45, s45, 0
	s_cmp_gt_u32 s60, 3
	s_mov_b64 s[24:25], s[16:17]
	s_cbranch_scc0 .LBB0_774
	s_and_b64 vcc, exec, s[14:15]
	s_cbranch_vccz .LBB0_777
	s_barrier

; #define PG8_STAGE(bufoff, gbase, voff) do { _Pragma("unroll") for (int _i = 0; _i < 2; ++_i) \
;         __builtin_amdgcn_global_load_lds((const unsigned*)((const char*)(gbase) + (voff)[_i]), (LAS unsigned*)(lds + (bufoff) + ldsw + _i * 8192), 16, 0, 0); } while (0)
; #define PG8_LDA(dst, b, h) do { _Pragma("unroll") for (int m = 0; m < 4; ++m) _Pragma("unroll") for (int k = 0; k < 2; ++k) dst[m][k] = *(const LAS bf16x8*)(lds + PG8_SA(b, h) + aoff + m * 2048 + k * 1024); } while (0)
; #define PG8_LDB(dst, b, h) do { _Pragma("unroll") for (int n = 0; n < 2; ++n) _Pragma("unroll") for (int k = 0; k < 2; ++k) dst[n][k] = *(const LAS bf16x8*)(lds + PG8_SB(b, h) + boff + n * 2048 + k * 1024); } while (0)
; #define PG8_MMA(ai, bj, At, Bt) do { __builtin_amdgcn_s_setprio(1); _Pragma("unroll") for (int m = 0; m < 4; ++m) _Pragma("unroll") for (int n = 0; n < 2; ++n) _Pragma("unroll") for (int k = 0; k < 2; ++k) \
;         acc[ai][bj][m][n] = __builtin_amdgcn_mfma_f32_16x16x32_bf16(Bt[n][k], At[m][k], acc[ai][bj][m][n], 0, 0, 0); __builtin_amdgcn_s_setprio(0); } while (0)
; #define PG8_WAIT_V(n) asm volatile("s_waitcnt vmcnt(" #n ")" ::: "memory")
; #define PG8_WAIT_L(n) asm volatile("s_waitcnt lgkmcnt(" #n ")" ::: "memory")
; #define PG8_BAR __builtin_amdgcn_s_barrier()
; #define PG8_SCHED __builtin_amdgcn_sched_barrier(0)
; template <class Epi, bool ALIGN_EPI = true>
; __device__ __forceinline__ void gemm_phase(LAS unsigned char* lds, const Gemm g, const StaticOrder& S, const Epi& E, int wave_k) {
;     ...
;             const bool last = (t == nt - 2);
;             const char* a1 = cA + (size_t)(t + 1) * kstep;
;             const char* a2 = last ? nA : cA + (size_t)(t + 2) * kstep; const char* b2 = last ? nB : cB + (size_t)(t + 2) * kstep;
;             const char* a3 = a2 + kstep; const char* b3 = b2 + kstep;
;             PG8_LDB(B0, 0, 0); PG8_LDB(B1, 0, 1); PG8_SCHED; PG8_LDA(At, 0, 0); PG8_STAGE(PG8_SA(1, 1), a1 + hstepA, voffA);
;             PG8_WAIT_V(8); PG8_WAIT_L(0); PG8_BAR; PG8_MMA(0, 0, At, B0); PG8_MMA(0, 1, At, B1); PG8_BAR; PG8_SCHED;
;             PG8_LDA(At, 0, 1); PG8_STAGE(PG8_SB(0, 0), b2, voffB); PG8_STAGE(PG8_SB(0, 1), b2 + hstepB, voffB); PG8_STAGE(PG8_SA(0, 0), a2, voffA);
;             PG8_WAIT_V(8); PG8_WAIT_L(0); PG8_BAR; PG8_MMA(1, 0, At, B0); PG8_MMA(1, 1, At, B1); PG8_BAR; PG8_SCHED;
.LBB0_800:
	s_add_u32 s25, s20, s24
	s_addc_u32 s46, s21, 0
	s_add_u32 s28, s25, 0x100
	s_addc_u32 s29, s46, 0
	s_and_b64 s[26:27], s[16:17], exec
	s_cselect_b32 s27, s37, s29
	s_cselect_b32 s26, s36, s28
	s_add_u32 s24, s18, s24
	s_addc_u32 s28, s19, 0
	s_add_u32 s24, s24, 0x100
	s_addc_u32 s28, s28, 0
	s_add_i32 s79, 0, 0x10000
	s_and_b64 s[16:17], s[16:17], exec
	s_cselect_b32 s29, s35, s28
	s_cselect_b32 s28, s70, s24
	s_add_i32 s17, 0, 0x14000
	s_add_u32 s48, s25, 0x28080
	s_addc_u32 s49, s46, 0
	s_add_i32 s78, s79, s57
	s_add_i32 m0, s58, 0xc000
	s_add_i32 s81, s58, 0xe000
	s_add_i32 s75, s78, 0x2000
	s_add_u32 s46, s28, 0x10000
	v_add_u32_e32 v150, s79, v135
	v_add_u32_e32 v158, s17, v135
	s_addc_u32 s47, s29, 0
	s_add_i32 s77, s17, s57
	ds_read_b128 v[138:141], v150
	ds_read_b128 v[142:145], v150 offset:1024
	ds_read_b128 v[146:149], v150 offset:2048
	ds_read_b128 v[150:153], v150 offset:3072
	ds_read_b128 v[154:157], v158
	ds_read_b128 v[162:165], v158 offset:1024
	ds_read_b128 v[166:169], v158 offset:2048
	ds_read_b128 v[170:173], v158 offset:3072
	s_add_i32 s76, s77, 0x2000
	s_add_i32 s74, 0, 0x18000
	s_add_i32 s73, 0, 0x1c000
	s_add_u32 s24, s26, 0x28000
	s_addc_u32 s25, s27, 0
	s_add_i32 s72, s74, s57
	s_add_i32 s71, s72, 0x2000
	s_add_u32 s16, s28, 0x10080
	s_addc_u32 s17, s29, 0
	s_add_i32 s80, s73, s57
	s_add_i32 s79, s80, 0x2000
	ds_read_b128 v[174:177], v137
	ds_read_b128 v[178:181], v137 offset:1024
	ds_read_b128 v[182:185], v137 offset:2048
	ds_read_b128 v[186:189], v137 offset:3072
	ds_read_b128 v[190:193], v137 offset:4096
	ds_read_b128 v[194:197], v137 offset:5120
	ds_read_b128 v[198:201], v137 offset:6144
	ds_read_b128 v[202:205], v137 offset:7168
	global_load_lds_dwordx4 v128, s[48:49]
	s_mov_b32 m0, s81
	s_nop 0
	global_load_lds_dwordx4 v130, s[48:49]
	s_waitcnt vmcnt(8) lgkmcnt(0)
	s_barrier
	v_mfma_f32_16x16x32_bf16 v[124:127], v[138:141], v[174:177], v[124:127]
	v_mfma_f32_16x16x32_bf16 v[120:123], v[146:149], v[174:177], v[120:123]
	v_mfma_f32_16x16x32_bf16 v[116:119], v[138:141], v[182:185], v[116:119]
	v_mfma_f32_16x16x32_bf16 v[112:115], v[146:149], v[182:185], v[112:115]
	v_mfma_f32_16x16x32_bf16 v[100:103], v[138:141], v[190:193], v[100:103]
	v_mfma_f32_16x16x32_bf16 v[96:99], v[146:149], v[190:193], v[96:99]
	v_mfma_f32_16x16x32_bf16 v[84:87], v[138:141], v[198:201], v[84:87]
	v_mfma_f32_16x16x32_bf16 v[80:83], v[146:149], v[198:201], v[80:83]
	v_mfma_f32_16x16x32_bf16 v[124:127], v[142:145], v[178:181], v[124:127]
	v_mfma_f32_16x16x32_bf16 v[120:123], v[150:153], v[178:181], v[120:123]
	v_mfma_f32_16x16x32_bf16 v[116:119], v[142:145], v[186:189], v[116:119]
	v_mfma_f32_16x16x32_bf16 v[112:115], v[150:153], v[186:189], v[112:115]
	v_mfma_f32_16x16x32_bf16 v[100:103], v[142:145], v[194:197], v[100:103]
	v_mfma_f32_16x16x32_bf16 v[96:99], v[150:153], v[194:197], v[96:99]
	v_mfma_f32_16x16x32_bf16 v[84:87], v[142:145], v[202:205], v[84:87]
	v_mfma_f32_16x16x32_bf16 v[80:83], v[150:153], v[202:205], v[80:83]
	v_mfma_f32_16x16x32_bf16 v[108:111], v[154:157], v[174:177], v[108:111]
	v_mfma_f32_16x16x32_bf16 v[104:107], v[166:169], v[174:177], v[104:107]
	v_mfma_f32_16x16x32_bf16 v[92:95], v[154:157], v[182:185], v[92:95]
	v_mfma_f32_16x16x32_bf16 v[88:91], v[166:169], v[182:185], v[88:91]
	v_mfma_f32_16x16x32_bf16 v[76:79], v[154:157], v[190:193], v[76:79]
	v_mfma_f32_16x16x32_bf16 v[72:75], v[166:169], v[190:193], v[72:75]
	v_mfma_f32_16x16x32_bf16 v[68:71], v[154:157], v[198:201], v[68:71]
	v_mfma_f32_16x16x32_bf16 v[64:67], v[166:169], v[198:201], v[64:67]
	v_mfma_f32_16x16x32_bf16 v[108:111], v[162:165], v[178:181], v[108:111]
	v_mfma_f32_16x16x32_bf16 v[104:107], v[170:173], v[178:181], v[104:107]
	v_mfma_f32_16x16x32_bf16 v[92:95], v[162:165], v[186:189], v[92:95]
	v_mfma_f32_16x16x32_bf16 v[88:91], v[170:173], v[186:189], v[88:91]
	v_mfma_f32_16x16x32_bf16 v[76:79], v[162:165], v[194:197], v[76:79]
	v_mfma_f32_16x16x32_bf16 v[72:75], v[170:173], v[194:197], v[72:75]
	v_mfma_f32_16x16x32_bf16 v[68:71], v[162:165], v[202:205], v[68:71]
	v_mfma_f32_16x16x32_bf16 v[64:67], v[170:173], v[202:205], v[64:67]
	s_barrier
	s_mov_b32 m0, s78
	v_lshl_add_u64 v[158:159], s[28:29], 0, v[160:161]
	ds_read_b128 v[174:177], v137 offset:16384
	ds_read_b128 v[178:181], v137 offset:17408
	ds_read_b128 v[182:185], v137 offset:18432
	ds_read_b128 v[186:189], v137 offset:19456
	ds_read_b128 v[190:193], v137 offset:20480
	ds_read_b128 v[194:197], v137 offset:21504
	ds_read_b128 v[198:201], v137 offset:22528
	ds_read_b128 v[202:205], v137 offset:23552
	global_load_lds_dwordx4 v[158:159], off
	v_lshl_add_u64 v[206:207], s[28:29], 0, v[132:133]
	s_mov_b32 m0, s75
	global_load_lds_dwordx4 v[206:207], off
	s_mov_b32 m0, s77
	v_lshl_add_u64 v[210:211], s[26:27], 0, v[130:131]
	global_load_lds_dwordx4 v160, s[46:47]
	s_mov_b32 m0, s76
	s_nop 0
	global_load_lds_dwordx4 v132, s[46:47]
	v_lshl_add_u64 v[208:209], s[26:27], 0, v[128:129]
	s_mov_b32 m0, s58
	s_nop 0
	global_load_lds_dwordx4 v[208:209], off
	s_mov_b32 m0, s59
	s_nop 0
	global_load_lds_dwordx4 v[210:211], off
	s_waitcnt vmcnt(8) lgkmcnt(0)
	s_barrier
; #define PG8_STAGE(bufoff, gbase, voff) do { _Pragma("unroll") for (int _i = 0; _i < 2; ++_i) \
;         __builtin_amdgcn_global_load_lds((const unsigned*)((const char*)(gbase) + (voff)[_i]), (LAS unsigned*)(lds + (bufoff) + ldsw + _i * 8192), 16, 0, 0); } while (0)
; #define PG8_LDA(dst, b, h) do { _Pragma("unroll") for (int m = 0; m < 4; ++m) _Pragma("unroll") for (int k = 0; k < 2; ++k) dst[m][k] = *(const LAS bf16x8*)(lds + PG8_SA(b, h) + aoff + m * 2048 + k * 1024); } while (0)
; #define PG8_LDB(dst, b, h) do { _Pragma("unroll") for (int n = 0; n < 2; ++n) _Pragma("unroll") for (int k = 0; k < 2; ++k) dst[n][k] = *(const LAS bf16x8*)(lds + PG8_SB(b, h) + boff + n * 2048 + k * 1024); } while (0)
; #define PG8_MMA(ai, bj, At, Bt) do { __builtin_amdgcn_s_setprio(1); _Pragma("unroll") for (int m = 0; m < 4; ++m) _Pragma("unroll") for (int n = 0; n < 2; ++n) _Pragma("unroll") for (int k = 0; k < 2; ++k) \
;         acc[ai][bj][m][n] = __builtin_amdgcn_mfma_f32_16x16x32_bf16(Bt[n][k], At[m][k], acc[ai][bj][m][n], 0, 0, 0); __builtin_amdgcn_s_setprio(0); } while (0)
; #define PG8_WAIT_V(n) asm volatile("s_waitcnt vmcnt(" #n ")" ::: "memory")
; #define PG8_WAIT_L(n) asm volatile("s_waitcnt lgkmcnt(" #n ")" ::: "memory")
; #define PG8_BAR __builtin_amdgcn_s_barrier()
; #define PG8_SCHED __builtin_amdgcn_sched_barrier(0)
; template <class Epi, bool ALIGN_EPI = true>
; __device__ __forceinline__ void gemm_phase(LAS unsigned char* lds, const Gemm g, const StaticOrder& S, const Epi& E, int wave_k) {
;     ...
;             PG8_WAIT_V(8); PG8_WAIT_L(0); PG8_BAR; PG8_MMA(1, 0, At, B0); PG8_MMA(1, 1, At, B1); PG8_BAR; PG8_SCHED;
;             PG8_LDB(B0, 1, 0); PG8_LDB(B1, 1, 1); PG8_SCHED; PG8_LDA(At, 1, 0); PG8_STAGE(PG8_SA(0, 1), a2 + hstepA, voffA);
;             PG8_WAIT_V(8); PG8_WAIT_L(0); PG8_BAR; PG8_MMA(0, 0, At, B0); PG8_MMA(0, 1, At, B1); PG8_BAR; PG8_SCHED;
	v_mfma_f32_16x16x32_bf16 v[60:63], v[138:141], v[174:177], v[60:63]
	v_mfma_f32_16x16x32_bf16 v[56:59], v[146:149], v[174:177], v[56:59]
	v_mfma_f32_16x16x32_bf16 v[52:55], v[138:141], v[182:185], v[52:55]
	v_mfma_f32_16x16x32_bf16 v[48:51], v[146:149], v[182:185], v[48:51]
	v_mfma_f32_16x16x32_bf16 v[36:39], v[138:141], v[190:193], v[36:39]
	v_mfma_f32_16x16x32_bf16 v[32:35], v[146:149], v[190:193], v[32:35]
	v_mfma_f32_16x16x32_bf16 v[20:23], v[138:141], v[198:201], v[20:23]
	v_mfma_f32_16x16x32_bf16 v[16:19], v[146:149], v[198:201], v[16:19]
	v_mfma_f32_16x16x32_bf16 v[60:63], v[142:145], v[178:181], v[60:63]
	v_mfma_f32_16x16x32_bf16 v[56:59], v[150:153], v[178:181], v[56:59]
	v_mfma_f32_16x16x32_bf16 v[52:55], v[142:145], v[186:189], v[52:55]
	v_mfma_f32_16x16x32_bf16 v[48:51], v[150:153], v[186:189], v[48:51]
	v_mfma_f32_16x16x32_bf16 v[36:39], v[142:145], v[194:197], v[36:39]
	v_mfma_f32_16x16x32_bf16 v[32:35], v[150:153], v[194:197], v[32:35]
	v_mfma_f32_16x16x32_bf16 v[20:23], v[142:145], v[202:205], v[20:23]
	v_mfma_f32_16x16x32_bf16 v[16:19], v[150:153], v[202:205], v[16:19]
	v_mfma_f32_16x16x32_bf16 v[44:47], v[154:157], v[174:177], v[44:47]
	v_mfma_f32_16x16x32_bf16 v[40:43], v[166:169], v[174:177], v[40:43]
	v_mfma_f32_16x16x32_bf16 v[28:31], v[154:157], v[182:185], v[28:31]
	v_mfma_f32_16x16x32_bf16 v[24:27], v[166:169], v[182:185], v[24:27]
	v_mfma_f32_16x16x32_bf16 v[12:15], v[154:157], v[190:193], v[12:15]
	v_mfma_f32_16x16x32_bf16 v[8:11], v[166:169], v[190:193], v[8:11]
	v_mfma_f32_16x16x32_bf16 v[4:7], v[154:157], v[198:201], v[4:7]
	v_mfma_f32_16x16x32_bf16 v[0:3], v[166:169], v[198:201], v[0:3]
	v_mfma_f32_16x16x32_bf16 v[44:47], v[162:165], v[178:181], v[44:47]
	v_mfma_f32_16x16x32_bf16 v[40:43], v[170:173], v[178:181], v[40:43]
	v_mfma_f32_16x16x32_bf16 v[28:31], v[162:165], v[186:189], v[28:31]
	v_mfma_f32_16x16x32_bf16 v[24:27], v[170:173], v[186:189], v[24:27]
	v_mfma_f32_16x16x32_bf16 v[12:15], v[162:165], v[194:197], v[12:15]
	v_mfma_f32_16x16x32_bf16 v[8:11], v[170:173], v[194:197], v[8:11]
	v_mfma_f32_16x16x32_bf16 v[4:7], v[162:165], v[202:205], v[4:7]
	v_mfma_f32_16x16x32_bf16 v[0:3], v[170:173], v[202:205], v[0:3]
	s_barrier
	v_add_u32_e32 v150, s74, v135
	v_add_u32_e32 v170, s73, v135
	ds_read_b128 v[138:141], v150
	ds_read_b128 v[142:145], v150 offset:1024
	ds_read_b128 v[146:149], v150 offset:2048
	ds_read_b128 v[150:153], v150 offset:3072
	ds_read_b128 v[154:157], v170
	ds_read_b128 v[162:165], v170 offset:1024
	ds_read_b128 v[166:169], v170 offset:2048
	ds_read_b128 v[170:173], v170 offset:3072
	s_mov_b32 m0, s60
	ds_read_b128 v[174:177], v137 offset:32768
	ds_read_b128 v[178:181], v137 offset:33792
	ds_read_b128 v[182:185], v137 offset:34816
	ds_read_b128 v[186:189], v137 offset:35840
	ds_read_b128 v[190:193], v137 offset:36864
	ds_read_b128 v[194:197], v137 offset:37888
	ds_read_b128 v[198:201], v137 offset:38912
	ds_read_b128 v[202:205], v137 offset:39936
	global_load_lds_dwordx4 v128, s[24:25]
	s_mov_b32 m0, s61
	s_nop 0
	global_load_lds_dwordx4 v130, s[24:25]
	s_waitcnt vmcnt(8) lgkmcnt(0)
	s_barrier
	v_mfma_f32_16x16x32_bf16 v[124:127], v[138:141], v[174:177], v[124:127]
	v_mfma_f32_16x16x32_bf16 v[120:123], v[146:149], v[174:177], v[120:123]
	v_mfma_f32_16x16x32_bf16 v[116:119], v[138:141], v[182:185], v[116:119]
	v_mfma_f32_16x16x32_bf16 v[112:115], v[146:149], v[182:185], v[112:115]
	v_mfma_f32_16x16x32_bf16 v[100:103], v[138:141], v[190:193], v[100:103]
	v_mfma_f32_16x16x32_bf16 v[96:99], v[146:149], v[190:193], v[96:99]
	v_mfma_f32_16x16x32_bf16 v[84:87], v[138:141], v[198:201], v[84:87]
	v_mfma_f32_16x16x32_bf16 v[80:83], v[146:149], v[198:201], v[80:83]
	v_mfma_f32_16x16x32_bf16 v[124:127], v[142:145], v[178:181], v[124:127]
	v_mfma_f32_16x16x32_bf16 v[120:123], v[150:153], v[178:181], v[120:123]
	v_mfma_f32_16x16x32_bf16 v[116:119], v[142:145], v[186:189], v[116:119]
	v_mfma_f32_16x16x32_bf16 v[112:115], v[150:153], v[186:189], v[112:115]
	v_mfma_f32_16x16x32_bf16 v[100:103], v[142:145], v[194:197], v[100:103]
	v_mfma_f32_16x16x32_bf16 v[96:99], v[150:153], v[194:197], v[96:99]
	v_mfma_f32_16x16x32_bf16 v[84:87], v[142:145], v[202:205], v[84:87]
	v_mfma_f32_16x16x32_bf16 v[80:83], v[150:153], v[202:205], v[80:83]
	v_mfma_f32_16x16x32_bf16 v[108:111], v[154:157], v[174:177], v[108:111]
	v_mfma_f32_16x16x32_bf16 v[104:107], v[166:169], v[174:177], v[104:107]
	v_mfma_f32_16x16x32_bf16 v[92:95], v[154:157], v[182:185], v[92:95]
	v_mfma_f32_16x16x32_bf16 v[88:91], v[166:169], v[182:185], v[88:91]
	v_mfma_f32_16x16x32_bf16 v[76:79], v[154:157], v[190:193], v[76:79]
	v_mfma_f32_16x16x32_bf16 v[72:75], v[166:169], v[190:193], v[72:75]
	v_mfma_f32_16x16x32_bf16 v[68:71], v[154:157], v[198:201], v[68:71]
	v_mfma_f32_16x16x32_bf16 v[64:67], v[166:169], v[198:201], v[64:67]
	v_mfma_f32_16x16x32_bf16 v[108:111], v[162:165], v[178:181], v[108:111]
	v_mfma_f32_16x16x32_bf16 v[104:107], v[170:173], v[178:181], v[104:107]
	v_mfma_f32_16x16x32_bf16 v[92:95], v[162:165], v[186:189], v[92:95]
	v_mfma_f32_16x16x32_bf16 v[88:91], v[170:173], v[186:189], v[88:91]
	v_mfma_f32_16x16x32_bf16 v[76:79], v[162:165], v[194:197], v[76:79]
	v_mfma_f32_16x16x32_bf16 v[72:75], v[170:173], v[194:197], v[72:75]
	v_mfma_f32_16x16x32_bf16 v[68:71], v[162:165], v[202:205], v[68:71]
	v_mfma_f32_16x16x32_bf16 v[64:67], v[170:173], v[202:205], v[64:67]
	s_barrier
; #define PG8_STAGE(bufoff, gbase, voff) do { _Pragma("unroll") for (int _i = 0; _i < 2; ++_i) \
;         __builtin_amdgcn_global_load_lds((const unsigned*)((const char*)(gbase) + (voff)[_i]), (LAS unsigned*)(lds + (bufoff) + ldsw + _i * 8192), 16, 0, 0); } while (0)
; #define PG8_LDA(dst, b, h) do { _Pragma("unroll") for (int m = 0; m < 4; ++m) _Pragma("unroll") for (int k = 0; k < 2; ++k) dst[m][k] = *(const LAS bf16x8*)(lds + PG8_SA(b, h) + aoff + m * 2048 + k * 1024); } while (0)
; #define PG8_MMA(ai, bj, At, Bt) do { __builtin_amdgcn_s_setprio(1); _Pragma("unroll") for (int m = 0; m < 4; ++m) _Pragma("unroll") for (int n = 0; n < 2; ++n) _Pragma("unroll") for (int k = 0; k < 2; ++k) \
;         acc[ai][bj][m][n] = __builtin_amdgcn_mfma_f32_16x16x32_bf16(Bt[n][k], At[m][k], acc[ai][bj][m][n], 0, 0, 0); __builtin_amdgcn_s_setprio(0); } while (0)
; #define PG8_WAIT_V(n) asm volatile("s_waitcnt vmcnt(" #n ")" ::: "memory")
; #define PG8_WAIT_L(n) asm volatile("s_waitcnt lgkmcnt(" #n ")" ::: "memory")
; #define PG8_BAR __builtin_amdgcn_s_barrier()
; #define PG8_SCHED __builtin_amdgcn_sched_barrier(0)
; template <class Epi, bool ALIGN_EPI = true>
; __device__ __forceinline__ void gemm_phase(LAS unsigned char* lds, const Gemm g, const StaticOrder& S, const Epi& E, int wave_k) {
;     ...
;             PG8_LDA(At, 1, 1); PG8_STAGE(PG8_SB(1, 0), b3, voffB); PG8_STAGE(PG8_SB(1, 1), b3 + hstepB, voffB); PG8_STAGE(PG8_SA(1, 0), a3, voffA);
;             PG8_WAIT_V(8); PG8_WAIT_L(0); PG8_BAR; PG8_MMA(1, 0, At, B0); PG8_MMA(1, 1, At, B1); PG8_BAR; PG8_SCHED;
;         }
;         if constexpr (ALIGN_EPI) { if (wr == 0) PG8_BAR; }
	s_mov_b32 m0, s72
	v_lshl_add_u64 v[158:159], v[158:159], 0, s[22:23]
	ds_read_b128 v[174:177], v137 offset:49152
	ds_read_b128 v[178:181], v137 offset:50176
	ds_read_b128 v[182:185], v137 offset:51200
	ds_read_b128 v[186:189], v137 offset:52224
	ds_read_b128 v[190:193], v137 offset:53248
	ds_read_b128 v[194:197], v137 offset:54272
	ds_read_b128 v[198:201], v137 offset:55296
	ds_read_b128 v[202:205], v137 offset:56320
	global_load_lds_dwordx4 v[158:159], off
	v_lshl_add_u64 v[158:159], v[206:207], 0, s[22:23]
	s_mov_b32 m0, s71
	s_nop 0
	global_load_lds_dwordx4 v[158:159], off
	s_mov_b32 m0, s80
	s_nop 0
	global_load_lds_dwordx4 v160, s[16:17]
	s_mov_b32 m0, s79
	s_nop 0
	global_load_lds_dwordx4 v132, s[16:17]
	v_lshl_add_u64 v[158:159], v[208:209], 0, s[22:23]
	s_mov_b32 m0, s62
	s_nop 0
	global_load_lds_dwordx4 v[158:159], off
	v_lshl_add_u64 v[158:159], v[210:211], 0, s[22:23]
	s_mov_b32 m0, s63
	s_nop 0
	global_load_lds_dwordx4 v[158:159], off
	s_waitcnt vmcnt(8) lgkmcnt(0)
	s_barrier
	v_mfma_f32_16x16x32_bf16 v[60:63], v[138:141], v[174:177], v[60:63]
	v_mfma_f32_16x16x32_bf16 v[56:59], v[146:149], v[174:177], v[56:59]
	v_mfma_f32_16x16x32_bf16 v[52:55], v[138:141], v[182:185], v[52:55]
	v_mfma_f32_16x16x32_bf16 v[48:51], v[146:149], v[182:185], v[48:51]
	v_mfma_f32_16x16x32_bf16 v[36:39], v[138:141], v[190:193], v[36:39]
	v_mfma_f32_16x16x32_bf16 v[32:35], v[146:149], v[190:193], v[32:35]
	v_mfma_f32_16x16x32_bf16 v[20:23], v[138:141], v[198:201], v[20:23]
	v_mfma_f32_16x16x32_bf16 v[16:19], v[146:149], v[198:201], v[16:19]
	v_mfma_f32_16x16x32_bf16 v[60:63], v[142:145], v[178:181], v[60:63]
	v_mfma_f32_16x16x32_bf16 v[56:59], v[150:153], v[178:181], v[56:59]
	v_mfma_f32_16x16x32_bf16 v[52:55], v[142:145], v[186:189], v[52:55]
	v_mfma_f32_16x16x32_bf16 v[48:51], v[150:153], v[186:189], v[48:51]
	v_mfma_f32_16x16x32_bf16 v[36:39], v[142:145], v[194:197], v[36:39]
	v_mfma_f32_16x16x32_bf16 v[32:35], v[150:153], v[194:197], v[32:35]
	v_mfma_f32_16x16x32_bf16 v[20:23], v[142:145], v[202:205], v[20:23]
	v_mfma_f32_16x16x32_bf16 v[16:19], v[150:153], v[202:205], v[16:19]
	v_mfma_f32_16x16x32_bf16 v[44:47], v[154:157], v[174:177], v[44:47]
	v_mfma_f32_16x16x32_bf16 v[40:43], v[166:169], v[174:177], v[40:43]
	v_mfma_f32_16x16x32_bf16 v[28:31], v[154:157], v[182:185], v[28:31]
	v_mfma_f32_16x16x32_bf16 v[24:27], v[166:169], v[182:185], v[24:27]
	v_mfma_f32_16x16x32_bf16 v[12:15], v[154:157], v[190:193], v[12:15]
	v_mfma_f32_16x16x32_bf16 v[8:11], v[166:169], v[190:193], v[8:11]
	v_mfma_f32_16x16x32_bf16 v[4:7], v[154:157], v[198:201], v[4:7]
	v_mfma_f32_16x16x32_bf16 v[0:3], v[166:169], v[198:201], v[0:3]
	v_mfma_f32_16x16x32_bf16 v[44:47], v[162:165], v[178:181], v[44:47]
	v_mfma_f32_16x16x32_bf16 v[40:43], v[170:173], v[178:181], v[40:43]
	v_mfma_f32_16x16x32_bf16 v[28:31], v[162:165], v[186:189], v[28:31]
	v_mfma_f32_16x16x32_bf16 v[24:27], v[170:173], v[186:189], v[24:27]
	v_mfma_f32_16x16x32_bf16 v[12:15], v[162:165], v[194:197], v[12:15]
	v_mfma_f32_16x16x32_bf16 v[8:11], v[170:173], v[194:197], v[8:11]
	v_mfma_f32_16x16x32_bf16 v[4:7], v[162:165], v[202:205], v[4:7]
	v_mfma_f32_16x16x32_bf16 v[0:3], v[170:173], v[202:205], v[0:3]
	s_barrier
	s_movk_i32 s24, 0x100
	s_andn2_b64 vcc, exec, s[44:45]
	s_mov_b64 s[16:17], -1
	s_mov_b64 s[44:45], 0
	s_cbranch_vccz .LBB0_800
	s_and_b64 vcc, exec, s[14:15]
	s_cbranch_vccz .LBB0_803
	s_barrier

; #define PG8_STAGE(bufoff, gbase, voff) do { _Pragma("unroll") for (int _i = 0; _i < 2; ++_i) \
;         __builtin_amdgcn_global_load_lds((const unsigned*)((const char*)(gbase) + (voff)[_i]), (LAS unsigned*)(lds + (bufoff) + ldsw + _i * 8192), 16, 0, 0); } while (0)
; #define PG8_LDA(dst, b, h) do { _Pragma("unroll") for (int m = 0; m < 4; ++m) _Pragma("unroll") for (int k = 0; k < 2; ++k) dst[m][k] = *(const LAS bf16x8*)(lds + PG8_SA(b, h) + aoff + m * 2048 + k * 1024); } while (0)
; #define PG8_LDB(dst, b, h) do { _Pragma("unroll") for (int n = 0; n < 2; ++n) _Pragma("unroll") for (int k = 0; k < 2; ++k) dst[n][k] = *(const LAS bf16x8*)(lds + PG8_SB(b, h) + boff + n * 2048 + k * 1024); } while (0)
; #define PG8_MMA(ai, bj, At, Bt) do { __builtin_amdgcn_s_setprio(1); _Pragma("unroll") for (int m = 0; m < 4; ++m) _Pragma("unroll") for (int n = 0; n < 2; ++n) _Pragma("unroll") for (int k = 0; k < 2; ++k) \
;         acc[ai][bj][m][n] = __builtin_amdgcn_mfma_f32_16x16x32_bf16(Bt[n][k], At[m][k], acc[ai][bj][m][n], 0, 0, 0); __builtin_amdgcn_s_setprio(0); } while (0)
; #define PG8_WAIT_V(n) asm volatile("s_waitcnt vmcnt(" #n ")" ::: "memory")
; #define PG8_WAIT_L(n) asm volatile("s_waitcnt lgkmcnt(" #n ")" ::: "memory")
; #define PG8_BAR __builtin_amdgcn_s_barrier()
; #define PG8_SCHED __builtin_amdgcn_sched_barrier(0)
; template <class Epi, bool ALIGN_EPI = true>
; __device__ __forceinline__ void gemm_phase(LAS unsigned char* lds, const Gemm g, const StaticOrder& S, const Epi& E, int wave_k) {
;     ...
;             PG8_LDB(B0, 0, 0); PG8_LDB(B1, 0, 1); PG8_SCHED; PG8_LDA(At, 0, 0); PG8_STAGE(PG8_SA(1, 1), a1 + hstepA, voffA);
;             PG8_WAIT_V(8); PG8_WAIT_L(0); PG8_BAR; PG8_MMA(0, 0, At, B0); PG8_MMA(0, 1, At, B1); PG8_BAR; PG8_SCHED;
;             PG8_LDA(At, 0, 1); PG8_STAGE(PG8_SB(0, 0), b2, voffB); PG8_STAGE(PG8_SB(0, 1), b2 + hstepB, voffB); PG8_STAGE(PG8_SA(0, 0), a2, voffA);
;             PG8_WAIT_V(8); PG8_WAIT_L(0); PG8_BAR; PG8_MMA(1, 0, At, B0); PG8_MMA(1, 1, At, B1); PG8_BAR; PG8_SCHED;
.LBB0_886:
	s_add_u32 s16, s46, 0xfffe0080
	s_addc_u32 s17, s47, -1
	s_add_i32 s65, 0, 0x10000
	s_cmp_eq_u32 s64, 4
	s_cselect_b32 s25, s26, s17
	s_cselect_b32 s24, s27, s16
	s_cselect_b32 s17, s21, s63
	s_cselect_b32 s16, s35, s62
	s_add_i32 s68, 0, 0x14000
	v_add_u32_e32 v154, s65, v143
	v_add_u32_e32 v158, s68, v143
	ds_read_b128 v[138:141], v154
	ds_read_b128 v[146:149], v154 offset:1024
	ds_read_b128 v[150:153], v154 offset:2048
	ds_read_b128 v[154:157], v154 offset:3072
	ds_read_b128 v[162:165], v158
	ds_read_b128 v[166:169], v158 offset:1024
	ds_read_b128 v[170:173], v158 offset:2048
	ds_read_b128 v[174:177], v158 offset:3072
	s_add_i32 m0, s45, 0xc000
	ds_read_b128 v[178:181], v145
	ds_read_b128 v[182:185], v145 offset:1024
	ds_read_b128 v[186:189], v145 offset:2048
	ds_read_b128 v[190:193], v145 offset:3072
	ds_read_b128 v[194:197], v145 offset:4096
	ds_read_b128 v[198:201], v145 offset:5120
	ds_read_b128 v[202:205], v145 offset:6144
	ds_read_b128 v[206:209], v145 offset:7168
	global_load_lds_dwordx4 v134, s[46:47]
	s_add_i32 m0, s45, 0xe000
	s_nop 0
	global_load_lds_dwordx4 v136, s[46:47]
	s_waitcnt vmcnt(8) lgkmcnt(0)
	s_barrier
	v_mfma_f32_16x16x32_bf16 v[124:127], v[138:141], v[178:181], v[124:127]
	v_mfma_f32_16x16x32_bf16 v[120:123], v[150:153], v[178:181], v[120:123]
	v_mfma_f32_16x16x32_bf16 v[108:111], v[138:141], v[186:189], v[108:111]
	v_mfma_f32_16x16x32_bf16 v[104:107], v[150:153], v[186:189], v[104:107]
	v_mfma_f32_16x16x32_bf16 v[92:95], v[138:141], v[194:197], v[92:95]
	v_mfma_f32_16x16x32_bf16 v[88:91], v[150:153], v[194:197], v[88:91]
	v_mfma_f32_16x16x32_bf16 v[76:79], v[138:141], v[202:205], v[76:79]
	v_mfma_f32_16x16x32_bf16 v[72:75], v[150:153], v[202:205], v[72:75]
	v_mfma_f32_16x16x32_bf16 v[124:127], v[146:149], v[182:185], v[124:127]
	v_mfma_f32_16x16x32_bf16 v[120:123], v[154:157], v[182:185], v[120:123]
	v_mfma_f32_16x16x32_bf16 v[108:111], v[146:149], v[190:193], v[108:111]
	v_mfma_f32_16x16x32_bf16 v[104:107], v[154:157], v[190:193], v[104:107]
	v_mfma_f32_16x16x32_bf16 v[92:95], v[146:149], v[198:201], v[92:95]
	v_mfma_f32_16x16x32_bf16 v[88:91], v[154:157], v[198:201], v[88:91]
	v_mfma_f32_16x16x32_bf16 v[76:79], v[146:149], v[206:209], v[76:79]
	v_mfma_f32_16x16x32_bf16 v[72:75], v[154:157], v[206:209], v[72:75]
	v_mfma_f32_16x16x32_bf16 v[116:119], v[162:165], v[178:181], v[116:119]
	v_mfma_f32_16x16x32_bf16 v[112:115], v[170:173], v[178:181], v[112:115]
	v_mfma_f32_16x16x32_bf16 v[100:103], v[162:165], v[186:189], v[100:103]
	v_mfma_f32_16x16x32_bf16 v[96:99], v[170:173], v[186:189], v[96:99]
	v_mfma_f32_16x16x32_bf16 v[84:87], v[162:165], v[194:197], v[84:87]
	v_mfma_f32_16x16x32_bf16 v[80:83], v[170:173], v[194:197], v[80:83]
	v_mfma_f32_16x16x32_bf16 v[68:71], v[162:165], v[202:205], v[68:71]
	v_mfma_f32_16x16x32_bf16 v[64:67], v[170:173], v[202:205], v[64:67]
	v_mfma_f32_16x16x32_bf16 v[116:119], v[166:169], v[182:185], v[116:119]
	v_mfma_f32_16x16x32_bf16 v[112:115], v[174:177], v[182:185], v[112:115]
	v_mfma_f32_16x16x32_bf16 v[100:103], v[166:169], v[190:193], v[100:103]
	v_mfma_f32_16x16x32_bf16 v[96:99], v[174:177], v[190:193], v[96:99]
	v_mfma_f32_16x16x32_bf16 v[84:87], v[166:169], v[198:201], v[84:87]
	v_mfma_f32_16x16x32_bf16 v[80:83], v[174:177], v[198:201], v[80:83]
	v_mfma_f32_16x16x32_bf16 v[68:71], v[166:169], v[206:209], v[68:71]
	v_mfma_f32_16x16x32_bf16 v[64:67], v[174:177], v[206:209], v[64:67]
	s_barrier
	s_add_i32 s65, s65, s53
	v_lshl_add_u64 v[158:159], s[16:17], 0, v[160:161]
	s_mov_b32 m0, s65
	ds_read_b128 v[178:181], v145 offset:16384
	ds_read_b128 v[182:185], v145 offset:17408
	ds_read_b128 v[186:189], v145 offset:18432
	ds_read_b128 v[190:193], v145 offset:19456
	ds_read_b128 v[194:197], v145 offset:20480
	ds_read_b128 v[198:201], v145 offset:21504
	ds_read_b128 v[202:205], v145 offset:22528
	ds_read_b128 v[206:209], v145 offset:23552
	global_load_lds_dwordx4 v[158:159], off
	s_add_i32 m0, s65, 0x2000
	s_add_u32 s66, s16, 0x20000
	v_lshl_add_u64 v[210:211], s[16:17], 0, v[132:133]
	s_addc_u32 s67, s17, 0
	s_add_i32 s65, s68, s53
	global_load_lds_dwordx4 v[210:211], off
	s_mov_b32 m0, s65
	v_lshl_add_u64 v[218:219], s[24:25], 0, v[130:131]
	global_load_lds_dwordx4 v160, s[66:67]
	s_add_i32 m0, s65, 0x2000
	s_nop 0
	global_load_lds_dwordx4 v132, s[66:67]
	v_lshl_add_u64 v[212:213], s[24:25], 0, v[128:129]
	s_mov_b32 m0, s45
	s_nop 0
	global_load_lds_dwordx4 v[212:213], off
	s_mov_b32 m0, s54
	s_nop 0
	global_load_lds_dwordx4 v[218:219], off
	s_waitcnt vmcnt(8) lgkmcnt(0)
	s_barrier
	v_mfma_f32_16x16x32_bf16 v[60:63], v[138:141], v[178:181], v[60:63]
	v_mfma_f32_16x16x32_bf16 v[56:59], v[150:153], v[178:181], v[56:59]
	v_mfma_f32_16x16x32_bf16 v[44:47], v[138:141], v[186:189], v[44:47]
	v_mfma_f32_16x16x32_bf16 v[40:43], v[150:153], v[186:189], v[40:43]
	v_mfma_f32_16x16x32_bf16 v[28:31], v[138:141], v[194:197], v[28:31]
	v_mfma_f32_16x16x32_bf16 v[24:27], v[150:153], v[194:197], v[24:27]
	v_mfma_f32_16x16x32_bf16 v[12:15], v[138:141], v[202:205], v[12:15]
	v_mfma_f32_16x16x32_bf16 v[8:11], v[150:153], v[202:205], v[8:11]
	v_mfma_f32_16x16x32_bf16 v[60:63], v[146:149], v[182:185], v[60:63]
	v_mfma_f32_16x16x32_bf16 v[56:59], v[154:157], v[182:185], v[56:59]
	v_mfma_f32_16x16x32_bf16 v[44:47], v[146:149], v[190:193], v[44:47]
	v_mfma_f32_16x16x32_bf16 v[40:43], v[154:157], v[190:193], v[40:43]
	v_mfma_f32_16x16x32_bf16 v[28:31], v[146:149], v[198:201], v[28:31]
	v_mfma_f32_16x16x32_bf16 v[24:27], v[154:157], v[198:201], v[24:27]
	v_mfma_f32_16x16x32_bf16 v[12:15], v[146:149], v[206:209], v[12:15]
	v_mfma_f32_16x16x32_bf16 v[8:11], v[154:157], v[206:209], v[8:11]
	v_mfma_f32_16x16x32_bf16 v[52:55], v[162:165], v[178:181], v[52:55]
	v_mfma_f32_16x16x32_bf16 v[48:51], v[170:173], v[178:181], v[48:51]
	v_mfma_f32_16x16x32_bf16 v[36:39], v[162:165], v[186:189], v[36:39]
	v_mfma_f32_16x16x32_bf16 v[32:35], v[170:173], v[186:189], v[32:35]
	v_mfma_f32_16x16x32_bf16 v[20:23], v[162:165], v[194:197], v[20:23]
	v_mfma_f32_16x16x32_bf16 v[16:19], v[170:173], v[194:197], v[16:19]
	v_mfma_f32_16x16x32_bf16 v[4:7], v[162:165], v[202:205], v[4:7]
	v_mfma_f32_16x16x32_bf16 v[0:3], v[170:173], v[202:205], v[0:3]
	v_mfma_f32_16x16x32_bf16 v[52:55], v[166:169], v[182:185], v[52:55]
	v_mfma_f32_16x16x32_bf16 v[48:51], v[174:177], v[182:185], v[48:51]
	v_mfma_f32_16x16x32_bf16 v[36:39], v[166:169], v[190:193], v[36:39]
	v_mfma_f32_16x16x32_bf16 v[32:35], v[174:177], v[190:193], v[32:35]
	v_mfma_f32_16x16x32_bf16 v[20:23], v[166:169], v[198:201], v[20:23]
	v_mfma_f32_16x16x32_bf16 v[16:19], v[174:177], v[198:201], v[16:19]
	v_mfma_f32_16x16x32_bf16 v[4:7], v[166:169], v[206:209], v[4:7]
	v_mfma_f32_16x16x32_bf16 v[0:3], v[174:177], v[206:209], v[0:3]
	s_barrier
; #define PG8_STAGE(bufoff, gbase, voff) do { _Pragma("unroll") for (int _i = 0; _i < 2; ++_i) \
;         __builtin_amdgcn_global_load_lds((const unsigned*)((const char*)(gbase) + (voff)[_i]), (LAS unsigned*)(lds + (bufoff) + ldsw + _i * 8192), 16, 0, 0); } while (0)
; #define PG8_LDA(dst, b, h) do { _Pragma("unroll") for (int m = 0; m < 4; ++m) _Pragma("unroll") for (int k = 0; k < 2; ++k) dst[m][k] = *(const LAS bf16x8*)(lds + PG8_SA(b, h) + aoff + m * 2048 + k * 1024); } while (0)
; #define PG8_LDB(dst, b, h) do { _Pragma("unroll") for (int n = 0; n < 2; ++n) _Pragma("unroll") for (int k = 0; k < 2; ++k) dst[n][k] = *(const LAS bf16x8*)(lds + PG8_SB(b, h) + boff + n * 2048 + k * 1024); } while (0)
; #define PG8_MMA(ai, bj, At, Bt) do { __builtin_amdgcn_s_setprio(1); _Pragma("unroll") for (int m = 0; m < 4; ++m) _Pragma("unroll") for (int n = 0; n < 2; ++n) _Pragma("unroll") for (int k = 0; k < 2; ++k) \
;         acc[ai][bj][m][n] = __builtin_amdgcn_mfma_f32_16x16x32_bf16(Bt[n][k], At[m][k], acc[ai][bj][m][n], 0, 0, 0); __builtin_amdgcn_s_setprio(0); } while (0)
; #define PG8_WAIT_V(n) asm volatile("s_waitcnt vmcnt(" #n ")" ::: "memory")
; #define PG8_WAIT_L(n) asm volatile("s_waitcnt lgkmcnt(" #n ")" ::: "memory")
; #define PG8_BAR __builtin_amdgcn_s_barrier()
; #define PG8_SCHED __builtin_amdgcn_sched_barrier(0)
; template <class Epi, bool ALIGN_EPI = true>
; __device__ __forceinline__ void gemm_phase(LAS unsigned char* lds, const Gemm g, const StaticOrder& S, const Epi& E, int wave_k) {
;     ...
;             PG8_LDB(B0, 1, 0); PG8_LDB(B1, 1, 1); PG8_SCHED; PG8_LDA(At, 1, 0); PG8_STAGE(PG8_SA(0, 1), a2 + hstepA, voffA);
;             PG8_WAIT_V(8); PG8_WAIT_L(0); PG8_BAR; PG8_MMA(0, 0, At, B0); PG8_MMA(0, 1, At, B1); PG8_BAR; PG8_SCHED;
;             PG8_LDA(At, 1, 1); PG8_STAGE(PG8_SB(1, 0), b3, voffB); PG8_STAGE(PG8_SB(1, 1), b3 + hstepB, voffB); PG8_STAGE(PG8_SA(1, 0), a3, voffA);
;             PG8_WAIT_V(8); PG8_WAIT_L(0); PG8_BAR; PG8_MMA(1, 0, At, B0); PG8_MMA(1, 1, At, B1); PG8_BAR; PG8_SCHED;
;         }
	s_add_i32 s65, 0, 0x18000
	s_add_i32 s66, 0, 0x1c000
	v_add_u32_e32 v154, s65, v143
	v_add_u32_e32 v174, s66, v143
	ds_read_b128 v[138:141], v154
	ds_read_b128 v[146:149], v154 offset:1024
	ds_read_b128 v[150:153], v154 offset:2048
	ds_read_b128 v[154:157], v154 offset:3072
	ds_read_b128 v[162:165], v174
	ds_read_b128 v[166:169], v174 offset:1024
	ds_read_b128 v[170:173], v174 offset:2048
	ds_read_b128 v[174:177], v174 offset:3072
	s_add_u32 s24, s24, 0x20000
	s_addc_u32 s25, s25, 0
	s_mov_b32 m0, s55
	ds_read_b128 v[178:181], v145 offset:32768
	ds_read_b128 v[182:185], v145 offset:33792
	ds_read_b128 v[186:189], v145 offset:34816
	ds_read_b128 v[190:193], v145 offset:35840
	ds_read_b128 v[194:197], v145 offset:36864
	ds_read_b128 v[198:201], v145 offset:37888
	ds_read_b128 v[202:205], v145 offset:38912
	ds_read_b128 v[206:209], v145 offset:39936
	global_load_lds_dwordx4 v128, s[24:25]
	s_mov_b32 m0, s56
	s_nop 0
	global_load_lds_dwordx4 v130, s[24:25]
	s_waitcnt vmcnt(8) lgkmcnt(0)
	s_barrier
	v_mfma_f32_16x16x32_bf16 v[124:127], v[138:141], v[178:181], v[124:127]
	v_mfma_f32_16x16x32_bf16 v[120:123], v[150:153], v[178:181], v[120:123]
	v_mfma_f32_16x16x32_bf16 v[108:111], v[138:141], v[186:189], v[108:111]
	v_mfma_f32_16x16x32_bf16 v[104:107], v[150:153], v[186:189], v[104:107]
	v_mfma_f32_16x16x32_bf16 v[92:95], v[138:141], v[194:197], v[92:95]
	v_mfma_f32_16x16x32_bf16 v[88:91], v[150:153], v[194:197], v[88:91]
	v_mfma_f32_16x16x32_bf16 v[76:79], v[138:141], v[202:205], v[76:79]
	v_mfma_f32_16x16x32_bf16 v[72:75], v[150:153], v[202:205], v[72:75]
	v_mfma_f32_16x16x32_bf16 v[124:127], v[146:149], v[182:185], v[124:127]
	v_mfma_f32_16x16x32_bf16 v[120:123], v[154:157], v[182:185], v[120:123]
	v_mfma_f32_16x16x32_bf16 v[108:111], v[146:149], v[190:193], v[108:111]
	v_mfma_f32_16x16x32_bf16 v[104:107], v[154:157], v[190:193], v[104:107]
	v_mfma_f32_16x16x32_bf16 v[92:95], v[146:149], v[198:201], v[92:95]
	v_mfma_f32_16x16x32_bf16 v[88:91], v[154:157], v[198:201], v[88:91]
	v_mfma_f32_16x16x32_bf16 v[76:79], v[146:149], v[206:209], v[76:79]
	v_mfma_f32_16x16x32_bf16 v[72:75], v[154:157], v[206:209], v[72:75]
	v_mfma_f32_16x16x32_bf16 v[116:119], v[162:165], v[178:181], v[116:119]
	v_mfma_f32_16x16x32_bf16 v[112:115], v[170:173], v[178:181], v[112:115]
	v_mfma_f32_16x16x32_bf16 v[100:103], v[162:165], v[186:189], v[100:103]
	v_mfma_f32_16x16x32_bf16 v[96:99], v[170:173], v[186:189], v[96:99]
	v_mfma_f32_16x16x32_bf16 v[84:87], v[162:165], v[194:197], v[84:87]
	v_mfma_f32_16x16x32_bf16 v[80:83], v[170:173], v[194:197], v[80:83]
	v_mfma_f32_16x16x32_bf16 v[68:71], v[162:165], v[202:205], v[68:71]
	v_mfma_f32_16x16x32_bf16 v[64:67], v[170:173], v[202:205], v[64:67]
	v_mfma_f32_16x16x32_bf16 v[116:119], v[166:169], v[182:185], v[116:119]
	v_mfma_f32_16x16x32_bf16 v[112:115], v[174:177], v[182:185], v[112:115]
	v_mfma_f32_16x16x32_bf16 v[100:103], v[166:169], v[190:193], v[100:103]
	v_mfma_f32_16x16x32_bf16 v[96:99], v[174:177], v[190:193], v[96:99]
	v_mfma_f32_16x16x32_bf16 v[84:87], v[166:169], v[198:201], v[84:87]
	v_mfma_f32_16x16x32_bf16 v[80:83], v[174:177], v[198:201], v[80:83]
	v_mfma_f32_16x16x32_bf16 v[68:71], v[166:169], v[206:209], v[68:71]
	v_mfma_f32_16x16x32_bf16 v[64:67], v[174:177], v[206:209], v[64:67]
	s_barrier
	s_add_i32 s24, s65, s53
	v_lshl_add_u64 v[158:159], v[158:159], 0, s[22:23]
	s_mov_b32 m0, s24
	ds_read_b128 v[178:181], v145 offset:49152
	ds_read_b128 v[182:185], v145 offset:50176
	ds_read_b128 v[186:189], v145 offset:51200
	ds_read_b128 v[190:193], v145 offset:52224
	ds_read_b128 v[194:197], v145 offset:53248
	ds_read_b128 v[198:201], v145 offset:54272
	ds_read_b128 v[202:205], v145 offset:55296
	ds_read_b128 v[206:209], v145 offset:56320
	global_load_lds_dwordx4 v[158:159], off
	s_add_i32 m0, s24, 0x2000
	s_add_u32 s16, s16, 0x20080
	v_lshl_add_u64 v[158:159], v[210:211], 0, s[22:23]
	s_addc_u32 s17, s17, 0
	s_add_i32 s24, s66, s53
	global_load_lds_dwordx4 v[158:159], off
	s_mov_b32 m0, s24
	s_nop 0
	global_load_lds_dwordx4 v160, s[16:17]
	s_add_i32 m0, s24, 0x2000
	s_nop 0
	global_load_lds_dwordx4 v132, s[16:17]
	v_lshl_add_u64 v[158:159], v[212:213], 0, s[22:23]
	s_mov_b32 m0, s57
	s_nop 0
	global_load_lds_dwordx4 v[158:159], off
	v_lshl_add_u64 v[158:159], v[218:219], 0, s[22:23]
	s_mov_b32 m0, s58
	s_nop 0
	global_load_lds_dwordx4 v[158:159], off
	s_waitcnt vmcnt(8) lgkmcnt(0)
	s_barrier
	v_mfma_f32_16x16x32_bf16 v[60:63], v[138:141], v[178:181], v[60:63]
	v_mfma_f32_16x16x32_bf16 v[56:59], v[150:153], v[178:181], v[56:59]
	v_mfma_f32_16x16x32_bf16 v[44:47], v[138:141], v[186:189], v[44:47]
	v_mfma_f32_16x16x32_bf16 v[40:43], v[150:153], v[186:189], v[40:43]
	v_mfma_f32_16x16x32_bf16 v[28:31], v[138:141], v[194:197], v[28:31]
	v_mfma_f32_16x16x32_bf16 v[24:27], v[150:153], v[194:197], v[24:27]
	v_mfma_f32_16x16x32_bf16 v[12:15], v[138:141], v[202:205], v[12:15]
	v_mfma_f32_16x16x32_bf16 v[8:11], v[150:153], v[202:205], v[8:11]
	v_mfma_f32_16x16x32_bf16 v[60:63], v[146:149], v[182:185], v[60:63]
	v_mfma_f32_16x16x32_bf16 v[56:59], v[154:157], v[182:185], v[56:59]
	v_mfma_f32_16x16x32_bf16 v[44:47], v[146:149], v[190:193], v[44:47]
	v_mfma_f32_16x16x32_bf16 v[40:43], v[154:157], v[190:193], v[40:43]
	v_mfma_f32_16x16x32_bf16 v[28:31], v[146:149], v[198:201], v[28:31]
	v_mfma_f32_16x16x32_bf16 v[24:27], v[154:157], v[198:201], v[24:27]
	v_mfma_f32_16x16x32_bf16 v[12:15], v[146:149], v[206:209], v[12:15]
	v_mfma_f32_16x16x32_bf16 v[8:11], v[154:157], v[206:209], v[8:11]
	v_mfma_f32_16x16x32_bf16 v[52:55], v[162:165], v[178:181], v[52:55]
	v_mfma_f32_16x16x32_bf16 v[48:51], v[170:173], v[178:181], v[48:51]
	v_mfma_f32_16x16x32_bf16 v[36:39], v[162:165], v[186:189], v[36:39]
	v_mfma_f32_16x16x32_bf16 v[32:35], v[170:173], v[186:189], v[32:35]
	v_mfma_f32_16x16x32_bf16 v[20:23], v[162:165], v[194:197], v[20:23]
	v_mfma_f32_16x16x32_bf16 v[16:19], v[170:173], v[194:197], v[16:19]
	v_mfma_f32_16x16x32_bf16 v[4:7], v[162:165], v[202:205], v[4:7]
	v_mfma_f32_16x16x32_bf16 v[0:3], v[170:173], v[202:205], v[0:3]
	v_mfma_f32_16x16x32_bf16 v[52:55], v[166:169], v[182:185], v[52:55]
	v_mfma_f32_16x16x32_bf16 v[48:51], v[174:177], v[182:185], v[48:51]
	v_mfma_f32_16x16x32_bf16 v[36:39], v[166:169], v[190:193], v[36:39]
	v_mfma_f32_16x16x32_bf16 v[32:35], v[174:177], v[190:193], v[32:35]
	v_mfma_f32_16x16x32_bf16 v[20:23], v[166:169], v[198:201], v[20:23]
	v_mfma_f32_16x16x32_bf16 v[16:19], v[174:177], v[198:201], v[16:19]
	v_mfma_f32_16x16x32_bf16 v[4:7], v[166:169], v[206:209], v[4:7]
	v_mfma_f32_16x16x32_bf16 v[0:3], v[174:177], v[206:209], v[0:3]
	s_barrier
	s_add_i32 s64, s64, 2
	s_add_u32 s46, s46, 0x100
	s_addc_u32 s47, s47, 0
	s_add_u32 s62, s62, 0x100
	s_addc_u32 s63, s63, 0
	s_cmp_gt_u32 s64, 5
	s_cbranch_scc0 .LBB0_886
	s_and_b64 vcc, exec, s[18:19]
	s_cbranch_vccz .LBB0_889
	s_barrier

; #define PG8_STAGE(bufoff, gbase, voff) do { _Pragma("unroll") for (int _i = 0; _i < 2; ++_i) \
;         __builtin_amdgcn_global_load_lds((const unsigned*)((const char*)(gbase) + (voff)[_i]), (LAS unsigned*)(lds + (bufoff) + ldsw + _i * 8192), 16, 0, 0); } while (0)
; #define PG8_LDA(dst, b, h) do { _Pragma("unroll") for (int m = 0; m < 4; ++m) _Pragma("unroll") for (int k = 0; k < 2; ++k) dst[m][k] = *(const LAS bf16x8*)(lds + PG8_SA(b, h) + aoff + m * 2048 + k * 1024); } while (0)
; #define PG8_LDB(dst, b, h) do { _Pragma("unroll") for (int n = 0; n < 2; ++n) _Pragma("unroll") for (int k = 0; k < 2; ++k) dst[n][k] = *(const LAS bf16x8*)(lds + PG8_SB(b, h) + boff + n * 2048 + k * 1024); } while (0)
; #define PG8_MMA(ai, bj, At, Bt) do { __builtin_amdgcn_s_setprio(1); _Pragma("unroll") for (int m = 0; m < 4; ++m) _Pragma("unroll") for (int n = 0; n < 2; ++n) _Pragma("unroll") for (int k = 0; k < 2; ++k) \
;         acc[ai][bj][m][n] = __builtin_amdgcn_mfma_f32_16x16x32_bf16(Bt[n][k], At[m][k], acc[ai][bj][m][n], 0, 0, 0); __builtin_amdgcn_s_setprio(0); } while (0)
; #define PG8_WAIT_V(n) asm volatile("s_waitcnt vmcnt(" #n ")" ::: "memory")
; #define PG8_WAIT_L(n) asm volatile("s_waitcnt lgkmcnt(" #n ")" ::: "memory")
; #define PG8_BAR __builtin_amdgcn_s_barrier()
; #define PG8_SCHED __builtin_amdgcn_sched_barrier(0)
; template <class Epi, bool ALIGN_EPI = true>
; __device__ __forceinline__ void gemm_phase(LAS unsigned char* lds, const Gemm g, const StaticOrder& S, const Epi& E, int wave_k) {
;     ...
;             PG8_LDB(B0, 0, 0); PG8_LDB(B1, 0, 1); PG8_SCHED; PG8_LDA(At, 0, 0); PG8_STAGE(PG8_SA(1, 1), a1 + hstepA, voffA);
;             PG8_WAIT_V(8); PG8_WAIT_L(0); PG8_BAR; PG8_MMA(0, 0, At, B0); PG8_MMA(0, 1, At, B1); PG8_BAR; PG8_SCHED;
;             PG8_LDA(At, 0, 1); PG8_STAGE(PG8_SB(0, 0), b2, voffB); PG8_STAGE(PG8_SB(0, 1), b2 + hstepB, voffB); PG8_STAGE(PG8_SA(0, 0), a2, voffA);
;             PG8_WAIT_V(8); PG8_WAIT_L(0); PG8_BAR; PG8_MMA(1, 0, At, B0); PG8_MMA(1, 1, At, B1); PG8_BAR; PG8_SCHED;
.LBB0_1057:
	s_add_u32 s16, s50, 0xfffc0080
	s_addc_u32 s17, s51, -1
	s_add_i32 s71, 0, 0x10000
	s_cmp_eq_u32 s70, 12
	s_cselect_b32 s25, s26, s17
	s_cselect_b32 s24, s27, s16
	s_cselect_b32 s17, s1, s67
	s_cselect_b32 s16, s35, s66
	s_add_i32 s74, 0, 0x14000
	v_add_u32_e32 v154, s71, v143
	v_add_u32_e32 v158, s74, v143
	ds_read_b128 v[138:141], v154
	ds_read_b128 v[146:149], v154 offset:1024
	ds_read_b128 v[150:153], v154 offset:2048
	ds_read_b128 v[154:157], v154 offset:3072
	ds_read_b128 v[162:165], v158
	ds_read_b128 v[166:169], v158 offset:1024
	ds_read_b128 v[170:173], v158 offset:2048
	ds_read_b128 v[174:177], v158 offset:3072
	s_add_i32 m0, s47, 0xc000
	ds_read_b128 v[178:181], v145
	ds_read_b128 v[182:185], v145 offset:1024
	ds_read_b128 v[186:189], v145 offset:2048
	ds_read_b128 v[190:193], v145 offset:3072
	ds_read_b128 v[194:197], v145 offset:4096
	ds_read_b128 v[198:201], v145 offset:5120
	ds_read_b128 v[202:205], v145 offset:6144
	ds_read_b128 v[206:209], v145 offset:7168
	global_load_lds_dwordx4 v134, s[50:51]
	s_add_i32 m0, s47, 0xe000
	s_nop 0
	global_load_lds_dwordx4 v136, s[50:51]
	s_waitcnt vmcnt(8) lgkmcnt(0)
	s_barrier
	v_mfma_f32_16x16x32_bf16 v[124:127], v[138:141], v[178:181], v[124:127]
	v_mfma_f32_16x16x32_bf16 v[120:123], v[150:153], v[178:181], v[120:123]
	v_mfma_f32_16x16x32_bf16 v[108:111], v[138:141], v[186:189], v[108:111]
	v_mfma_f32_16x16x32_bf16 v[104:107], v[150:153], v[186:189], v[104:107]
	v_mfma_f32_16x16x32_bf16 v[92:95], v[138:141], v[194:197], v[92:95]
	v_mfma_f32_16x16x32_bf16 v[88:91], v[150:153], v[194:197], v[88:91]
	v_mfma_f32_16x16x32_bf16 v[76:79], v[138:141], v[202:205], v[76:79]
	v_mfma_f32_16x16x32_bf16 v[72:75], v[150:153], v[202:205], v[72:75]
	v_mfma_f32_16x16x32_bf16 v[124:127], v[146:149], v[182:185], v[124:127]
	v_mfma_f32_16x16x32_bf16 v[120:123], v[154:157], v[182:185], v[120:123]
	v_mfma_f32_16x16x32_bf16 v[108:111], v[146:149], v[190:193], v[108:111]
	v_mfma_f32_16x16x32_bf16 v[104:107], v[154:157], v[190:193], v[104:107]
	v_mfma_f32_16x16x32_bf16 v[92:95], v[146:149], v[198:201], v[92:95]
	v_mfma_f32_16x16x32_bf16 v[88:91], v[154:157], v[198:201], v[88:91]
	v_mfma_f32_16x16x32_bf16 v[76:79], v[146:149], v[206:209], v[76:79]
	v_mfma_f32_16x16x32_bf16 v[72:75], v[154:157], v[206:209], v[72:75]
	v_mfma_f32_16x16x32_bf16 v[116:119], v[162:165], v[178:181], v[116:119]
	v_mfma_f32_16x16x32_bf16 v[112:115], v[170:173], v[178:181], v[112:115]
	v_mfma_f32_16x16x32_bf16 v[100:103], v[162:165], v[186:189], v[100:103]
	v_mfma_f32_16x16x32_bf16 v[96:99], v[170:173], v[186:189], v[96:99]
	v_mfma_f32_16x16x32_bf16 v[84:87], v[162:165], v[194:197], v[84:87]
	v_mfma_f32_16x16x32_bf16 v[80:83], v[170:173], v[194:197], v[80:83]
	v_mfma_f32_16x16x32_bf16 v[68:71], v[162:165], v[202:205], v[68:71]
	v_mfma_f32_16x16x32_bf16 v[64:67], v[170:173], v[202:205], v[64:67]
	v_mfma_f32_16x16x32_bf16 v[116:119], v[166:169], v[182:185], v[116:119]
	v_mfma_f32_16x16x32_bf16 v[112:115], v[174:177], v[182:185], v[112:115]
	v_mfma_f32_16x16x32_bf16 v[100:103], v[166:169], v[190:193], v[100:103]
	v_mfma_f32_16x16x32_bf16 v[96:99], v[174:177], v[190:193], v[96:99]
	v_mfma_f32_16x16x32_bf16 v[84:87], v[166:169], v[198:201], v[84:87]
	v_mfma_f32_16x16x32_bf16 v[80:83], v[174:177], v[198:201], v[80:83]
	v_mfma_f32_16x16x32_bf16 v[68:71], v[166:169], v[206:209], v[68:71]
	v_mfma_f32_16x16x32_bf16 v[64:67], v[174:177], v[206:209], v[64:67]
	s_barrier
	s_add_i32 s71, s71, s58
	v_lshl_add_u64 v[158:159], s[16:17], 0, v[160:161]
	s_mov_b32 m0, s71
	ds_read_b128 v[178:181], v145 offset:16384
	ds_read_b128 v[182:185], v145 offset:17408
	ds_read_b128 v[186:189], v145 offset:18432
	ds_read_b128 v[190:193], v145 offset:19456
	ds_read_b128 v[194:197], v145 offset:20480
	ds_read_b128 v[198:201], v145 offset:21504
	ds_read_b128 v[202:205], v145 offset:22528
	ds_read_b128 v[206:209], v145 offset:23552
	global_load_lds_dwordx4 v[158:159], off
	s_add_i32 m0, s71, 0x2000
	s_add_u32 s72, s16, 0x40000
	v_lshl_add_u64 v[210:211], s[16:17], 0, v[132:133]
	s_addc_u32 s73, s17, 0
	s_add_i32 s71, s74, s58
	global_load_lds_dwordx4 v[210:211], off
	s_mov_b32 m0, s71
	v_lshl_add_u64 v[218:219], s[24:25], 0, v[130:131]
	global_load_lds_dwordx4 v160, s[72:73]
	s_add_i32 m0, s71, 0x2000
	s_nop 0
	global_load_lds_dwordx4 v132, s[72:73]
	v_lshl_add_u64 v[212:213], s[24:25], 0, v[128:129]
	s_mov_b32 m0, s47
	s_nop 0
	global_load_lds_dwordx4 v[212:213], off
	s_mov_b32 m0, s53
	s_nop 0
	global_load_lds_dwordx4 v[218:219], off
	s_waitcnt vmcnt(8) lgkmcnt(0)
	s_barrier
	v_mfma_f32_16x16x32_bf16 v[60:63], v[138:141], v[178:181], v[60:63]
	v_mfma_f32_16x16x32_bf16 v[56:59], v[150:153], v[178:181], v[56:59]
	v_mfma_f32_16x16x32_bf16 v[44:47], v[138:141], v[186:189], v[44:47]
	v_mfma_f32_16x16x32_bf16 v[40:43], v[150:153], v[186:189], v[40:43]
	v_mfma_f32_16x16x32_bf16 v[28:31], v[138:141], v[194:197], v[28:31]
	v_mfma_f32_16x16x32_bf16 v[24:27], v[150:153], v[194:197], v[24:27]
	v_mfma_f32_16x16x32_bf16 v[12:15], v[138:141], v[202:205], v[12:15]
	v_mfma_f32_16x16x32_bf16 v[8:11], v[150:153], v[202:205], v[8:11]
	v_mfma_f32_16x16x32_bf16 v[60:63], v[146:149], v[182:185], v[60:63]
	v_mfma_f32_16x16x32_bf16 v[56:59], v[154:157], v[182:185], v[56:59]
	v_mfma_f32_16x16x32_bf16 v[44:47], v[146:149], v[190:193], v[44:47]
	v_mfma_f32_16x16x32_bf16 v[40:43], v[154:157], v[190:193], v[40:43]
	v_mfma_f32_16x16x32_bf16 v[28:31], v[146:149], v[198:201], v[28:31]
	v_mfma_f32_16x16x32_bf16 v[24:27], v[154:157], v[198:201], v[24:27]
	v_mfma_f32_16x16x32_bf16 v[12:15], v[146:149], v[206:209], v[12:15]
	v_mfma_f32_16x16x32_bf16 v[8:11], v[154:157], v[206:209], v[8:11]
	v_mfma_f32_16x16x32_bf16 v[52:55], v[162:165], v[178:181], v[52:55]
	v_mfma_f32_16x16x32_bf16 v[48:51], v[170:173], v[178:181], v[48:51]
	v_mfma_f32_16x16x32_bf16 v[36:39], v[162:165], v[186:189], v[36:39]
	v_mfma_f32_16x16x32_bf16 v[32:35], v[170:173], v[186:189], v[32:35]
	v_mfma_f32_16x16x32_bf16 v[20:23], v[162:165], v[194:197], v[20:23]
	v_mfma_f32_16x16x32_bf16 v[16:19], v[170:173], v[194:197], v[16:19]
	v_mfma_f32_16x16x32_bf16 v[4:7], v[162:165], v[202:205], v[4:7]
	v_mfma_f32_16x16x32_bf16 v[0:3], v[170:173], v[202:205], v[0:3]
	v_mfma_f32_16x16x32_bf16 v[52:55], v[166:169], v[182:185], v[52:55]
	v_mfma_f32_16x16x32_bf16 v[48:51], v[174:177], v[182:185], v[48:51]
	v_mfma_f32_16x16x32_bf16 v[36:39], v[166:169], v[190:193], v[36:39]
	v_mfma_f32_16x16x32_bf16 v[32:35], v[174:177], v[190:193], v[32:35]
	v_mfma_f32_16x16x32_bf16 v[20:23], v[166:169], v[198:201], v[20:23]
	v_mfma_f32_16x16x32_bf16 v[16:19], v[174:177], v[198:201], v[16:19]
	v_mfma_f32_16x16x32_bf16 v[4:7], v[166:169], v[206:209], v[4:7]
	v_mfma_f32_16x16x32_bf16 v[0:3], v[174:177], v[206:209], v[0:3]
	s_barrier
; #define PG8_STAGE(bufoff, gbase, voff) do { _Pragma("unroll") for (int _i = 0; _i < 2; ++_i) \
;         __builtin_amdgcn_global_load_lds((const unsigned*)((const char*)(gbase) + (voff)[_i]), (LAS unsigned*)(lds + (bufoff) + ldsw + _i * 8192), 16, 0, 0); } while (0)
; #define PG8_LDA(dst, b, h) do { _Pragma("unroll") for (int m = 0; m < 4; ++m) _Pragma("unroll") for (int k = 0; k < 2; ++k) dst[m][k] = *(const LAS bf16x8*)(lds + PG8_SA(b, h) + aoff + m * 2048 + k * 1024); } while (0)
; #define PG8_LDB(dst, b, h) do { _Pragma("unroll") for (int n = 0; n < 2; ++n) _Pragma("unroll") for (int k = 0; k < 2; ++k) dst[n][k] = *(const LAS bf16x8*)(lds + PG8_SB(b, h) + boff + n * 2048 + k * 1024); } while (0)
; #define PG8_MMA(ai, bj, At, Bt) do { __builtin_amdgcn_s_setprio(1); _Pragma("unroll") for (int m = 0; m < 4; ++m) _Pragma("unroll") for (int n = 0; n < 2; ++n) _Pragma("unroll") for (int k = 0; k < 2; ++k) \
;         acc[ai][bj][m][n] = __builtin_amdgcn_mfma_f32_16x16x32_bf16(Bt[n][k], At[m][k], acc[ai][bj][m][n], 0, 0, 0); __builtin_amdgcn_s_setprio(0); } while (0)
; #define PG8_WAIT_V(n) asm volatile("s_waitcnt vmcnt(" #n ")" ::: "memory")
; #define PG8_WAIT_L(n) asm volatile("s_waitcnt lgkmcnt(" #n ")" ::: "memory")
; #define PG8_BAR __builtin_amdgcn_s_barrier()
; #define PG8_SCHED __builtin_amdgcn_sched_barrier(0)
; template <class Epi, bool ALIGN_EPI = true>
; __device__ __forceinline__ void gemm_phase(LAS unsigned char* lds, const Gemm g, const StaticOrder& S, const Epi& E, int wave_k) {
;     ...
;             PG8_LDB(B0, 1, 0); PG8_LDB(B1, 1, 1); PG8_SCHED; PG8_LDA(At, 1, 0); PG8_STAGE(PG8_SA(0, 1), a2 + hstepA, voffA);
;             PG8_WAIT_V(8); PG8_WAIT_L(0); PG8_BAR; PG8_MMA(0, 0, At, B0); PG8_MMA(0, 1, At, B1); PG8_BAR; PG8_SCHED;
;             PG8_LDA(At, 1, 1); PG8_STAGE(PG8_SB(1, 0), b3, voffB); PG8_STAGE(PG8_SB(1, 1), b3 + hstepB, voffB); PG8_STAGE(PG8_SA(1, 0), a3, voffA);
;             PG8_WAIT_V(8); PG8_WAIT_L(0); PG8_BAR; PG8_MMA(1, 0, At, B0); PG8_MMA(1, 1, At, B1); PG8_BAR; PG8_SCHED;
;         }
	s_add_i32 s71, 0, 0x18000
	s_add_i32 s72, 0, 0x1c000
	v_add_u32_e32 v154, s71, v143
	v_add_u32_e32 v174, s72, v143
	ds_read_b128 v[138:141], v154
	ds_read_b128 v[146:149], v154 offset:1024
	ds_read_b128 v[150:153], v154 offset:2048
	ds_read_b128 v[154:157], v154 offset:3072
	ds_read_b128 v[162:165], v174
	ds_read_b128 v[166:169], v174 offset:1024
	ds_read_b128 v[170:173], v174 offset:2048
	ds_read_b128 v[174:177], v174 offset:3072
	s_add_u32 s24, s24, 0x40000
	s_addc_u32 s25, s25, 0
	s_mov_b32 m0, s59
	ds_read_b128 v[178:181], v145 offset:32768
	ds_read_b128 v[182:185], v145 offset:33792
	ds_read_b128 v[186:189], v145 offset:34816
	ds_read_b128 v[190:193], v145 offset:35840
	ds_read_b128 v[194:197], v145 offset:36864
	ds_read_b128 v[198:201], v145 offset:37888
	ds_read_b128 v[202:205], v145 offset:38912
	ds_read_b128 v[206:209], v145 offset:39936
	global_load_lds_dwordx4 v128, s[24:25]
	s_mov_b32 m0, s60
	s_nop 0
	global_load_lds_dwordx4 v130, s[24:25]
	s_waitcnt vmcnt(8) lgkmcnt(0)
	s_barrier
	v_mfma_f32_16x16x32_bf16 v[124:127], v[138:141], v[178:181], v[124:127]
	v_mfma_f32_16x16x32_bf16 v[120:123], v[150:153], v[178:181], v[120:123]
	v_mfma_f32_16x16x32_bf16 v[108:111], v[138:141], v[186:189], v[108:111]
	v_mfma_f32_16x16x32_bf16 v[104:107], v[150:153], v[186:189], v[104:107]
	v_mfma_f32_16x16x32_bf16 v[92:95], v[138:141], v[194:197], v[92:95]
	v_mfma_f32_16x16x32_bf16 v[88:91], v[150:153], v[194:197], v[88:91]
	v_mfma_f32_16x16x32_bf16 v[76:79], v[138:141], v[202:205], v[76:79]
	v_mfma_f32_16x16x32_bf16 v[72:75], v[150:153], v[202:205], v[72:75]
	v_mfma_f32_16x16x32_bf16 v[124:127], v[146:149], v[182:185], v[124:127]
	v_mfma_f32_16x16x32_bf16 v[120:123], v[154:157], v[182:185], v[120:123]
	v_mfma_f32_16x16x32_bf16 v[108:111], v[146:149], v[190:193], v[108:111]
	v_mfma_f32_16x16x32_bf16 v[104:107], v[154:157], v[190:193], v[104:107]
	v_mfma_f32_16x16x32_bf16 v[92:95], v[146:149], v[198:201], v[92:95]
	v_mfma_f32_16x16x32_bf16 v[88:91], v[154:157], v[198:201], v[88:91]
	v_mfma_f32_16x16x32_bf16 v[76:79], v[146:149], v[206:209], v[76:79]
	v_mfma_f32_16x16x32_bf16 v[72:75], v[154:157], v[206:209], v[72:75]
	v_mfma_f32_16x16x32_bf16 v[116:119], v[162:165], v[178:181], v[116:119]
	v_mfma_f32_16x16x32_bf16 v[112:115], v[170:173], v[178:181], v[112:115]
	v_mfma_f32_16x16x32_bf16 v[100:103], v[162:165], v[186:189], v[100:103]
	v_mfma_f32_16x16x32_bf16 v[96:99], v[170:173], v[186:189], v[96:99]
	v_mfma_f32_16x16x32_bf16 v[84:87], v[162:165], v[194:197], v[84:87]
	v_mfma_f32_16x16x32_bf16 v[80:83], v[170:173], v[194:197], v[80:83]
	v_mfma_f32_16x16x32_bf16 v[68:71], v[162:165], v[202:205], v[68:71]
	v_mfma_f32_16x16x32_bf16 v[64:67], v[170:173], v[202:205], v[64:67]
	v_mfma_f32_16x16x32_bf16 v[116:119], v[166:169], v[182:185], v[116:119]
	v_mfma_f32_16x16x32_bf16 v[112:115], v[174:177], v[182:185], v[112:115]
	v_mfma_f32_16x16x32_bf16 v[100:103], v[166:169], v[190:193], v[100:103]
	v_mfma_f32_16x16x32_bf16 v[96:99], v[174:177], v[190:193], v[96:99]
	v_mfma_f32_16x16x32_bf16 v[84:87], v[166:169], v[198:201], v[84:87]
	v_mfma_f32_16x16x32_bf16 v[80:83], v[174:177], v[198:201], v[80:83]
	v_mfma_f32_16x16x32_bf16 v[68:71], v[166:169], v[206:209], v[68:71]
	v_mfma_f32_16x16x32_bf16 v[64:67], v[174:177], v[206:209], v[64:67]
	s_barrier
	s_add_i32 s24, s71, s58
	v_lshl_add_u64 v[158:159], v[158:159], 0, s[22:23]
	s_mov_b32 m0, s24
	ds_read_b128 v[178:181], v145 offset:49152
	ds_read_b128 v[182:185], v145 offset:50176
	ds_read_b128 v[186:189], v145 offset:51200
	ds_read_b128 v[190:193], v145 offset:52224
	ds_read_b128 v[194:197], v145 offset:53248
	ds_read_b128 v[198:201], v145 offset:54272
	ds_read_b128 v[202:205], v145 offset:55296
	ds_read_b128 v[206:209], v145 offset:56320
	global_load_lds_dwordx4 v[158:159], off
	s_add_i32 m0, s24, 0x2000
	s_add_u32 s16, s16, 0x40080
	v_lshl_add_u64 v[158:159], v[210:211], 0, s[22:23]
	s_addc_u32 s17, s17, 0
	s_add_i32 s24, s72, s58
	global_load_lds_dwordx4 v[158:159], off
	s_mov_b32 m0, s24
	s_nop 0
	global_load_lds_dwordx4 v160, s[16:17]
	s_add_i32 m0, s24, 0x2000
	s_nop 0
	global_load_lds_dwordx4 v132, s[16:17]
	v_lshl_add_u64 v[158:159], v[212:213], 0, s[22:23]
	s_mov_b32 m0, s61
	s_nop 0
	global_load_lds_dwordx4 v[158:159], off
	v_lshl_add_u64 v[158:159], v[218:219], 0, s[22:23]
	s_mov_b32 m0, s62
	s_nop 0
	global_load_lds_dwordx4 v[158:159], off
	s_waitcnt vmcnt(8) lgkmcnt(0)
	s_barrier
	v_mfma_f32_16x16x32_bf16 v[60:63], v[138:141], v[178:181], v[60:63]
	v_mfma_f32_16x16x32_bf16 v[56:59], v[150:153], v[178:181], v[56:59]
	v_mfma_f32_16x16x32_bf16 v[44:47], v[138:141], v[186:189], v[44:47]
	v_mfma_f32_16x16x32_bf16 v[40:43], v[150:153], v[186:189], v[40:43]
	v_mfma_f32_16x16x32_bf16 v[28:31], v[138:141], v[194:197], v[28:31]
	v_mfma_f32_16x16x32_bf16 v[24:27], v[150:153], v[194:197], v[24:27]
	v_mfma_f32_16x16x32_bf16 v[12:15], v[138:141], v[202:205], v[12:15]
	v_mfma_f32_16x16x32_bf16 v[8:11], v[150:153], v[202:205], v[8:11]
	v_mfma_f32_16x16x32_bf16 v[60:63], v[146:149], v[182:185], v[60:63]
	v_mfma_f32_16x16x32_bf16 v[56:59], v[154:157], v[182:185], v[56:59]
	v_mfma_f32_16x16x32_bf16 v[44:47], v[146:149], v[190:193], v[44:47]
	v_mfma_f32_16x16x32_bf16 v[40:43], v[154:157], v[190:193], v[40:43]
	v_mfma_f32_16x16x32_bf16 v[28:31], v[146:149], v[198:201], v[28:31]
	v_mfma_f32_16x16x32_bf16 v[24:27], v[154:157], v[198:201], v[24:27]
	v_mfma_f32_16x16x32_bf16 v[12:15], v[146:149], v[206:209], v[12:15]
	v_mfma_f32_16x16x32_bf16 v[8:11], v[154:157], v[206:209], v[8:11]
	v_mfma_f32_16x16x32_bf16 v[52:55], v[162:165], v[178:181], v[52:55]
	v_mfma_f32_16x16x32_bf16 v[48:51], v[170:173], v[178:181], v[48:51]
	v_mfma_f32_16x16x32_bf16 v[36:39], v[162:165], v[186:189], v[36:39]
	v_mfma_f32_16x16x32_bf16 v[32:35], v[170:173], v[186:189], v[32:35]
	v_mfma_f32_16x16x32_bf16 v[20:23], v[162:165], v[194:197], v[20:23]
	v_mfma_f32_16x16x32_bf16 v[16:19], v[170:173], v[194:197], v[16:19]
	v_mfma_f32_16x16x32_bf16 v[4:7], v[162:165], v[202:205], v[4:7]
	v_mfma_f32_16x16x32_bf16 v[0:3], v[170:173], v[202:205], v[0:3]
	v_mfma_f32_16x16x32_bf16 v[52:55], v[166:169], v[182:185], v[52:55]
	v_mfma_f32_16x16x32_bf16 v[48:51], v[174:177], v[182:185], v[48:51]
	v_mfma_f32_16x16x32_bf16 v[36:39], v[166:169], v[190:193], v[36:39]
	v_mfma_f32_16x16x32_bf16 v[32:35], v[174:177], v[190:193], v[32:35]
	v_mfma_f32_16x16x32_bf16 v[20:23], v[166:169], v[198:201], v[20:23]
	v_mfma_f32_16x16x32_bf16 v[16:19], v[174:177], v[198:201], v[16:19]
	v_mfma_f32_16x16x32_bf16 v[4:7], v[166:169], v[206:209], v[4:7]
	v_mfma_f32_16x16x32_bf16 v[0:3], v[174:177], v[206:209], v[0:3]
	s_barrier
	s_add_i32 s70, s70, 2
	s_add_u32 s50, s50, 0x100
	s_addc_u32 s51, s51, 0
	s_add_u32 s66, s66, 0x100
	s_addc_u32 s67, s67, 0
	s_cmp_gt_u32 s70, 13
	s_cbranch_scc0 .LBB0_1057
	s_and_b64 vcc, exec, s[20:21]
	s_cbranch_vccz .LBB0_1060
	s_barrier

; #define PG8_STAGE(bufoff, gbase, voff) do { _Pragma("unroll") for (int _i = 0; _i < 2; ++_i) \
;         __builtin_amdgcn_global_load_lds((const unsigned*)((const char*)(gbase) + (voff)[_i]), (LAS unsigned*)(lds + (bufoff) + ldsw + _i * 8192), 16, 0, 0); } while (0)
; #define PG8_LDA(dst, b, h) do { _Pragma("unroll") for (int m = 0; m < 4; ++m) _Pragma("unroll") for (int k = 0; k < 2; ++k) dst[m][k] = *(const LAS bf16x8*)(lds + PG8_SA(b, h) + aoff + m * 2048 + k * 1024); } while (0)
; #define PG8_LDB(dst, b, h) do { _Pragma("unroll") for (int n = 0; n < 2; ++n) _Pragma("unroll") for (int k = 0; k < 2; ++k) dst[n][k] = *(const LAS bf16x8*)(lds + PG8_SB(b, h) + boff + n * 2048 + k * 1024); } while (0)
; #define PG8_MMA(ai, bj, At, Bt) do { __builtin_amdgcn_s_setprio(1); _Pragma("unroll") for (int m = 0; m < 4; ++m) _Pragma("unroll") for (int n = 0; n < 2; ++n) _Pragma("unroll") for (int k = 0; k < 2; ++k) \
;         acc[ai][bj][m][n] = __builtin_amdgcn_mfma_f32_16x16x32_bf16(Bt[n][k], At[m][k], acc[ai][bj][m][n], 0, 0, 0); __builtin_amdgcn_s_setprio(0); } while (0)
; #define PG8_WAIT_V(n) asm volatile("s_waitcnt vmcnt(" #n ")" ::: "memory")
; #define PG8_WAIT_L(n) asm volatile("s_waitcnt lgkmcnt(" #n ")" ::: "memory")
; #define PG8_BAR __builtin_amdgcn_s_barrier()
; #define PG8_SCHED __builtin_amdgcn_sched_barrier(0)
; template <class Epi, bool ALIGN_EPI = true>
; __device__ __forceinline__ void gemm_phase(LAS unsigned char* lds, const Gemm g, const StaticOrder& S, const Epi& E, int wave_k) {
;     ...
;             PG8_LDB(B0, 0, 0); PG8_LDB(B1, 0, 1); PG8_SCHED; PG8_LDA(At, 0, 0); PG8_STAGE(PG8_SA(1, 1), a1 + hstepA, voffA);
;             PG8_WAIT_V(8); PG8_WAIT_L(0); PG8_BAR; PG8_MMA(0, 0, At, B0); PG8_MMA(0, 1, At, B1); PG8_BAR; PG8_SCHED;
;             PG8_LDA(At, 0, 1); PG8_STAGE(PG8_SB(0, 0), b2, voffB); PG8_STAGE(PG8_SB(0, 1), b2 + hstepB, voffB); PG8_STAGE(PG8_SA(0, 0), a2, voffA);
;             PG8_WAIT_V(8); PG8_WAIT_L(0); PG8_BAR; PG8_MMA(1, 0, At, B0); PG8_MMA(1, 1, At, B1); PG8_BAR; PG8_SCHED;
.LBB0_1141:
	s_add_u32 s16, s2, 0xfffc0080
	s_addc_u32 s17, s3, -1
	s_add_i32 s65, 0, 0x10000
	s_cmp_eq_u32 s64, 12
	s_cselect_b32 s19, s44, s17
	s_cselect_b32 s18, s45, s16
	s_cselect_b32 s17, s47, s63
	s_cselect_b32 s16, s49, s62
	s_add_i32 s68, 0, 0x14000
	v_add_u32_e32 v150, s65, v157
	v_add_u32_e32 v154, s68, v157
	ds_read_b128 v[138:141], v150
	ds_read_b128 v[142:145], v150 offset:1024
	ds_read_b128 v[146:149], v150 offset:2048
	ds_read_b128 v[150:153], v150 offset:3072
	ds_read_b128 v[162:165], v154
	ds_read_b128 v[166:169], v154 offset:1024
	ds_read_b128 v[170:173], v154 offset:2048
	ds_read_b128 v[174:177], v154 offset:3072
	s_add_i32 m0, s55, 0xc000
	ds_read_b128 v[178:181], v159
	ds_read_b128 v[182:185], v159 offset:1024
	ds_read_b128 v[186:189], v159 offset:2048
	ds_read_b128 v[190:193], v159 offset:3072
	ds_read_b128 v[194:197], v159 offset:4096
	ds_read_b128 v[198:201], v159 offset:5120
	ds_read_b128 v[202:205], v159 offset:6144
	ds_read_b128 v[206:209], v159 offset:7168
	global_load_lds_dwordx4 v134, s[2:3]
	s_add_i32 m0, s55, 0xe000
	s_nop 0
	global_load_lds_dwordx4 v136, s[2:3]
	s_waitcnt vmcnt(8) lgkmcnt(0)
	s_barrier
	v_mfma_f32_16x16x32_bf16 v[124:127], v[138:141], v[178:181], v[124:127]
	v_mfma_f32_16x16x32_bf16 v[120:123], v[146:149], v[178:181], v[120:123]
	v_mfma_f32_16x16x32_bf16 v[108:111], v[138:141], v[186:189], v[108:111]
	v_mfma_f32_16x16x32_bf16 v[100:103], v[146:149], v[186:189], v[100:103]
	v_mfma_f32_16x16x32_bf16 v[92:95], v[138:141], v[194:197], v[92:95]
	v_mfma_f32_16x16x32_bf16 v[84:87], v[146:149], v[194:197], v[84:87]
	v_mfma_f32_16x16x32_bf16 v[76:79], v[138:141], v[202:205], v[76:79]
	v_mfma_f32_16x16x32_bf16 v[68:71], v[146:149], v[202:205], v[68:71]
	v_mfma_f32_16x16x32_bf16 v[124:127], v[142:145], v[182:185], v[124:127]
	v_mfma_f32_16x16x32_bf16 v[120:123], v[150:153], v[182:185], v[120:123]
	v_mfma_f32_16x16x32_bf16 v[108:111], v[142:145], v[190:193], v[108:111]
	v_mfma_f32_16x16x32_bf16 v[100:103], v[150:153], v[190:193], v[100:103]
	v_mfma_f32_16x16x32_bf16 v[92:95], v[142:145], v[198:201], v[92:95]
	v_mfma_f32_16x16x32_bf16 v[84:87], v[150:153], v[198:201], v[84:87]
	v_mfma_f32_16x16x32_bf16 v[76:79], v[142:145], v[206:209], v[76:79]
	v_mfma_f32_16x16x32_bf16 v[68:71], v[150:153], v[206:209], v[68:71]
	v_mfma_f32_16x16x32_bf16 v[116:119], v[162:165], v[178:181], v[116:119]
	v_mfma_f32_16x16x32_bf16 v[112:115], v[170:173], v[178:181], v[112:115]
	v_mfma_f32_16x16x32_bf16 v[104:107], v[162:165], v[186:189], v[104:107]
	v_mfma_f32_16x16x32_bf16 v[96:99], v[170:173], v[186:189], v[96:99]
	v_mfma_f32_16x16x32_bf16 v[88:91], v[162:165], v[194:197], v[88:91]
	v_mfma_f32_16x16x32_bf16 v[80:83], v[170:173], v[194:197], v[80:83]
	v_mfma_f32_16x16x32_bf16 v[72:75], v[162:165], v[202:205], v[72:75]
	v_mfma_f32_16x16x32_bf16 v[64:67], v[170:173], v[202:205], v[64:67]
	v_mfma_f32_16x16x32_bf16 v[116:119], v[166:169], v[182:185], v[116:119]
	v_mfma_f32_16x16x32_bf16 v[112:115], v[174:177], v[182:185], v[112:115]
	v_mfma_f32_16x16x32_bf16 v[104:107], v[166:169], v[190:193], v[104:107]
	v_mfma_f32_16x16x32_bf16 v[96:99], v[174:177], v[190:193], v[96:99]
	v_mfma_f32_16x16x32_bf16 v[88:91], v[166:169], v[198:201], v[88:91]
	v_mfma_f32_16x16x32_bf16 v[80:83], v[174:177], v[198:201], v[80:83]
	v_mfma_f32_16x16x32_bf16 v[72:75], v[166:169], v[206:209], v[72:75]
	v_mfma_f32_16x16x32_bf16 v[64:67], v[174:177], v[206:209], v[64:67]
	s_barrier
	s_add_i32 s65, s65, s29
	v_lshl_add_u64 v[154:155], s[16:17], 0, v[160:161]
	s_mov_b32 m0, s65
	ds_read_b128 v[178:181], v159 offset:16384
	ds_read_b128 v[182:185], v159 offset:17408
	ds_read_b128 v[186:189], v159 offset:18432
	ds_read_b128 v[190:193], v159 offset:19456
	ds_read_b128 v[194:197], v159 offset:20480
	ds_read_b128 v[198:201], v159 offset:21504
	ds_read_b128 v[202:205], v159 offset:22528
	ds_read_b128 v[206:209], v159 offset:23552
	global_load_lds_dwordx4 v[154:155], off
	s_add_i32 m0, s65, 0x2000
	s_add_u32 s66, s16, 0x40000
	v_lshl_add_u64 v[210:211], s[16:17], 0, v[128:129]
	s_addc_u32 s67, s17, 0
	s_add_i32 s65, s68, s29
	global_load_lds_dwordx4 v[210:211], off
	s_mov_b32 m0, s65
	v_lshl_add_u64 v[218:219], s[18:19], 0, v[130:131]
	global_load_lds_dwordx4 v160, s[66:67]
	s_add_i32 m0, s65, 0x2000
	s_nop 0
	global_load_lds_dwordx4 v128, s[66:67]
	v_lshl_add_u64 v[212:213], s[18:19], 0, v[132:133]
	s_mov_b32 m0, s55
	s_nop 0
	global_load_lds_dwordx4 v[212:213], off
	s_mov_b32 m0, s56
	s_nop 0
	global_load_lds_dwordx4 v[218:219], off
	s_waitcnt vmcnt(8) lgkmcnt(0)
	s_barrier
	v_mfma_f32_16x16x32_bf16 v[60:63], v[138:141], v[178:181], v[60:63]
	v_mfma_f32_16x16x32_bf16 v[52:55], v[146:149], v[178:181], v[52:55]
	v_mfma_f32_16x16x32_bf16 v[44:47], v[138:141], v[186:189], v[44:47]
	v_mfma_f32_16x16x32_bf16 v[36:39], v[146:149], v[186:189], v[36:39]
	v_mfma_f32_16x16x32_bf16 v[28:31], v[138:141], v[194:197], v[28:31]
	v_mfma_f32_16x16x32_bf16 v[20:23], v[146:149], v[194:197], v[20:23]
	v_mfma_f32_16x16x32_bf16 v[12:15], v[138:141], v[202:205], v[12:15]
	v_mfma_f32_16x16x32_bf16 v[4:7], v[146:149], v[202:205], v[4:7]
	v_mfma_f32_16x16x32_bf16 v[60:63], v[142:145], v[182:185], v[60:63]
	v_mfma_f32_16x16x32_bf16 v[52:55], v[150:153], v[182:185], v[52:55]
	v_mfma_f32_16x16x32_bf16 v[44:47], v[142:145], v[190:193], v[44:47]
	v_mfma_f32_16x16x32_bf16 v[36:39], v[150:153], v[190:193], v[36:39]
	v_mfma_f32_16x16x32_bf16 v[28:31], v[142:145], v[198:201], v[28:31]
	v_mfma_f32_16x16x32_bf16 v[20:23], v[150:153], v[198:201], v[20:23]
	v_mfma_f32_16x16x32_bf16 v[12:15], v[142:145], v[206:209], v[12:15]
	v_mfma_f32_16x16x32_bf16 v[4:7], v[150:153], v[206:209], v[4:7]
	v_mfma_f32_16x16x32_bf16 v[56:59], v[162:165], v[178:181], v[56:59]
	v_mfma_f32_16x16x32_bf16 v[48:51], v[170:173], v[178:181], v[48:51]
	v_mfma_f32_16x16x32_bf16 v[40:43], v[162:165], v[186:189], v[40:43]
	v_mfma_f32_16x16x32_bf16 v[32:35], v[170:173], v[186:189], v[32:35]
	v_mfma_f32_16x16x32_bf16 v[24:27], v[162:165], v[194:197], v[24:27]
	v_mfma_f32_16x16x32_bf16 v[16:19], v[170:173], v[194:197], v[16:19]
	v_mfma_f32_16x16x32_bf16 v[8:11], v[162:165], v[202:205], v[8:11]
	v_mfma_f32_16x16x32_bf16 v[0:3], v[170:173], v[202:205], v[0:3]
	v_mfma_f32_16x16x32_bf16 v[56:59], v[166:169], v[182:185], v[56:59]
	v_mfma_f32_16x16x32_bf16 v[48:51], v[174:177], v[182:185], v[48:51]
	v_mfma_f32_16x16x32_bf16 v[40:43], v[166:169], v[190:193], v[40:43]
	v_mfma_f32_16x16x32_bf16 v[32:35], v[174:177], v[190:193], v[32:35]
	v_mfma_f32_16x16x32_bf16 v[24:27], v[166:169], v[198:201], v[24:27]
	v_mfma_f32_16x16x32_bf16 v[16:19], v[174:177], v[198:201], v[16:19]
	v_mfma_f32_16x16x32_bf16 v[8:11], v[166:169], v[206:209], v[8:11]
	v_mfma_f32_16x16x32_bf16 v[0:3], v[174:177], v[206:209], v[0:3]
	s_barrier
; #define PG8_STAGE(bufoff, gbase, voff) do { _Pragma("unroll") for (int _i = 0; _i < 2; ++_i) \
;         __builtin_amdgcn_global_load_lds((const unsigned*)((const char*)(gbase) + (voff)[_i]), (LAS unsigned*)(lds + (bufoff) + ldsw + _i * 8192), 16, 0, 0); } while (0)
; #define PG8_LDA(dst, b, h) do { _Pragma("unroll") for (int m = 0; m < 4; ++m) _Pragma("unroll") for (int k = 0; k < 2; ++k) dst[m][k] = *(const LAS bf16x8*)(lds + PG8_SA(b, h) + aoff + m * 2048 + k * 1024); } while (0)
; #define PG8_LDB(dst, b, h) do { _Pragma("unroll") for (int n = 0; n < 2; ++n) _Pragma("unroll") for (int k = 0; k < 2; ++k) dst[n][k] = *(const LAS bf16x8*)(lds + PG8_SB(b, h) + boff + n * 2048 + k * 1024); } while (0)
; #define PG8_MMA(ai, bj, At, Bt) do { __builtin_amdgcn_s_setprio(1); _Pragma("unroll") for (int m = 0; m < 4; ++m) _Pragma("unroll") for (int n = 0; n < 2; ++n) _Pragma("unroll") for (int k = 0; k < 2; ++k) \
;         acc[ai][bj][m][n] = __builtin_amdgcn_mfma_f32_16x16x32_bf16(Bt[n][k], At[m][k], acc[ai][bj][m][n], 0, 0, 0); __builtin_amdgcn_s_setprio(0); } while (0)
; #define PG8_WAIT_V(n) asm volatile("s_waitcnt vmcnt(" #n ")" ::: "memory")
; #define PG8_WAIT_L(n) asm volatile("s_waitcnt lgkmcnt(" #n ")" ::: "memory")
; #define PG8_BAR __builtin_amdgcn_s_barrier()
; #define PG8_SCHED __builtin_amdgcn_sched_barrier(0)
; template <class Epi, bool ALIGN_EPI = true>
; __device__ __forceinline__ void gemm_phase(LAS unsigned char* lds, const Gemm g, const StaticOrder& S, const Epi& E, int wave_k) {
;     ...
;             PG8_LDB(B0, 1, 0); PG8_LDB(B1, 1, 1); PG8_SCHED; PG8_LDA(At, 1, 0); PG8_STAGE(PG8_SA(0, 1), a2 + hstepA, voffA);
;             PG8_WAIT_V(8); PG8_WAIT_L(0); PG8_BAR; PG8_MMA(0, 0, At, B0); PG8_MMA(0, 1, At, B1); PG8_BAR; PG8_SCHED;
;             PG8_LDA(At, 1, 1); PG8_STAGE(PG8_SB(1, 0), b3, voffB); PG8_STAGE(PG8_SB(1, 1), b3 + hstepB, voffB); PG8_STAGE(PG8_SA(1, 0), a3, voffA);
;             PG8_WAIT_V(8); PG8_WAIT_L(0); PG8_BAR; PG8_MMA(1, 0, At, B0); PG8_MMA(1, 1, At, B1); PG8_BAR; PG8_SCHED;
;         }
	s_add_i32 s65, 0, 0x18000
	s_add_i32 s66, 0, 0x1c000
	v_add_u32_e32 v150, s65, v157
	v_add_u32_e32 v174, s66, v157
	ds_read_b128 v[138:141], v150
	ds_read_b128 v[142:145], v150 offset:1024
	ds_read_b128 v[146:149], v150 offset:2048
	ds_read_b128 v[150:153], v150 offset:3072
	ds_read_b128 v[162:165], v174
	ds_read_b128 v[166:169], v174 offset:1024
	ds_read_b128 v[170:173], v174 offset:2048
	ds_read_b128 v[174:177], v174 offset:3072
	s_add_u32 s18, s18, 0x40000
	s_addc_u32 s19, s19, 0
	s_mov_b32 m0, s57
	ds_read_b128 v[178:181], v159 offset:32768
	ds_read_b128 v[182:185], v159 offset:33792
	ds_read_b128 v[186:189], v159 offset:34816
	ds_read_b128 v[190:193], v159 offset:35840
	ds_read_b128 v[194:197], v159 offset:36864
	ds_read_b128 v[198:201], v159 offset:37888
	ds_read_b128 v[202:205], v159 offset:38912
	ds_read_b128 v[206:209], v159 offset:39936
	global_load_lds_dwordx4 v132, s[18:19]
	s_mov_b32 m0, s58
	s_nop 0
	global_load_lds_dwordx4 v130, s[18:19]
	s_waitcnt vmcnt(8) lgkmcnt(0)
	s_barrier
	v_mfma_f32_16x16x32_bf16 v[124:127], v[138:141], v[178:181], v[124:127]
	v_mfma_f32_16x16x32_bf16 v[120:123], v[146:149], v[178:181], v[120:123]
	v_mfma_f32_16x16x32_bf16 v[108:111], v[138:141], v[186:189], v[108:111]
	v_mfma_f32_16x16x32_bf16 v[100:103], v[146:149], v[186:189], v[100:103]
	v_mfma_f32_16x16x32_bf16 v[92:95], v[138:141], v[194:197], v[92:95]
	v_mfma_f32_16x16x32_bf16 v[84:87], v[146:149], v[194:197], v[84:87]
	v_mfma_f32_16x16x32_bf16 v[76:79], v[138:141], v[202:205], v[76:79]
	v_mfma_f32_16x16x32_bf16 v[68:71], v[146:149], v[202:205], v[68:71]
	v_mfma_f32_16x16x32_bf16 v[124:127], v[142:145], v[182:185], v[124:127]
	v_mfma_f32_16x16x32_bf16 v[120:123], v[150:153], v[182:185], v[120:123]
	v_mfma_f32_16x16x32_bf16 v[108:111], v[142:145], v[190:193], v[108:111]
	v_mfma_f32_16x16x32_bf16 v[100:103], v[150:153], v[190:193], v[100:103]
	v_mfma_f32_16x16x32_bf16 v[92:95], v[142:145], v[198:201], v[92:95]
	v_mfma_f32_16x16x32_bf16 v[84:87], v[150:153], v[198:201], v[84:87]
	v_mfma_f32_16x16x32_bf16 v[76:79], v[142:145], v[206:209], v[76:79]
	v_mfma_f32_16x16x32_bf16 v[68:71], v[150:153], v[206:209], v[68:71]
	v_mfma_f32_16x16x32_bf16 v[116:119], v[162:165], v[178:181], v[116:119]
	v_mfma_f32_16x16x32_bf16 v[112:115], v[170:173], v[178:181], v[112:115]
	v_mfma_f32_16x16x32_bf16 v[104:107], v[162:165], v[186:189], v[104:107]
	v_mfma_f32_16x16x32_bf16 v[96:99], v[170:173], v[186:189], v[96:99]
	v_mfma_f32_16x16x32_bf16 v[88:91], v[162:165], v[194:197], v[88:91]
	v_mfma_f32_16x16x32_bf16 v[80:83], v[170:173], v[194:197], v[80:83]
	v_mfma_f32_16x16x32_bf16 v[72:75], v[162:165], v[202:205], v[72:75]
	v_mfma_f32_16x16x32_bf16 v[64:67], v[170:173], v[202:205], v[64:67]
	v_mfma_f32_16x16x32_bf16 v[116:119], v[166:169], v[182:185], v[116:119]
	v_mfma_f32_16x16x32_bf16 v[112:115], v[174:177], v[182:185], v[112:115]
	v_mfma_f32_16x16x32_bf16 v[104:107], v[166:169], v[190:193], v[104:107]
	v_mfma_f32_16x16x32_bf16 v[96:99], v[174:177], v[190:193], v[96:99]
	v_mfma_f32_16x16x32_bf16 v[88:91], v[166:169], v[198:201], v[88:91]
	v_mfma_f32_16x16x32_bf16 v[80:83], v[174:177], v[198:201], v[80:83]
	v_mfma_f32_16x16x32_bf16 v[72:75], v[166:169], v[206:209], v[72:75]
	v_mfma_f32_16x16x32_bf16 v[64:67], v[174:177], v[206:209], v[64:67]
	s_barrier
	s_add_i32 s18, s65, s29
	v_lshl_add_u64 v[154:155], v[154:155], 0, s[22:23]
	s_mov_b32 m0, s18
	ds_read_b128 v[178:181], v159 offset:49152
	ds_read_b128 v[182:185], v159 offset:50176
	ds_read_b128 v[186:189], v159 offset:51200
	ds_read_b128 v[190:193], v159 offset:52224
	ds_read_b128 v[194:197], v159 offset:53248
	ds_read_b128 v[198:201], v159 offset:54272
	ds_read_b128 v[202:205], v159 offset:55296
	ds_read_b128 v[206:209], v159 offset:56320
	global_load_lds_dwordx4 v[154:155], off
	s_add_i32 m0, s18, 0x2000
	s_add_u32 s16, s16, 0x40080
	v_lshl_add_u64 v[154:155], v[210:211], 0, s[22:23]
	s_addc_u32 s17, s17, 0
	s_add_i32 s18, s66, s29
	global_load_lds_dwordx4 v[154:155], off
	s_mov_b32 m0, s18
	s_nop 0
	global_load_lds_dwordx4 v160, s[16:17]
	s_add_i32 m0, s18, 0x2000
	s_nop 0
	global_load_lds_dwordx4 v128, s[16:17]
	v_lshl_add_u64 v[154:155], v[212:213], 0, s[22:23]
	s_mov_b32 m0, s20
	s_nop 0
	global_load_lds_dwordx4 v[154:155], off
	v_lshl_add_u64 v[154:155], v[218:219], 0, s[22:23]
	s_mov_b32 m0, s59
	s_nop 0
	global_load_lds_dwordx4 v[154:155], off
	s_waitcnt vmcnt(8) lgkmcnt(0)
	s_barrier
	v_mfma_f32_16x16x32_bf16 v[60:63], v[138:141], v[178:181], v[60:63]
	v_mfma_f32_16x16x32_bf16 v[52:55], v[146:149], v[178:181], v[52:55]
	v_mfma_f32_16x16x32_bf16 v[44:47], v[138:141], v[186:189], v[44:47]
	v_mfma_f32_16x16x32_bf16 v[36:39], v[146:149], v[186:189], v[36:39]
	v_mfma_f32_16x16x32_bf16 v[28:31], v[138:141], v[194:197], v[28:31]
	v_mfma_f32_16x16x32_bf16 v[20:23], v[146:149], v[194:197], v[20:23]
	v_mfma_f32_16x16x32_bf16 v[12:15], v[138:141], v[202:205], v[12:15]
	v_mfma_f32_16x16x32_bf16 v[4:7], v[146:149], v[202:205], v[4:7]
	v_mfma_f32_16x16x32_bf16 v[60:63], v[142:145], v[182:185], v[60:63]
	v_mfma_f32_16x16x32_bf16 v[52:55], v[150:153], v[182:185], v[52:55]
	v_mfma_f32_16x16x32_bf16 v[44:47], v[142:145], v[190:193], v[44:47]
	v_mfma_f32_16x16x32_bf16 v[36:39], v[150:153], v[190:193], v[36:39]
	v_mfma_f32_16x16x32_bf16 v[28:31], v[142:145], v[198:201], v[28:31]
	v_mfma_f32_16x16x32_bf16 v[20:23], v[150:153], v[198:201], v[20:23]
	v_mfma_f32_16x16x32_bf16 v[12:15], v[142:145], v[206:209], v[12:15]
	v_mfma_f32_16x16x32_bf16 v[4:7], v[150:153], v[206:209], v[4:7]
	v_mfma_f32_16x16x32_bf16 v[56:59], v[162:165], v[178:181], v[56:59]
	v_mfma_f32_16x16x32_bf16 v[48:51], v[170:173], v[178:181], v[48:51]
	v_mfma_f32_16x16x32_bf16 v[40:43], v[162:165], v[186:189], v[40:43]
	v_mfma_f32_16x16x32_bf16 v[32:35], v[170:173], v[186:189], v[32:35]
	v_mfma_f32_16x16x32_bf16 v[24:27], v[162:165], v[194:197], v[24:27]
	v_mfma_f32_16x16x32_bf16 v[16:19], v[170:173], v[194:197], v[16:19]
	v_mfma_f32_16x16x32_bf16 v[8:11], v[162:165], v[202:205], v[8:11]
	v_mfma_f32_16x16x32_bf16 v[0:3], v[170:173], v[202:205], v[0:3]
	v_mfma_f32_16x16x32_bf16 v[56:59], v[166:169], v[182:185], v[56:59]
	v_mfma_f32_16x16x32_bf16 v[48:51], v[174:177], v[182:185], v[48:51]
	v_mfma_f32_16x16x32_bf16 v[40:43], v[166:169], v[190:193], v[40:43]
	v_mfma_f32_16x16x32_bf16 v[32:35], v[174:177], v[190:193], v[32:35]
	v_mfma_f32_16x16x32_bf16 v[24:27], v[166:169], v[198:201], v[24:27]
	v_mfma_f32_16x16x32_bf16 v[16:19], v[174:177], v[198:201], v[16:19]
	v_mfma_f32_16x16x32_bf16 v[8:11], v[166:169], v[206:209], v[8:11]
	v_mfma_f32_16x16x32_bf16 v[0:3], v[174:177], v[206:209], v[0:3]
	s_barrier
	s_add_i32 s64, s64, 2
	s_add_u32 s2, s2, 0x100
	s_addc_u32 s3, s3, 0
	s_add_u32 s62, s62, 0x100
	s_addc_u32 s63, s63, 0
	s_cmp_gt_u32 s64, 13
	s_cbranch_scc0 .LBB0_1141
	s_and_b64 vcc, exec, s[40:41]
	s_cbranch_vccz .LBB0_1144
	s_barrier

; #define PG8_STAGE(bufoff, gbase, voff) do { _Pragma("unroll") for (int _i = 0; _i < 2; ++_i) \
;         __builtin_amdgcn_global_load_lds((const unsigned*)((const char*)(gbase) + (voff)[_i]), (LAS unsigned*)(lds + (bufoff) + ldsw + _i * 8192), 16, 0, 0); } while (0)
; #define PG8_LDA(dst, b, h) do { _Pragma("unroll") for (int m = 0; m < 4; ++m) _Pragma("unroll") for (int k = 0; k < 2; ++k) dst[m][k] = *(const LAS bf16x8*)(lds + PG8_SA(b, h) + aoff + m * 2048 + k * 1024); } while (0)
; #define PG8_LDB(dst, b, h) do { _Pragma("unroll") for (int n = 0; n < 2; ++n) _Pragma("unroll") for (int k = 0; k < 2; ++k) dst[n][k] = *(const LAS bf16x8*)(lds + PG8_SB(b, h) + boff + n * 2048 + k * 1024); } while (0)
; #define PG8_MMA(ai, bj, At, Bt) do { __builtin_amdgcn_s_setprio(1); _Pragma("unroll") for (int m = 0; m < 4; ++m) _Pragma("unroll") for (int n = 0; n < 2; ++n) _Pragma("unroll") for (int k = 0; k < 2; ++k) \
;         acc[ai][bj][m][n] = __builtin_amdgcn_mfma_f32_16x16x32_bf16(Bt[n][k], At[m][k], acc[ai][bj][m][n], 0, 0, 0); __builtin_amdgcn_s_setprio(0); } while (0)
; #define PG8_WAIT_V(n) asm volatile("s_waitcnt vmcnt(" #n ")" ::: "memory")
; #define PG8_WAIT_L(n) asm volatile("s_waitcnt lgkmcnt(" #n ")" ::: "memory")
; #define PG8_BAR __builtin_amdgcn_s_barrier()
; #define PG8_SCHED __builtin_amdgcn_sched_barrier(0)
; template <class Epi, bool ALIGN_EPI = true>
; __device__ __forceinline__ void gemm_phase(LAS unsigned char* lds, const Gemm g, const StaticOrder& S, const Epi& E, int wave_k) {
;     ...
;             PG8_LDB(B0, 0, 0); PG8_LDB(B1, 0, 1); PG8_SCHED; PG8_LDA(At, 0, 0); PG8_STAGE(PG8_SA(1, 1), a1 + hstepA, voffA);
;             PG8_WAIT_V(8); PG8_WAIT_L(0); PG8_BAR; PG8_MMA(0, 0, At, B0); PG8_MMA(0, 1, At, B1); PG8_BAR; PG8_SCHED;
;             PG8_LDA(At, 0, 1); PG8_STAGE(PG8_SB(0, 0), b2, voffB); PG8_STAGE(PG8_SB(0, 1), b2 + hstepB, voffB); PG8_STAGE(PG8_SA(0, 0), a2, voffA);
;             PG8_WAIT_V(8); PG8_WAIT_L(0); PG8_BAR; PG8_MMA(1, 0, At, B0); PG8_MMA(1, 1, At, B1); PG8_BAR; PG8_SCHED;
.LBB0_1257:
	s_add_u32 s16, s24, 0x100
	s_addc_u32 s17, s25, 0
	s_add_i32 s67, 0, 0x10000
	s_cmp_eq_u32 s66, 40
	s_cselect_b32 s29, s1, s17
	s_cselect_b32 s28, s0, s16
	s_cselect_b32 s27, s35, s45
	s_cselect_b32 s26, s34, s44
	s_add_i32 s68, 0, 0x14000
	v_add_u32_e32 v154, s67, v143
	v_add_u32_e32 v158, s68, v143
	ds_read_b128 v[138:141], v154
	ds_read_b128 v[146:149], v154 offset:1024
	ds_read_b128 v[150:153], v154 offset:2048
	ds_read_b128 v[154:157], v154 offset:3072
	ds_read_b128 v[162:165], v158
	ds_read_b128 v[166:169], v158 offset:1024
	ds_read_b128 v[170:173], v158 offset:2048
	ds_read_b128 v[174:177], v158 offset:3072
	v_lshl_add_u64 v[158:159], s[24:25], 0, v[134:135]
	s_add_i32 m0, s55, 0xc000
	ds_read_b128 v[178:181], v145
	ds_read_b128 v[182:185], v145 offset:1024
	ds_read_b128 v[186:189], v145 offset:2048
	ds_read_b128 v[190:193], v145 offset:3072
	ds_read_b128 v[194:197], v145 offset:4096
	ds_read_b128 v[198:201], v145 offset:5120
	ds_read_b128 v[202:205], v145 offset:6144
	ds_read_b128 v[206:209], v145 offset:7168
	global_load_lds_dwordx4 v[158:159], off
	v_lshl_add_u64 v[158:159], s[24:25], 0, v[136:137]
	s_add_i32 m0, s55, 0xe000
	s_nop 0
	global_load_lds_dwordx4 v[158:159], off
	s_waitcnt vmcnt(8) lgkmcnt(0)
	s_barrier
	v_mfma_f32_16x16x32_bf16 v[124:127], v[138:141], v[178:181], v[124:127]
	v_mfma_f32_16x16x32_bf16 v[120:123], v[150:153], v[178:181], v[120:123]
	v_mfma_f32_16x16x32_bf16 v[108:111], v[138:141], v[186:189], v[108:111]
	v_mfma_f32_16x16x32_bf16 v[104:107], v[150:153], v[186:189], v[104:107]
	v_mfma_f32_16x16x32_bf16 v[92:95], v[138:141], v[194:197], v[92:95]
	v_mfma_f32_16x16x32_bf16 v[88:91], v[150:153], v[194:197], v[88:91]
	v_mfma_f32_16x16x32_bf16 v[76:79], v[138:141], v[202:205], v[76:79]
	v_mfma_f32_16x16x32_bf16 v[72:75], v[150:153], v[202:205], v[72:75]
	v_mfma_f32_16x16x32_bf16 v[124:127], v[146:149], v[182:185], v[124:127]
	v_mfma_f32_16x16x32_bf16 v[120:123], v[154:157], v[182:185], v[120:123]
	v_mfma_f32_16x16x32_bf16 v[108:111], v[146:149], v[190:193], v[108:111]
	v_mfma_f32_16x16x32_bf16 v[104:107], v[154:157], v[190:193], v[104:107]
	v_mfma_f32_16x16x32_bf16 v[92:95], v[146:149], v[198:201], v[92:95]
	v_mfma_f32_16x16x32_bf16 v[88:91], v[154:157], v[198:201], v[88:91]
	v_mfma_f32_16x16x32_bf16 v[76:79], v[146:149], v[206:209], v[76:79]
	v_mfma_f32_16x16x32_bf16 v[72:75], v[154:157], v[206:209], v[72:75]
	v_mfma_f32_16x16x32_bf16 v[116:119], v[162:165], v[178:181], v[116:119]
	v_mfma_f32_16x16x32_bf16 v[112:115], v[170:173], v[178:181], v[112:115]
	v_mfma_f32_16x16x32_bf16 v[100:103], v[162:165], v[186:189], v[100:103]
	v_mfma_f32_16x16x32_bf16 v[96:99], v[170:173], v[186:189], v[96:99]
	v_mfma_f32_16x16x32_bf16 v[84:87], v[162:165], v[194:197], v[84:87]
	v_mfma_f32_16x16x32_bf16 v[80:83], v[170:173], v[194:197], v[80:83]
	v_mfma_f32_16x16x32_bf16 v[68:71], v[162:165], v[202:205], v[68:71]
	v_mfma_f32_16x16x32_bf16 v[64:67], v[170:173], v[202:205], v[64:67]
	v_mfma_f32_16x16x32_bf16 v[116:119], v[166:169], v[182:185], v[116:119]
	v_mfma_f32_16x16x32_bf16 v[112:115], v[174:177], v[182:185], v[112:115]
	v_mfma_f32_16x16x32_bf16 v[100:103], v[166:169], v[190:193], v[100:103]
	v_mfma_f32_16x16x32_bf16 v[96:99], v[174:177], v[190:193], v[96:99]
	v_mfma_f32_16x16x32_bf16 v[84:87], v[166:169], v[198:201], v[84:87]
	v_mfma_f32_16x16x32_bf16 v[80:83], v[174:177], v[198:201], v[80:83]
	v_mfma_f32_16x16x32_bf16 v[68:71], v[166:169], v[206:209], v[68:71]
	v_mfma_f32_16x16x32_bf16 v[64:67], v[174:177], v[206:209], v[64:67]
	s_barrier
	s_add_i32 s24, s67, s54
	v_lshl_add_u64 v[158:159], s[26:27], 0, v[160:161]
	s_mov_b32 m0, s24
	ds_read_b128 v[178:181], v145 offset:16384
	ds_read_b128 v[182:185], v145 offset:17408
	ds_read_b128 v[186:189], v145 offset:18432
	ds_read_b128 v[190:193], v145 offset:19456
	ds_read_b128 v[194:197], v145 offset:20480
	ds_read_b128 v[198:201], v145 offset:21504
	ds_read_b128 v[202:205], v145 offset:22528
	ds_read_b128 v[206:209], v145 offset:23552
	global_load_lds_dwordx4 v[158:159], off
	s_add_i32 m0, s24, 0x2000
	s_add_u32 s24, s26, 0xb0000
	v_lshl_add_u64 v[210:211], s[26:27], 0, v[132:133]
	s_addc_u32 s25, s27, 0
	s_add_i32 s67, s68, s54
	global_load_lds_dwordx4 v[210:211], off
	s_mov_b32 m0, s67
	v_lshl_add_u64 v[218:219], s[28:29], 0, v[130:131]
	global_load_lds_dwordx4 v160, s[24:25]
	s_add_i32 m0, s67, 0x2000
	s_nop 0
	global_load_lds_dwordx4 v132, s[24:25]
	v_lshl_add_u64 v[212:213], s[28:29], 0, v[128:129]
	s_mov_b32 m0, s55
	s_nop 0
	global_load_lds_dwordx4 v[212:213], off
	s_mov_b32 m0, s56
	s_nop 0
	global_load_lds_dwordx4 v[218:219], off
	s_waitcnt vmcnt(8) lgkmcnt(0)
	s_barrier
; #define PG8_STAGE(bufoff, gbase, voff) do { _Pragma("unroll") for (int _i = 0; _i < 2; ++_i) \
;         __builtin_amdgcn_global_load_lds((const unsigned*)((const char*)(gbase) + (voff)[_i]), (LAS unsigned*)(lds + (bufoff) + ldsw + _i * 8192), 16, 0, 0); } while (0)
; #define PG8_LDA(dst, b, h) do { _Pragma("unroll") for (int m = 0; m < 4; ++m) _Pragma("unroll") for (int k = 0; k < 2; ++k) dst[m][k] = *(const LAS bf16x8*)(lds + PG8_SA(b, h) + aoff + m * 2048 + k * 1024); } while (0)
; #define PG8_LDB(dst, b, h) do { _Pragma("unroll") for (int n = 0; n < 2; ++n) _Pragma("unroll") for (int k = 0; k < 2; ++k) dst[n][k] = *(const LAS bf16x8*)(lds + PG8_SB(b, h) + boff + n * 2048 + k * 1024); } while (0)
; #define PG8_MMA(ai, bj, At, Bt) do { __builtin_amdgcn_s_setprio(1); _Pragma("unroll") for (int m = 0; m < 4; ++m) _Pragma("unroll") for (int n = 0; n < 2; ++n) _Pragma("unroll") for (int k = 0; k < 2; ++k) \
;         acc[ai][bj][m][n] = __builtin_amdgcn_mfma_f32_16x16x32_bf16(Bt[n][k], At[m][k], acc[ai][bj][m][n], 0, 0, 0); __builtin_amdgcn_s_setprio(0); } while (0)
; #define PG8_WAIT_V(n) asm volatile("s_waitcnt vmcnt(" #n ")" ::: "memory")
; #define PG8_WAIT_L(n) asm volatile("s_waitcnt lgkmcnt(" #n ")" ::: "memory")
; #define PG8_BAR __builtin_amdgcn_s_barrier()
; #define PG8_SCHED __builtin_amdgcn_sched_barrier(0)
; template <class Epi, bool ALIGN_EPI = true>
; __device__ __forceinline__ void gemm_phase(LAS unsigned char* lds, const Gemm g, const StaticOrder& S, const Epi& E, int wave_k) {
;     ...
;             PG8_WAIT_V(8); PG8_WAIT_L(0); PG8_BAR; PG8_MMA(1, 0, At, B0); PG8_MMA(1, 1, At, B1); PG8_BAR; PG8_SCHED;
;             PG8_LDB(B0, 1, 0); PG8_LDB(B1, 1, 1); PG8_SCHED; PG8_LDA(At, 1, 0); PG8_STAGE(PG8_SA(0, 1), a2 + hstepA, voffA);
;             PG8_WAIT_V(8); PG8_WAIT_L(0); PG8_BAR; PG8_MMA(0, 0, At, B0); PG8_MMA(0, 1, At, B1); PG8_BAR; PG8_SCHED;
	v_mfma_f32_16x16x32_bf16 v[60:63], v[138:141], v[178:181], v[60:63]
	v_mfma_f32_16x16x32_bf16 v[56:59], v[150:153], v[178:181], v[56:59]
	v_mfma_f32_16x16x32_bf16 v[44:47], v[138:141], v[186:189], v[44:47]
	v_mfma_f32_16x16x32_bf16 v[40:43], v[150:153], v[186:189], v[40:43]
	v_mfma_f32_16x16x32_bf16 v[28:31], v[138:141], v[194:197], v[28:31]
	v_mfma_f32_16x16x32_bf16 v[24:27], v[150:153], v[194:197], v[24:27]
	v_mfma_f32_16x16x32_bf16 v[12:15], v[138:141], v[202:205], v[12:15]
	v_mfma_f32_16x16x32_bf16 v[8:11], v[150:153], v[202:205], v[8:11]
	v_mfma_f32_16x16x32_bf16 v[60:63], v[146:149], v[182:185], v[60:63]
	v_mfma_f32_16x16x32_bf16 v[56:59], v[154:157], v[182:185], v[56:59]
	v_mfma_f32_16x16x32_bf16 v[44:47], v[146:149], v[190:193], v[44:47]
	v_mfma_f32_16x16x32_bf16 v[40:43], v[154:157], v[190:193], v[40:43]
	v_mfma_f32_16x16x32_bf16 v[28:31], v[146:149], v[198:201], v[28:31]
	v_mfma_f32_16x16x32_bf16 v[24:27], v[154:157], v[198:201], v[24:27]
	v_mfma_f32_16x16x32_bf16 v[12:15], v[146:149], v[206:209], v[12:15]
	v_mfma_f32_16x16x32_bf16 v[8:11], v[154:157], v[206:209], v[8:11]
	v_mfma_f32_16x16x32_bf16 v[52:55], v[162:165], v[178:181], v[52:55]
	v_mfma_f32_16x16x32_bf16 v[48:51], v[170:173], v[178:181], v[48:51]
	v_mfma_f32_16x16x32_bf16 v[36:39], v[162:165], v[186:189], v[36:39]
	v_mfma_f32_16x16x32_bf16 v[32:35], v[170:173], v[186:189], v[32:35]
	v_mfma_f32_16x16x32_bf16 v[20:23], v[162:165], v[194:197], v[20:23]
	v_mfma_f32_16x16x32_bf16 v[16:19], v[170:173], v[194:197], v[16:19]
	v_mfma_f32_16x16x32_bf16 v[4:7], v[162:165], v[202:205], v[4:7]
	v_mfma_f32_16x16x32_bf16 v[0:3], v[170:173], v[202:205], v[0:3]
	v_mfma_f32_16x16x32_bf16 v[52:55], v[166:169], v[182:185], v[52:55]
	v_mfma_f32_16x16x32_bf16 v[48:51], v[174:177], v[182:185], v[48:51]
	v_mfma_f32_16x16x32_bf16 v[36:39], v[166:169], v[190:193], v[36:39]
	v_mfma_f32_16x16x32_bf16 v[32:35], v[174:177], v[190:193], v[32:35]
	v_mfma_f32_16x16x32_bf16 v[20:23], v[166:169], v[198:201], v[20:23]
	v_mfma_f32_16x16x32_bf16 v[16:19], v[174:177], v[198:201], v[16:19]
	v_mfma_f32_16x16x32_bf16 v[4:7], v[166:169], v[206:209], v[4:7]
	v_mfma_f32_16x16x32_bf16 v[0:3], v[174:177], v[206:209], v[0:3]
	s_barrier
	s_add_i32 s67, 0, 0x18000
	s_add_i32 s68, 0, 0x1c000
	v_add_u32_e32 v154, s67, v143
	v_add_u32_e32 v174, s68, v143
	ds_read_b128 v[138:141], v154
	ds_read_b128 v[146:149], v154 offset:1024
	ds_read_b128 v[150:153], v154 offset:2048
	ds_read_b128 v[154:157], v154 offset:3072
	ds_read_b128 v[162:165], v174
	ds_read_b128 v[166:169], v174 offset:1024
	ds_read_b128 v[170:173], v174 offset:2048
	ds_read_b128 v[174:177], v174 offset:3072
	s_add_u32 s24, s28, 0xb0000
	s_addc_u32 s25, s29, 0
	s_mov_b32 m0, s57
	ds_read_b128 v[178:181], v145 offset:32768
	ds_read_b128 v[182:185], v145 offset:33792
	ds_read_b128 v[186:189], v145 offset:34816
	ds_read_b128 v[190:193], v145 offset:35840
	ds_read_b128 v[194:197], v145 offset:36864
	ds_read_b128 v[198:201], v145 offset:37888
	ds_read_b128 v[202:205], v145 offset:38912
	ds_read_b128 v[206:209], v145 offset:39936
	global_load_lds_dwordx4 v128, s[24:25]
	s_mov_b32 m0, s58
	s_nop 0
	global_load_lds_dwordx4 v130, s[24:25]
	s_waitcnt vmcnt(8) lgkmcnt(0)
	s_barrier
	v_mfma_f32_16x16x32_bf16 v[124:127], v[138:141], v[178:181], v[124:127]
	v_mfma_f32_16x16x32_bf16 v[120:123], v[150:153], v[178:181], v[120:123]
	v_mfma_f32_16x16x32_bf16 v[108:111], v[138:141], v[186:189], v[108:111]
	v_mfma_f32_16x16x32_bf16 v[104:107], v[150:153], v[186:189], v[104:107]
	v_mfma_f32_16x16x32_bf16 v[92:95], v[138:141], v[194:197], v[92:95]
	v_mfma_f32_16x16x32_bf16 v[88:91], v[150:153], v[194:197], v[88:91]
	v_mfma_f32_16x16x32_bf16 v[76:79], v[138:141], v[202:205], v[76:79]
	v_mfma_f32_16x16x32_bf16 v[72:75], v[150:153], v[202:205], v[72:75]
	v_mfma_f32_16x16x32_bf16 v[124:127], v[146:149], v[182:185], v[124:127]
	v_mfma_f32_16x16x32_bf16 v[120:123], v[154:157], v[182:185], v[120:123]
	v_mfma_f32_16x16x32_bf16 v[108:111], v[146:149], v[190:193], v[108:111]
	v_mfma_f32_16x16x32_bf16 v[104:107], v[154:157], v[190:193], v[104:107]
	v_mfma_f32_16x16x32_bf16 v[92:95], v[146:149], v[198:201], v[92:95]
	v_mfma_f32_16x16x32_bf16 v[88:91], v[154:157], v[198:201], v[88:91]
	v_mfma_f32_16x16x32_bf16 v[76:79], v[146:149], v[206:209], v[76:79]
	v_mfma_f32_16x16x32_bf16 v[72:75], v[154:157], v[206:209], v[72:75]
	v_mfma_f32_16x16x32_bf16 v[116:119], v[162:165], v[178:181], v[116:119]
	v_mfma_f32_16x16x32_bf16 v[112:115], v[170:173], v[178:181], v[112:115]
	v_mfma_f32_16x16x32_bf16 v[100:103], v[162:165], v[186:189], v[100:103]
	v_mfma_f32_16x16x32_bf16 v[96:99], v[170:173], v[186:189], v[96:99]
	v_mfma_f32_16x16x32_bf16 v[84:87], v[162:165], v[194:197], v[84:87]
	v_mfma_f32_16x16x32_bf16 v[80:83], v[170:173], v[194:197], v[80:83]
	v_mfma_f32_16x16x32_bf16 v[68:71], v[162:165], v[202:205], v[68:71]
	v_mfma_f32_16x16x32_bf16 v[64:67], v[170:173], v[202:205], v[64:67]
	v_mfma_f32_16x16x32_bf16 v[116:119], v[166:169], v[182:185], v[116:119]
	v_mfma_f32_16x16x32_bf16 v[112:115], v[174:177], v[182:185], v[112:115]
	v_mfma_f32_16x16x32_bf16 v[100:103], v[166:169], v[190:193], v[100:103]
	v_mfma_f32_16x16x32_bf16 v[96:99], v[174:177], v[190:193], v[96:99]
	v_mfma_f32_16x16x32_bf16 v[84:87], v[166:169], v[198:201], v[84:87]
	v_mfma_f32_16x16x32_bf16 v[80:83], v[174:177], v[198:201], v[80:83]
	v_mfma_f32_16x16x32_bf16 v[68:71], v[166:169], v[206:209], v[68:71]
	v_mfma_f32_16x16x32_bf16 v[64:67], v[174:177], v[206:209], v[64:67]
	s_barrier
; #define PG8_STAGE(bufoff, gbase, voff) do { _Pragma("unroll") for (int _i = 0; _i < 2; ++_i) \
;         __builtin_amdgcn_global_load_lds((const unsigned*)((const char*)(gbase) + (voff)[_i]), (LAS unsigned*)(lds + (bufoff) + ldsw + _i * 8192), 16, 0, 0); } while (0)
; #define PG8_LDA(dst, b, h) do { _Pragma("unroll") for (int m = 0; m < 4; ++m) _Pragma("unroll") for (int k = 0; k < 2; ++k) dst[m][k] = *(const LAS bf16x8*)(lds + PG8_SA(b, h) + aoff + m * 2048 + k * 1024); } while (0)
; #define PG8_MMA(ai, bj, At, Bt) do { __builtin_amdgcn_s_setprio(1); _Pragma("unroll") for (int m = 0; m < 4; ++m) _Pragma("unroll") for (int n = 0; n < 2; ++n) _Pragma("unroll") for (int k = 0; k < 2; ++k) \
;         acc[ai][bj][m][n] = __builtin_amdgcn_mfma_f32_16x16x32_bf16(Bt[n][k], At[m][k], acc[ai][bj][m][n], 0, 0, 0); __builtin_amdgcn_s_setprio(0); } while (0)
; #define PG8_WAIT_V(n) asm volatile("s_waitcnt vmcnt(" #n ")" ::: "memory")
; #define PG8_WAIT_L(n) asm volatile("s_waitcnt lgkmcnt(" #n ")" ::: "memory")
; #define PG8_BAR __builtin_amdgcn_s_barrier()
; #define PG8_SCHED __builtin_amdgcn_sched_barrier(0)
; template <class Epi, bool ALIGN_EPI = true>
; __device__ __forceinline__ void gemm_phase(LAS unsigned char* lds, const Gemm g, const StaticOrder& S, const Epi& E, int wave_k) {
;     ...
;             PG8_LDA(At, 1, 1); PG8_STAGE(PG8_SB(1, 0), b3, voffB); PG8_STAGE(PG8_SB(1, 1), b3 + hstepB, voffB); PG8_STAGE(PG8_SA(1, 0), a3, voffA);
;             PG8_WAIT_V(8); PG8_WAIT_L(0); PG8_BAR; PG8_MMA(1, 0, At, B0); PG8_MMA(1, 1, At, B1); PG8_BAR; PG8_SCHED;
;         }
	s_add_i32 s24, s67, s54
	v_lshl_add_u64 v[158:159], v[158:159], 0, s[22:23]
	s_mov_b32 m0, s24
	ds_read_b128 v[178:181], v145 offset:49152
	ds_read_b128 v[182:185], v145 offset:50176
	ds_read_b128 v[186:189], v145 offset:51200
	ds_read_b128 v[190:193], v145 offset:52224
	ds_read_b128 v[194:197], v145 offset:53248
	ds_read_b128 v[198:201], v145 offset:54272
	ds_read_b128 v[202:205], v145 offset:55296
	ds_read_b128 v[206:209], v145 offset:56320
	global_load_lds_dwordx4 v[158:159], off
	s_add_i32 m0, s24, 0x2000
	s_add_u32 s24, s26, 0xb0080
	v_lshl_add_u64 v[158:159], v[210:211], 0, s[22:23]
	s_addc_u32 s25, s27, 0
	s_add_i32 s26, s68, s54
	global_load_lds_dwordx4 v[158:159], off
	s_mov_b32 m0, s26
	s_nop 0
	global_load_lds_dwordx4 v160, s[24:25]
	s_add_i32 m0, s26, 0x2000
	s_nop 0
	global_load_lds_dwordx4 v132, s[24:25]
	v_lshl_add_u64 v[158:159], v[212:213], 0, s[22:23]
	s_mov_b32 m0, s50
	s_nop 0
	global_load_lds_dwordx4 v[158:159], off
	v_lshl_add_u64 v[158:159], v[218:219], 0, s[22:23]
	s_mov_b32 m0, s51
	s_nop 0
	global_load_lds_dwordx4 v[158:159], off
	s_waitcnt vmcnt(8) lgkmcnt(0)
	s_barrier
	v_mfma_f32_16x16x32_bf16 v[60:63], v[138:141], v[178:181], v[60:63]
	v_mfma_f32_16x16x32_bf16 v[56:59], v[150:153], v[178:181], v[56:59]
	v_mfma_f32_16x16x32_bf16 v[44:47], v[138:141], v[186:189], v[44:47]
	v_mfma_f32_16x16x32_bf16 v[40:43], v[150:153], v[186:189], v[40:43]
	v_mfma_f32_16x16x32_bf16 v[28:31], v[138:141], v[194:197], v[28:31]
	v_mfma_f32_16x16x32_bf16 v[24:27], v[150:153], v[194:197], v[24:27]
	v_mfma_f32_16x16x32_bf16 v[12:15], v[138:141], v[202:205], v[12:15]
	v_mfma_f32_16x16x32_bf16 v[8:11], v[150:153], v[202:205], v[8:11]
	v_mfma_f32_16x16x32_bf16 v[60:63], v[146:149], v[182:185], v[60:63]
	v_mfma_f32_16x16x32_bf16 v[56:59], v[154:157], v[182:185], v[56:59]
	v_mfma_f32_16x16x32_bf16 v[44:47], v[146:149], v[190:193], v[44:47]
	v_mfma_f32_16x16x32_bf16 v[40:43], v[154:157], v[190:193], v[40:43]
	v_mfma_f32_16x16x32_bf16 v[28:31], v[146:149], v[198:201], v[28:31]
	v_mfma_f32_16x16x32_bf16 v[24:27], v[154:157], v[198:201], v[24:27]
	v_mfma_f32_16x16x32_bf16 v[12:15], v[146:149], v[206:209], v[12:15]
	v_mfma_f32_16x16x32_bf16 v[8:11], v[154:157], v[206:209], v[8:11]
	v_mfma_f32_16x16x32_bf16 v[52:55], v[162:165], v[178:181], v[52:55]
	v_mfma_f32_16x16x32_bf16 v[48:51], v[170:173], v[178:181], v[48:51]
	v_mfma_f32_16x16x32_bf16 v[36:39], v[162:165], v[186:189], v[36:39]
	v_mfma_f32_16x16x32_bf16 v[32:35], v[170:173], v[186:189], v[32:35]
	v_mfma_f32_16x16x32_bf16 v[20:23], v[162:165], v[194:197], v[20:23]
	v_mfma_f32_16x16x32_bf16 v[16:19], v[170:173], v[194:197], v[16:19]
	v_mfma_f32_16x16x32_bf16 v[4:7], v[162:165], v[202:205], v[4:7]
	v_mfma_f32_16x16x32_bf16 v[0:3], v[170:173], v[202:205], v[0:3]
	v_mfma_f32_16x16x32_bf16 v[52:55], v[166:169], v[182:185], v[52:55]
	v_mfma_f32_16x16x32_bf16 v[48:51], v[174:177], v[182:185], v[48:51]
	v_mfma_f32_16x16x32_bf16 v[36:39], v[166:169], v[190:193], v[36:39]
	v_mfma_f32_16x16x32_bf16 v[32:35], v[174:177], v[190:193], v[32:35]
	v_mfma_f32_16x16x32_bf16 v[20:23], v[166:169], v[198:201], v[20:23]
	v_mfma_f32_16x16x32_bf16 v[16:19], v[174:177], v[198:201], v[16:19]
	v_mfma_f32_16x16x32_bf16 v[4:7], v[166:169], v[206:209], v[4:7]
	v_mfma_f32_16x16x32_bf16 v[0:3], v[174:177], v[206:209], v[0:3]
	s_barrier
	s_add_i32 s66, s66, 2
	s_add_u32 s44, s44, 0x100
	s_addc_u32 s45, s45, 0
	s_cmp_gt_u32 s66, 41
	s_mov_b64 s[24:25], s[16:17]
	s_cbranch_scc0 .LBB0_1257
	s_and_b64 vcc, exec, s[20:21]
	s_cbranch_vccz .LBB0_1260
	s_barrier
